# code placement: every K-loop MFMA run at byte phase 0 mod 8 (25 s_nop pads in front of load-segment closing waits), on top of the handover variant
# speedup vs baseline: 1.0047x; 1.0018x over previous
.LBB0_297:
	s_add_u32 s0, s36, 0xfff80080
	s_addc_u32 s6, s37, -1
	s_add_i32 s49, 0, 0x10000
	s_cmp_eq_u32 s55, 28
	s_cselect_b32 s35, s25, s6
	s_cselect_b32 s34, s33, s0
	v_add_u32_e32 v156, s49, v159
	s_cselect_b32 s31, s40, s39
	s_cselect_b32 s30, s50, s38
	s_add_i32 s0, 0, 0x14000
	ds_read_b128 v[144:147], v156
	ds_read_b128 v[148:151], v156 offset:1024
	ds_read_b128 v[152:155], v156 offset:2048
	ds_read_b128 v[164:167], v156 offset:3072
	v_add_u32_e32 v156, s0, v159
	ds_read_b128 v[168:171], v156
	ds_read_b128 v[172:175], v156 offset:1024
	ds_read_b128 v[176:179], v156 offset:2048
	ds_read_b128 v[180:183], v156 offset:3072
	v_lshl_add_u64 v[156:157], s[36:37], 0, v[140:141]
	s_add_i32 m0, s47, 0xc000
	ds_read_b128 v[184:187], v163
	ds_read_b128 v[188:191], v163 offset:1024
	ds_read_b128 v[192:195], v163 offset:2048
	ds_read_b128 v[200:203], v163 offset:3072
	ds_read_b128 v[204:207], v163 offset:4096
	ds_read_b128 v[208:211], v163 offset:5120
	ds_read_b128 v[212:215], v163 offset:6144
	ds_read_b128 v[216:219], v163 offset:7168
	global_load_lds_dwordx4 v[156:157], off
	v_lshl_add_u64 v[156:157], s[36:37], 0, v[142:143]
	s_add_i32 m0, s47, 0xe000
	s_nop 0
	global_load_lds_dwordx4 v[156:157], off
	s_nop 0
	s_waitcnt vmcnt(8)
	s_waitcnt lgkmcnt(0)
	s_setprio 1
	s_barrier
	v_mfma_f32_16x16x32_bf16 v[128:131], v[144:147], v[184:187], v[128:131]
	v_mfma_f32_16x16x32_bf16 v[124:127], v[152:155], v[184:187], v[124:127]
	v_mfma_f32_16x16x32_bf16 v[112:115], v[144:147], v[192:195], v[112:115]
	v_mfma_f32_16x16x32_bf16 v[108:111], v[152:155], v[192:195], v[108:111]
	v_mfma_f32_16x16x32_bf16 v[96:99], v[144:147], v[204:207], v[96:99]
	v_mfma_f32_16x16x32_bf16 v[92:95], v[152:155], v[204:207], v[92:95]
	v_mfma_f32_16x16x32_bf16 v[80:83], v[144:147], v[212:215], v[80:83]
	v_mfma_f32_16x16x32_bf16 v[76:79], v[152:155], v[212:215], v[76:79]
	v_mfma_f32_16x16x32_bf16 v[128:131], v[148:151], v[188:191], v[128:131]
	v_mfma_f32_16x16x32_bf16 v[124:127], v[164:167], v[188:191], v[124:127]
	v_mfma_f32_16x16x32_bf16 v[112:115], v[148:151], v[200:203], v[112:115]
	v_mfma_f32_16x16x32_bf16 v[108:111], v[164:167], v[200:203], v[108:111]
	v_mfma_f32_16x16x32_bf16 v[96:99], v[148:151], v[208:211], v[96:99]
	v_mfma_f32_16x16x32_bf16 v[92:95], v[164:167], v[208:211], v[92:95]
	v_mfma_f32_16x16x32_bf16 v[80:83], v[148:151], v[216:219], v[80:83]
	v_mfma_f32_16x16x32_bf16 v[76:79], v[164:167], v[216:219], v[76:79]
	s_setprio 0
	s_setprio 1
	v_mfma_f32_16x16x32_bf16 v[120:123], v[168:171], v[184:187], v[120:123]
	v_mfma_f32_16x16x32_bf16 v[116:119], v[176:179], v[184:187], v[116:119]
	v_mfma_f32_16x16x32_bf16 v[104:107], v[168:171], v[192:195], v[104:107]
	v_mfma_f32_16x16x32_bf16 v[100:103], v[176:179], v[192:195], v[100:103]
	v_mfma_f32_16x16x32_bf16 v[88:91], v[168:171], v[204:207], v[88:91]
	v_mfma_f32_16x16x32_bf16 v[84:87], v[176:179], v[204:207], v[84:87]
	v_mfma_f32_16x16x32_bf16 v[72:75], v[168:171], v[212:215], v[72:75]
	v_mfma_f32_16x16x32_bf16 v[68:71], v[176:179], v[212:215], v[68:71]
	v_mfma_f32_16x16x32_bf16 v[120:123], v[172:175], v[188:191], v[120:123]
	v_mfma_f32_16x16x32_bf16 v[116:119], v[180:183], v[188:191], v[116:119]
	v_mfma_f32_16x16x32_bf16 v[104:107], v[172:175], v[200:203], v[104:107]
	v_mfma_f32_16x16x32_bf16 v[100:103], v[180:183], v[200:203], v[100:103]
	v_mfma_f32_16x16x32_bf16 v[88:91], v[172:175], v[208:211], v[88:91]
	v_mfma_f32_16x16x32_bf16 v[84:87], v[180:183], v[208:211], v[84:87]
	v_mfma_f32_16x16x32_bf16 v[72:75], v[172:175], v[216:219], v[72:75]
	v_mfma_f32_16x16x32_bf16 v[68:71], v[180:183], v[216:219], v[68:71]
	s_barrier
	s_setprio 0
	s_add_i32 s6, s49, s46
	v_lshl_add_u64 v[156:157], s[30:31], 0, v[136:137]
	s_mov_b32 m0, s6
	ds_read_b128 v[184:187], v163 offset:16384
	ds_read_b128 v[188:191], v163 offset:17408
	ds_read_b128 v[192:195], v163 offset:18432
	ds_read_b128 v[200:203], v163 offset:19456
	ds_read_b128 v[204:207], v163 offset:20480
	ds_read_b128 v[208:211], v163 offset:21504
	ds_read_b128 v[212:215], v163 offset:22528
	ds_read_b128 v[216:219], v163 offset:23552
	global_load_lds_dwordx4 v[156:157], off
	s_add_i32 m0, s6, 0x2000
	s_add_u32 s66, s30, 0x80000
	v_lshl_add_u64 v[220:221], s[30:31], 0, v[132:133]
	s_addc_u32 s67, s31, 0
	s_add_i32 s0, s0, s46
	global_load_lds_dwordx4 v[220:221], off
	v_lshl_add_u64 v[222:223], s[66:67], 0, v[136:137]
	s_mov_b32 m0, s0
	v_lshl_add_u64 v[224:225], s[34:35], 0, v[134:135]
	global_load_lds_dwordx4 v[222:223], off
	v_lshl_add_u64 v[222:223], s[66:67], 0, v[132:133]
	s_add_i32 m0, s0, 0x2000
	s_nop 0
	global_load_lds_dwordx4 v[222:223], off
	v_lshl_add_u64 v[222:223], s[34:35], 0, v[138:139]
	s_mov_b32 m0, s47
	s_nop 0
	global_load_lds_dwordx4 v[222:223], off
	s_mov_b32 m0, s52
	s_nop 0
	global_load_lds_dwordx4 v[224:225], off
	s_waitcnt vmcnt(8)
	s_waitcnt lgkmcnt(0)
	s_setprio 1
	s_barrier
	v_mfma_f32_16x16x32_bf16 v[64:67], v[144:147], v[184:187], v[64:67]
	v_mfma_f32_16x16x32_bf16 v[60:63], v[152:155], v[184:187], v[60:63]
	v_mfma_f32_16x16x32_bf16 v[48:51], v[144:147], v[192:195], v[48:51]
	v_mfma_f32_16x16x32_bf16 v[44:47], v[152:155], v[192:195], v[44:47]
	v_mfma_f32_16x16x32_bf16 v[32:35], v[144:147], v[204:207], v[32:35]
	v_mfma_f32_16x16x32_bf16 v[28:31], v[152:155], v[204:207], v[28:31]
	v_mfma_f32_16x16x32_bf16 v[16:19], v[144:147], v[212:215], v[16:19]
	v_mfma_f32_16x16x32_bf16 v[12:15], v[152:155], v[212:215], v[12:15]
	v_mfma_f32_16x16x32_bf16 v[64:67], v[148:151], v[188:191], v[64:67]
	v_mfma_f32_16x16x32_bf16 v[60:63], v[164:167], v[188:191], v[60:63]
	v_mfma_f32_16x16x32_bf16 v[48:51], v[148:151], v[200:203], v[48:51]
	v_mfma_f32_16x16x32_bf16 v[44:47], v[164:167], v[200:203], v[44:47]
	v_mfma_f32_16x16x32_bf16 v[32:35], v[148:151], v[208:211], v[32:35]
	v_mfma_f32_16x16x32_bf16 v[28:31], v[164:167], v[208:211], v[28:31]
	v_mfma_f32_16x16x32_bf16 v[16:19], v[148:151], v[216:219], v[16:19]
	v_mfma_f32_16x16x32_bf16 v[12:15], v[164:167], v[216:219], v[12:15]
	s_setprio 0
	s_setprio 1
	v_mfma_f32_16x16x32_bf16 v[56:59], v[168:171], v[184:187], v[56:59]
	v_mfma_f32_16x16x32_bf16 v[52:55], v[176:179], v[184:187], v[52:55]
	v_mfma_f32_16x16x32_bf16 v[40:43], v[168:171], v[192:195], v[40:43]
	v_mfma_f32_16x16x32_bf16 v[36:39], v[176:179], v[192:195], v[36:39]
	v_mfma_f32_16x16x32_bf16 v[24:27], v[168:171], v[204:207], v[24:27]
	v_mfma_f32_16x16x32_bf16 v[20:23], v[176:179], v[204:207], v[20:23]
	v_mfma_f32_16x16x32_bf16 v[8:11], v[168:171], v[212:215], v[8:11]
	v_mfma_f32_16x16x32_bf16 v[4:7], v[176:179], v[212:215], v[4:7]
	v_mfma_f32_16x16x32_bf16 v[56:59], v[172:175], v[188:191], v[56:59]
	v_mfma_f32_16x16x32_bf16 v[52:55], v[180:183], v[188:191], v[52:55]
	v_mfma_f32_16x16x32_bf16 v[40:43], v[172:175], v[200:203], v[40:43]
	v_mfma_f32_16x16x32_bf16 v[36:39], v[180:183], v[200:203], v[36:39]
	v_mfma_f32_16x16x32_bf16 v[24:27], v[172:175], v[208:211], v[24:27]
	v_mfma_f32_16x16x32_bf16 v[20:23], v[180:183], v[208:211], v[20:23]
	v_mfma_f32_16x16x32_bf16 v[8:11], v[172:175], v[216:219], v[8:11]
	v_mfma_f32_16x16x32_bf16 v[4:7], v[180:183], v[216:219], v[4:7]
	s_barrier
	s_setprio 0
	s_add_i32 s0, 0, 0x18000
	v_add_u32_e32 v158, s0, v159
	s_add_i32 s6, 0, 0x1c000
	ds_read_b128 v[144:147], v158
	ds_read_b128 v[148:151], v158 offset:1024
	ds_read_b128 v[152:155], v158 offset:2048
	ds_read_b128 v[164:167], v158 offset:3072
	v_add_u32_e32 v158, s6, v159
	ds_read_b128 v[168:171], v158
	ds_read_b128 v[172:175], v158 offset:1024
	ds_read_b128 v[176:179], v158 offset:2048
	ds_read_b128 v[180:183], v158 offset:3072
	s_add_u32 s34, s34, 0x80000
	s_addc_u32 s35, s35, 0
	s_mov_b32 m0, s53
	v_lshl_add_u64 v[226:227], s[34:35], 0, v[138:139]
	ds_read_b128 v[184:187], v163 offset:32768
	ds_read_b128 v[188:191], v163 offset:33792
	ds_read_b128 v[192:195], v163 offset:34816
	ds_read_b128 v[200:203], v163 offset:35840
	ds_read_b128 v[204:207], v163 offset:36864
	ds_read_b128 v[208:211], v163 offset:37888
	ds_read_b128 v[212:215], v163 offset:38912
	ds_read_b128 v[216:219], v163 offset:39936
	global_load_lds_dwordx4 v[226:227], off
	v_lshl_add_u64 v[226:227], s[34:35], 0, v[134:135]
	s_mov_b32 m0, s60
	s_nop 0
	global_load_lds_dwordx4 v[226:227], off
	s_waitcnt vmcnt(8)
	s_waitcnt lgkmcnt(0)
	s_setprio 1
	s_barrier
	v_mfma_f32_16x16x32_bf16 v[128:131], v[144:147], v[184:187], v[128:131]
	v_mfma_f32_16x16x32_bf16 v[124:127], v[152:155], v[184:187], v[124:127]
	v_mfma_f32_16x16x32_bf16 v[112:115], v[144:147], v[192:195], v[112:115]
	v_mfma_f32_16x16x32_bf16 v[108:111], v[152:155], v[192:195], v[108:111]
	v_mfma_f32_16x16x32_bf16 v[96:99], v[144:147], v[204:207], v[96:99]
	v_mfma_f32_16x16x32_bf16 v[92:95], v[152:155], v[204:207], v[92:95]
	v_mfma_f32_16x16x32_bf16 v[80:83], v[144:147], v[212:215], v[80:83]
	v_mfma_f32_16x16x32_bf16 v[76:79], v[152:155], v[212:215], v[76:79]
	v_mfma_f32_16x16x32_bf16 v[128:131], v[148:151], v[188:191], v[128:131]
	v_mfma_f32_16x16x32_bf16 v[124:127], v[164:167], v[188:191], v[124:127]
	v_mfma_f32_16x16x32_bf16 v[112:115], v[148:151], v[200:203], v[112:115]
	v_mfma_f32_16x16x32_bf16 v[108:111], v[164:167], v[200:203], v[108:111]
	v_mfma_f32_16x16x32_bf16 v[96:99], v[148:151], v[208:211], v[96:99]
	v_mfma_f32_16x16x32_bf16 v[92:95], v[164:167], v[208:211], v[92:95]
	v_mfma_f32_16x16x32_bf16 v[80:83], v[148:151], v[216:219], v[80:83]
	v_mfma_f32_16x16x32_bf16 v[76:79], v[164:167], v[216:219], v[76:79]
	s_setprio 0
	s_setprio 1
	v_mfma_f32_16x16x32_bf16 v[120:123], v[168:171], v[184:187], v[120:123]
	v_mfma_f32_16x16x32_bf16 v[116:119], v[176:179], v[184:187], v[116:119]
	v_mfma_f32_16x16x32_bf16 v[104:107], v[168:171], v[192:195], v[104:107]
	v_mfma_f32_16x16x32_bf16 v[100:103], v[176:179], v[192:195], v[100:103]
	v_mfma_f32_16x16x32_bf16 v[88:91], v[168:171], v[204:207], v[88:91]
	v_mfma_f32_16x16x32_bf16 v[84:87], v[176:179], v[204:207], v[84:87]
	v_mfma_f32_16x16x32_bf16 v[72:75], v[168:171], v[212:215], v[72:75]
	v_mfma_f32_16x16x32_bf16 v[68:71], v[176:179], v[212:215], v[68:71]
	v_mfma_f32_16x16x32_bf16 v[120:123], v[172:175], v[188:191], v[120:123]
	v_mfma_f32_16x16x32_bf16 v[116:119], v[180:183], v[188:191], v[116:119]
	v_mfma_f32_16x16x32_bf16 v[104:107], v[172:175], v[200:203], v[104:107]
	v_mfma_f32_16x16x32_bf16 v[100:103], v[180:183], v[200:203], v[100:103]
	v_mfma_f32_16x16x32_bf16 v[88:91], v[172:175], v[208:211], v[88:91]
	v_mfma_f32_16x16x32_bf16 v[84:87], v[180:183], v[208:211], v[84:87]
	v_mfma_f32_16x16x32_bf16 v[72:75], v[172:175], v[216:219], v[72:75]
	v_mfma_f32_16x16x32_bf16 v[68:71], v[180:183], v[216:219], v[68:71]
	s_barrier
	s_setprio 0
	s_add_i32 s0, s0, s46
	v_lshl_add_u64 v[156:157], v[156:157], 0, s[90:91]
	s_mov_b32 m0, s0
	ds_read_b128 v[184:187], v163 offset:49152
	ds_read_b128 v[188:191], v163 offset:50176
	ds_read_b128 v[192:195], v163 offset:51200
	ds_read_b128 v[200:203], v163 offset:52224
	ds_read_b128 v[204:207], v163 offset:53248
	ds_read_b128 v[208:211], v163 offset:54272
	ds_read_b128 v[212:215], v163 offset:55296
	ds_read_b128 v[216:219], v163 offset:56320
	global_load_lds_dwordx4 v[156:157], off
	s_add_i32 m0, s0, 0x2000
	s_add_u32 s30, s30, 0x80080
	v_lshl_add_u64 v[156:157], v[220:221], 0, s[90:91]
	s_addc_u32 s31, s31, 0
	s_add_i32 s0, s6, s46
	global_load_lds_dwordx4 v[156:157], off
	v_lshl_add_u64 v[156:157], s[30:31], 0, v[136:137]
	s_mov_b32 m0, s0
	s_nop 0
	global_load_lds_dwordx4 v[156:157], off
	v_lshl_add_u64 v[156:157], s[30:31], 0, v[132:133]
	s_add_i32 m0, s0, 0x2000
	s_nop 0
	global_load_lds_dwordx4 v[156:157], off
	v_lshl_add_u64 v[156:157], v[222:223], 0, s[90:91]
	s_mov_b32 m0, s62
	s_nop 0
	global_load_lds_dwordx4 v[156:157], off
	v_lshl_add_u64 v[156:157], v[224:225], 0, s[90:91]
	s_mov_b32 m0, s51
	s_nop 0
	global_load_lds_dwordx4 v[156:157], off
	s_nop 0
	s_waitcnt vmcnt(8)
	s_waitcnt lgkmcnt(0)
	s_setprio 1
	s_barrier
	v_mfma_f32_16x16x32_bf16 v[64:67], v[144:147], v[184:187], v[64:67]
	v_mfma_f32_16x16x32_bf16 v[60:63], v[152:155], v[184:187], v[60:63]
	v_mfma_f32_16x16x32_bf16 v[48:51], v[144:147], v[192:195], v[48:51]
	v_mfma_f32_16x16x32_bf16 v[44:47], v[152:155], v[192:195], v[44:47]
	v_mfma_f32_16x16x32_bf16 v[32:35], v[144:147], v[204:207], v[32:35]
	v_mfma_f32_16x16x32_bf16 v[28:31], v[152:155], v[204:207], v[28:31]
	v_mfma_f32_16x16x32_bf16 v[16:19], v[144:147], v[212:215], v[16:19]
	v_mfma_f32_16x16x32_bf16 v[12:15], v[152:155], v[212:215], v[12:15]
	v_mfma_f32_16x16x32_bf16 v[64:67], v[148:151], v[188:191], v[64:67]
	v_mfma_f32_16x16x32_bf16 v[60:63], v[164:167], v[188:191], v[60:63]
	v_mfma_f32_16x16x32_bf16 v[48:51], v[148:151], v[200:203], v[48:51]
	v_mfma_f32_16x16x32_bf16 v[44:47], v[164:167], v[200:203], v[44:47]
	v_mfma_f32_16x16x32_bf16 v[32:35], v[148:151], v[208:211], v[32:35]
	v_mfma_f32_16x16x32_bf16 v[28:31], v[164:167], v[208:211], v[28:31]
	v_mfma_f32_16x16x32_bf16 v[16:19], v[148:151], v[216:219], v[16:19]
	v_mfma_f32_16x16x32_bf16 v[12:15], v[164:167], v[216:219], v[12:15]
	s_setprio 0
	s_setprio 1
	v_mfma_f32_16x16x32_bf16 v[56:59], v[168:171], v[184:187], v[56:59]
	v_mfma_f32_16x16x32_bf16 v[52:55], v[176:179], v[184:187], v[52:55]
	v_mfma_f32_16x16x32_bf16 v[40:43], v[168:171], v[192:195], v[40:43]
	v_mfma_f32_16x16x32_bf16 v[36:39], v[176:179], v[192:195], v[36:39]
	v_mfma_f32_16x16x32_bf16 v[24:27], v[168:171], v[204:207], v[24:27]
	v_mfma_f32_16x16x32_bf16 v[20:23], v[176:179], v[204:207], v[20:23]
	v_mfma_f32_16x16x32_bf16 v[8:11], v[168:171], v[212:215], v[8:11]
	v_mfma_f32_16x16x32_bf16 v[4:7], v[176:179], v[212:215], v[4:7]
	v_mfma_f32_16x16x32_bf16 v[56:59], v[172:175], v[188:191], v[56:59]
	v_mfma_f32_16x16x32_bf16 v[52:55], v[180:183], v[188:191], v[52:55]
	v_mfma_f32_16x16x32_bf16 v[40:43], v[172:175], v[200:203], v[40:43]
	v_mfma_f32_16x16x32_bf16 v[36:39], v[180:183], v[200:203], v[36:39]
	v_mfma_f32_16x16x32_bf16 v[24:27], v[172:175], v[208:211], v[24:27]
	v_mfma_f32_16x16x32_bf16 v[20:23], v[180:183], v[208:211], v[20:23]
	v_mfma_f32_16x16x32_bf16 v[8:11], v[172:175], v[216:219], v[8:11]
	v_mfma_f32_16x16x32_bf16 v[4:7], v[180:183], v[216:219], v[4:7]
	s_barrier
	s_setprio 0
	s_add_i32 s55, s55, 2
	s_add_u32 s36, s36, 0x100
	s_addc_u32 s37, s37, 0
	s_add_u32 s38, s38, 0x100
	s_addc_u32 s39, s39, 0
	s_cmp_gt_u32 s55, 29
	s_cbranch_scc0 .LBB0_297
	s_and_b64 vcc, exec, s[22:23]
	s_cbranch_vccz .LBB0_300
	s_barrier

.LBB0_336:
	s_add_u32 s0, s36, 0xfff80080
	s_addc_u32 s6, s37, -1
	s_add_i32 s49, 0, 0x10000
	s_cmp_eq_u32 s50, 28
	s_cselect_b32 s35, s24, s6
	s_cselect_b32 s34, s25, s0
	v_add_u32_e32 v156, s49, v159
	s_cselect_b32 s31, s33, s39
	s_cselect_b32 s30, s40, s38
	s_add_i32 s0, 0, 0x14000
	ds_read_b128 v[144:147], v156
	ds_read_b128 v[148:151], v156 offset:1024
	ds_read_b128 v[152:155], v156 offset:2048
	ds_read_b128 v[164:167], v156 offset:3072
	v_add_u32_e32 v156, s0, v159
	ds_read_b128 v[168:171], v156
	ds_read_b128 v[172:175], v156 offset:1024
	ds_read_b128 v[176:179], v156 offset:2048
	ds_read_b128 v[180:183], v156 offset:3072
	v_lshl_add_u64 v[156:157], s[36:37], 0, v[140:141]
	s_add_i32 m0, s45, 0xc000
	ds_read_b128 v[184:187], v163
	ds_read_b128 v[188:191], v163 offset:1024
	ds_read_b128 v[192:195], v163 offset:2048
	ds_read_b128 v[200:203], v163 offset:3072
	ds_read_b128 v[204:207], v163 offset:4096
	ds_read_b128 v[208:211], v163 offset:5120
	ds_read_b128 v[212:215], v163 offset:6144
	ds_read_b128 v[216:219], v163 offset:7168
	global_load_lds_dwordx4 v[156:157], off
	v_lshl_add_u64 v[156:157], s[36:37], 0, v[142:143]
	s_add_i32 m0, s45, 0xe000
	s_nop 0
	global_load_lds_dwordx4 v[156:157], off
	s_waitcnt vmcnt(8)
	s_waitcnt lgkmcnt(0)
	s_setprio 1
	s_barrier
	v_mfma_f32_16x16x32_bf16 v[128:131], v[144:147], v[184:187], v[128:131]
	v_mfma_f32_16x16x32_bf16 v[124:127], v[152:155], v[184:187], v[124:127]
	v_mfma_f32_16x16x32_bf16 v[112:115], v[144:147], v[192:195], v[112:115]
	v_mfma_f32_16x16x32_bf16 v[108:111], v[152:155], v[192:195], v[108:111]
	v_mfma_f32_16x16x32_bf16 v[96:99], v[144:147], v[204:207], v[96:99]
	v_mfma_f32_16x16x32_bf16 v[92:95], v[152:155], v[204:207], v[92:95]
	v_mfma_f32_16x16x32_bf16 v[80:83], v[144:147], v[212:215], v[80:83]
	v_mfma_f32_16x16x32_bf16 v[76:79], v[152:155], v[212:215], v[76:79]
	v_mfma_f32_16x16x32_bf16 v[128:131], v[148:151], v[188:191], v[128:131]
	v_mfma_f32_16x16x32_bf16 v[124:127], v[164:167], v[188:191], v[124:127]
	v_mfma_f32_16x16x32_bf16 v[112:115], v[148:151], v[200:203], v[112:115]
	v_mfma_f32_16x16x32_bf16 v[108:111], v[164:167], v[200:203], v[108:111]
	v_mfma_f32_16x16x32_bf16 v[96:99], v[148:151], v[208:211], v[96:99]
	v_mfma_f32_16x16x32_bf16 v[92:95], v[164:167], v[208:211], v[92:95]
	v_mfma_f32_16x16x32_bf16 v[80:83], v[148:151], v[216:219], v[80:83]
	v_mfma_f32_16x16x32_bf16 v[76:79], v[164:167], v[216:219], v[76:79]
	s_setprio 0
	s_setprio 1
	v_mfma_f32_16x16x32_bf16 v[120:123], v[168:171], v[184:187], v[120:123]
	v_mfma_f32_16x16x32_bf16 v[116:119], v[176:179], v[184:187], v[116:119]
	v_mfma_f32_16x16x32_bf16 v[104:107], v[168:171], v[192:195], v[104:107]
	v_mfma_f32_16x16x32_bf16 v[100:103], v[176:179], v[192:195], v[100:103]
	v_mfma_f32_16x16x32_bf16 v[88:91], v[168:171], v[204:207], v[88:91]
	v_mfma_f32_16x16x32_bf16 v[84:87], v[176:179], v[204:207], v[84:87]
	v_mfma_f32_16x16x32_bf16 v[72:75], v[168:171], v[212:215], v[72:75]
	v_mfma_f32_16x16x32_bf16 v[68:71], v[176:179], v[212:215], v[68:71]
	v_mfma_f32_16x16x32_bf16 v[120:123], v[172:175], v[188:191], v[120:123]
	v_mfma_f32_16x16x32_bf16 v[116:119], v[180:183], v[188:191], v[116:119]
	v_mfma_f32_16x16x32_bf16 v[104:107], v[172:175], v[200:203], v[104:107]
	v_mfma_f32_16x16x32_bf16 v[100:103], v[180:183], v[200:203], v[100:103]
	v_mfma_f32_16x16x32_bf16 v[88:91], v[172:175], v[208:211], v[88:91]
	v_mfma_f32_16x16x32_bf16 v[84:87], v[180:183], v[208:211], v[84:87]
	v_mfma_f32_16x16x32_bf16 v[72:75], v[172:175], v[216:219], v[72:75]
	v_mfma_f32_16x16x32_bf16 v[68:71], v[180:183], v[216:219], v[68:71]
	s_barrier
	s_setprio 0
	s_add_i32 s6, s49, s47
	v_lshl_add_u64 v[156:157], s[30:31], 0, v[136:137]
	s_mov_b32 m0, s6
	ds_read_b128 v[184:187], v163 offset:16384
	ds_read_b128 v[188:191], v163 offset:17408
	ds_read_b128 v[192:195], v163 offset:18432
	ds_read_b128 v[200:203], v163 offset:19456
	ds_read_b128 v[204:207], v163 offset:20480
	ds_read_b128 v[208:211], v163 offset:21504
	ds_read_b128 v[212:215], v163 offset:22528
	ds_read_b128 v[216:219], v163 offset:23552
	global_load_lds_dwordx4 v[156:157], off
	s_add_i32 m0, s6, 0x2000
	s_add_u32 s54, s30, 0x80000
	v_lshl_add_u64 v[220:221], s[30:31], 0, v[132:133]
	s_addc_u32 s55, s31, 0
	s_add_i32 s0, s0, s47
	global_load_lds_dwordx4 v[220:221], off
	v_lshl_add_u64 v[222:223], s[54:55], 0, v[136:137]
	s_mov_b32 m0, s0
	v_lshl_add_u64 v[224:225], s[34:35], 0, v[134:135]
	global_load_lds_dwordx4 v[222:223], off
	v_lshl_add_u64 v[222:223], s[54:55], 0, v[132:133]
	s_add_i32 m0, s0, 0x2000
	s_nop 0
	global_load_lds_dwordx4 v[222:223], off
	v_lshl_add_u64 v[222:223], s[34:35], 0, v[138:139]
	s_mov_b32 m0, s45
	s_nop 0
	global_load_lds_dwordx4 v[222:223], off
	s_mov_b32 m0, s61
	s_nop 0
	global_load_lds_dwordx4 v[224:225], off
	s_waitcnt vmcnt(8)
	s_waitcnt lgkmcnt(0)
	s_setprio 1
	s_barrier
	v_mfma_f32_16x16x32_bf16 v[64:67], v[144:147], v[184:187], v[64:67]
	v_mfma_f32_16x16x32_bf16 v[60:63], v[152:155], v[184:187], v[60:63]
	v_mfma_f32_16x16x32_bf16 v[48:51], v[144:147], v[192:195], v[48:51]
	v_mfma_f32_16x16x32_bf16 v[44:47], v[152:155], v[192:195], v[44:47]
	v_mfma_f32_16x16x32_bf16 v[32:35], v[144:147], v[204:207], v[32:35]
	v_mfma_f32_16x16x32_bf16 v[28:31], v[152:155], v[204:207], v[28:31]
	v_mfma_f32_16x16x32_bf16 v[16:19], v[144:147], v[212:215], v[16:19]
	v_mfma_f32_16x16x32_bf16 v[12:15], v[152:155], v[212:215], v[12:15]
	v_mfma_f32_16x16x32_bf16 v[64:67], v[148:151], v[188:191], v[64:67]
	v_mfma_f32_16x16x32_bf16 v[60:63], v[164:167], v[188:191], v[60:63]
	v_mfma_f32_16x16x32_bf16 v[48:51], v[148:151], v[200:203], v[48:51]
	v_mfma_f32_16x16x32_bf16 v[44:47], v[164:167], v[200:203], v[44:47]
	v_mfma_f32_16x16x32_bf16 v[32:35], v[148:151], v[208:211], v[32:35]
	v_mfma_f32_16x16x32_bf16 v[28:31], v[164:167], v[208:211], v[28:31]
	v_mfma_f32_16x16x32_bf16 v[16:19], v[148:151], v[216:219], v[16:19]
	v_mfma_f32_16x16x32_bf16 v[12:15], v[164:167], v[216:219], v[12:15]
	s_setprio 0
	s_setprio 1
	v_mfma_f32_16x16x32_bf16 v[56:59], v[168:171], v[184:187], v[56:59]
	v_mfma_f32_16x16x32_bf16 v[52:55], v[176:179], v[184:187], v[52:55]
	v_mfma_f32_16x16x32_bf16 v[40:43], v[168:171], v[192:195], v[40:43]
	v_mfma_f32_16x16x32_bf16 v[36:39], v[176:179], v[192:195], v[36:39]
	v_mfma_f32_16x16x32_bf16 v[24:27], v[168:171], v[204:207], v[24:27]
	v_mfma_f32_16x16x32_bf16 v[20:23], v[176:179], v[204:207], v[20:23]
	v_mfma_f32_16x16x32_bf16 v[8:11], v[168:171], v[212:215], v[8:11]
	v_mfma_f32_16x16x32_bf16 v[4:7], v[176:179], v[212:215], v[4:7]
	v_mfma_f32_16x16x32_bf16 v[56:59], v[172:175], v[188:191], v[56:59]
	v_mfma_f32_16x16x32_bf16 v[52:55], v[180:183], v[188:191], v[52:55]
	v_mfma_f32_16x16x32_bf16 v[40:43], v[172:175], v[200:203], v[40:43]
	v_mfma_f32_16x16x32_bf16 v[36:39], v[180:183], v[200:203], v[36:39]
	v_mfma_f32_16x16x32_bf16 v[24:27], v[172:175], v[208:211], v[24:27]
	v_mfma_f32_16x16x32_bf16 v[20:23], v[180:183], v[208:211], v[20:23]
	v_mfma_f32_16x16x32_bf16 v[8:11], v[172:175], v[216:219], v[8:11]
	v_mfma_f32_16x16x32_bf16 v[4:7], v[180:183], v[216:219], v[4:7]
	s_barrier
	s_setprio 0
	s_add_i32 s0, 0, 0x18000
	v_add_u32_e32 v158, s0, v159
	s_add_i32 s6, 0, 0x1c000
	ds_read_b128 v[144:147], v158
	ds_read_b128 v[148:151], v158 offset:1024
	ds_read_b128 v[152:155], v158 offset:2048
	ds_read_b128 v[164:167], v158 offset:3072
	v_add_u32_e32 v158, s6, v159
	ds_read_b128 v[168:171], v158
	ds_read_b128 v[172:175], v158 offset:1024
	ds_read_b128 v[176:179], v158 offset:2048
	ds_read_b128 v[180:183], v158 offset:3072
	s_add_u32 s34, s34, 0x80000
	s_addc_u32 s35, s35, 0
	s_mov_b32 m0, s62
	v_lshl_add_u64 v[226:227], s[34:35], 0, v[138:139]
	ds_read_b128 v[184:187], v163 offset:32768
	ds_read_b128 v[188:191], v163 offset:33792
	ds_read_b128 v[192:195], v163 offset:34816
	ds_read_b128 v[200:203], v163 offset:35840
	ds_read_b128 v[204:207], v163 offset:36864
	ds_read_b128 v[208:211], v163 offset:37888
	ds_read_b128 v[212:215], v163 offset:38912
	ds_read_b128 v[216:219], v163 offset:39936
	global_load_lds_dwordx4 v[226:227], off
	v_lshl_add_u64 v[226:227], s[34:35], 0, v[134:135]
	s_mov_b32 m0, s63
	s_nop 0
	global_load_lds_dwordx4 v[226:227], off
	s_waitcnt vmcnt(8)
	s_waitcnt lgkmcnt(0)
	s_setprio 1
	s_barrier
	v_mfma_f32_16x16x32_bf16 v[128:131], v[144:147], v[184:187], v[128:131]
	v_mfma_f32_16x16x32_bf16 v[124:127], v[152:155], v[184:187], v[124:127]
	v_mfma_f32_16x16x32_bf16 v[112:115], v[144:147], v[192:195], v[112:115]
	v_mfma_f32_16x16x32_bf16 v[108:111], v[152:155], v[192:195], v[108:111]
	v_mfma_f32_16x16x32_bf16 v[96:99], v[144:147], v[204:207], v[96:99]
	v_mfma_f32_16x16x32_bf16 v[92:95], v[152:155], v[204:207], v[92:95]
	v_mfma_f32_16x16x32_bf16 v[80:83], v[144:147], v[212:215], v[80:83]
	v_mfma_f32_16x16x32_bf16 v[76:79], v[152:155], v[212:215], v[76:79]
	v_mfma_f32_16x16x32_bf16 v[128:131], v[148:151], v[188:191], v[128:131]
	v_mfma_f32_16x16x32_bf16 v[124:127], v[164:167], v[188:191], v[124:127]
	v_mfma_f32_16x16x32_bf16 v[112:115], v[148:151], v[200:203], v[112:115]
	v_mfma_f32_16x16x32_bf16 v[108:111], v[164:167], v[200:203], v[108:111]
	v_mfma_f32_16x16x32_bf16 v[96:99], v[148:151], v[208:211], v[96:99]
	v_mfma_f32_16x16x32_bf16 v[92:95], v[164:167], v[208:211], v[92:95]
	v_mfma_f32_16x16x32_bf16 v[80:83], v[148:151], v[216:219], v[80:83]
	v_mfma_f32_16x16x32_bf16 v[76:79], v[164:167], v[216:219], v[76:79]
	s_setprio 0
	s_setprio 1
	v_mfma_f32_16x16x32_bf16 v[120:123], v[168:171], v[184:187], v[120:123]
	v_mfma_f32_16x16x32_bf16 v[116:119], v[176:179], v[184:187], v[116:119]
	v_mfma_f32_16x16x32_bf16 v[104:107], v[168:171], v[192:195], v[104:107]
	v_mfma_f32_16x16x32_bf16 v[100:103], v[176:179], v[192:195], v[100:103]
	v_mfma_f32_16x16x32_bf16 v[88:91], v[168:171], v[204:207], v[88:91]
	v_mfma_f32_16x16x32_bf16 v[84:87], v[176:179], v[204:207], v[84:87]
	v_mfma_f32_16x16x32_bf16 v[72:75], v[168:171], v[212:215], v[72:75]
	v_mfma_f32_16x16x32_bf16 v[68:71], v[176:179], v[212:215], v[68:71]
	v_mfma_f32_16x16x32_bf16 v[120:123], v[172:175], v[188:191], v[120:123]
	v_mfma_f32_16x16x32_bf16 v[116:119], v[180:183], v[188:191], v[116:119]
	v_mfma_f32_16x16x32_bf16 v[104:107], v[172:175], v[200:203], v[104:107]
	v_mfma_f32_16x16x32_bf16 v[100:103], v[180:183], v[200:203], v[100:103]
	v_mfma_f32_16x16x32_bf16 v[88:91], v[172:175], v[208:211], v[88:91]
	v_mfma_f32_16x16x32_bf16 v[84:87], v[180:183], v[208:211], v[84:87]
	v_mfma_f32_16x16x32_bf16 v[72:75], v[172:175], v[216:219], v[72:75]
	v_mfma_f32_16x16x32_bf16 v[68:71], v[180:183], v[216:219], v[68:71]
	s_barrier
	s_setprio 0
	s_add_i32 s0, s0, s47
	v_lshl_add_u64 v[156:157], v[156:157], 0, s[90:91]
	s_mov_b32 m0, s0
	ds_read_b128 v[184:187], v163 offset:49152
	ds_read_b128 v[188:191], v163 offset:50176
	ds_read_b128 v[192:195], v163 offset:51200
	ds_read_b128 v[200:203], v163 offset:52224
	ds_read_b128 v[204:207], v163 offset:53248
	ds_read_b128 v[208:211], v163 offset:54272
	ds_read_b128 v[212:215], v163 offset:55296
	ds_read_b128 v[216:219], v163 offset:56320
	global_load_lds_dwordx4 v[156:157], off
	s_add_i32 m0, s0, 0x2000
	s_add_u32 s30, s30, 0x80080
	v_lshl_add_u64 v[156:157], v[220:221], 0, s[90:91]
	s_addc_u32 s31, s31, 0
	s_add_i32 s0, s6, s47
	global_load_lds_dwordx4 v[156:157], off
	v_lshl_add_u64 v[156:157], s[30:31], 0, v[136:137]
	s_mov_b32 m0, s0
	s_nop 0
	global_load_lds_dwordx4 v[156:157], off
	v_lshl_add_u64 v[156:157], s[30:31], 0, v[132:133]
	s_add_i32 m0, s0, 0x2000
	s_nop 0
	global_load_lds_dwordx4 v[156:157], off
	v_lshl_add_u64 v[156:157], v[222:223], 0, s[90:91]
	s_mov_b32 m0, s51
	s_nop 0
	global_load_lds_dwordx4 v[156:157], off
	v_lshl_add_u64 v[156:157], v[224:225], 0, s[90:91]
	s_mov_b32 m0, s4
	s_nop 0
	global_load_lds_dwordx4 v[156:157], off
	s_nop 0
	s_waitcnt vmcnt(8)
	s_waitcnt lgkmcnt(0)
	s_setprio 1
	s_barrier
	v_mfma_f32_16x16x32_bf16 v[64:67], v[144:147], v[184:187], v[64:67]
	v_mfma_f32_16x16x32_bf16 v[60:63], v[152:155], v[184:187], v[60:63]
	v_mfma_f32_16x16x32_bf16 v[48:51], v[144:147], v[192:195], v[48:51]
	v_mfma_f32_16x16x32_bf16 v[44:47], v[152:155], v[192:195], v[44:47]
	v_mfma_f32_16x16x32_bf16 v[32:35], v[144:147], v[204:207], v[32:35]
	v_mfma_f32_16x16x32_bf16 v[28:31], v[152:155], v[204:207], v[28:31]
	v_mfma_f32_16x16x32_bf16 v[16:19], v[144:147], v[212:215], v[16:19]
	v_mfma_f32_16x16x32_bf16 v[12:15], v[152:155], v[212:215], v[12:15]
	v_mfma_f32_16x16x32_bf16 v[64:67], v[148:151], v[188:191], v[64:67]
	v_mfma_f32_16x16x32_bf16 v[60:63], v[164:167], v[188:191], v[60:63]
	v_mfma_f32_16x16x32_bf16 v[48:51], v[148:151], v[200:203], v[48:51]
	v_mfma_f32_16x16x32_bf16 v[44:47], v[164:167], v[200:203], v[44:47]
	v_mfma_f32_16x16x32_bf16 v[32:35], v[148:151], v[208:211], v[32:35]
	v_mfma_f32_16x16x32_bf16 v[28:31], v[164:167], v[208:211], v[28:31]
	v_mfma_f32_16x16x32_bf16 v[16:19], v[148:151], v[216:219], v[16:19]
	v_mfma_f32_16x16x32_bf16 v[12:15], v[164:167], v[216:219], v[12:15]
	s_setprio 0
	s_setprio 1
	v_mfma_f32_16x16x32_bf16 v[56:59], v[168:171], v[184:187], v[56:59]
	v_mfma_f32_16x16x32_bf16 v[52:55], v[176:179], v[184:187], v[52:55]
	v_mfma_f32_16x16x32_bf16 v[40:43], v[168:171], v[192:195], v[40:43]
	v_mfma_f32_16x16x32_bf16 v[36:39], v[176:179], v[192:195], v[36:39]
	v_mfma_f32_16x16x32_bf16 v[24:27], v[168:171], v[204:207], v[24:27]
	v_mfma_f32_16x16x32_bf16 v[20:23], v[176:179], v[204:207], v[20:23]
	v_mfma_f32_16x16x32_bf16 v[8:11], v[168:171], v[212:215], v[8:11]
	v_mfma_f32_16x16x32_bf16 v[4:7], v[176:179], v[212:215], v[4:7]
	v_mfma_f32_16x16x32_bf16 v[56:59], v[172:175], v[188:191], v[56:59]
	v_mfma_f32_16x16x32_bf16 v[52:55], v[180:183], v[188:191], v[52:55]
	v_mfma_f32_16x16x32_bf16 v[40:43], v[172:175], v[200:203], v[40:43]
	v_mfma_f32_16x16x32_bf16 v[36:39], v[180:183], v[200:203], v[36:39]
	v_mfma_f32_16x16x32_bf16 v[24:27], v[172:175], v[208:211], v[24:27]
	v_mfma_f32_16x16x32_bf16 v[20:23], v[180:183], v[208:211], v[20:23]
	v_mfma_f32_16x16x32_bf16 v[8:11], v[172:175], v[216:219], v[8:11]
	v_mfma_f32_16x16x32_bf16 v[4:7], v[180:183], v[216:219], v[4:7]
	s_barrier
	s_setprio 0
	s_add_i32 s50, s50, 2
	s_add_u32 s36, s36, 0x100
	s_addc_u32 s37, s37, 0
	s_add_u32 s38, s38, 0x100
	s_addc_u32 s39, s39, 0
	s_cmp_gt_u32 s50, 29
	s_cbranch_scc0 .LBB0_336
	s_and_b64 vcc, exec, s[22:23]
	s_cbranch_vccz .LBB0_339
	s_barrier

.LBB0_747:
	s_add_i32 s0, s6, 2
	s_add_u32 s25, s66, 0xfffc0080
	s_addc_u32 s29, s67, -1
	s_add_i32 s33, 0, 0x10000
	s_cmp_eq_u32 s13, s6
	s_cselect_b32 s35, s45, s29
	s_cselect_b32 s34, s44, s25
	v_add_u32_e32 v3, s33, v237
	s_cselect_b32 s31, s61, s24
	s_cselect_b32 s30, s60, s15
	s_add_i32 s6, 0, 0x14000
	ds_read_b128 v[146:149], v3
	ds_read_b128 v[150:153], v3 offset:1024
	ds_read_b128 v[154:157], v3 offset:2048
	ds_read_b128 v[158:161], v3 offset:3072
	v_add_u32_e32 v3, s6, v237
	ds_read_b128 v[162:165], v3
	ds_read_b128 v[166:169], v3 offset:1024
	ds_read_b128 v[170:173], v3 offset:2048
	ds_read_b128 v[174:177], v3 offset:3072
	v_lshl_add_u64 v[4:5], s[66:67], 0, v[142:143]
	s_add_i32 m0, s52, 0xc000
	ds_read_b128 v[178:181], v249
	ds_read_b128 v[182:185], v249 offset:1024
	ds_read_b128 v[186:189], v249 offset:2048
	ds_read_b128 v[190:193], v249 offset:3072
	ds_read_b128 v[200:203], v249 offset:4096
	ds_read_b128 v[204:207], v249 offset:5120
	ds_read_b128 v[208:211], v249 offset:6144
	ds_read_b128 v[212:215], v249 offset:7168
	global_load_lds_dwordx4 v[4:5], off
	v_lshl_add_u64 v[4:5], s[66:67], 0, v[144:145]
	s_add_i32 m0, s52, 0xe000
	s_nop 0
	global_load_lds_dwordx4 v[4:5], off
	s_nop 0
	s_waitcnt vmcnt(8)
	s_waitcnt lgkmcnt(0)
	s_setprio 1
	s_barrier
	v_mfma_f32_16x16x32_bf16 v[130:133], v[146:149], v[178:181], v[130:133]
	v_mfma_f32_16x16x32_bf16 v[126:129], v[154:157], v[178:181], v[126:129]
	v_mfma_f32_16x16x32_bf16 v[122:125], v[146:149], v[186:189], v[122:125]
	v_mfma_f32_16x16x32_bf16 v[118:121], v[154:157], v[186:189], v[118:121]
	v_mfma_f32_16x16x32_bf16 v[114:117], v[146:149], v[200:203], v[114:117]
	v_mfma_f32_16x16x32_bf16 v[110:113], v[154:157], v[200:203], v[110:113]
	v_mfma_f32_16x16x32_bf16 v[106:109], v[146:149], v[208:211], v[106:109]
	v_mfma_f32_16x16x32_bf16 v[102:105], v[154:157], v[208:211], v[102:105]
	v_mfma_f32_16x16x32_bf16 v[130:133], v[150:153], v[182:185], v[130:133]
	v_mfma_f32_16x16x32_bf16 v[126:129], v[158:161], v[182:185], v[126:129]
	v_mfma_f32_16x16x32_bf16 v[122:125], v[150:153], v[190:193], v[122:125]
	v_mfma_f32_16x16x32_bf16 v[118:121], v[158:161], v[190:193], v[118:121]
	v_mfma_f32_16x16x32_bf16 v[114:117], v[150:153], v[204:207], v[114:117]
	v_mfma_f32_16x16x32_bf16 v[110:113], v[158:161], v[204:207], v[110:113]
	v_mfma_f32_16x16x32_bf16 v[106:109], v[150:153], v[212:215], v[106:109]
	v_mfma_f32_16x16x32_bf16 v[102:105], v[158:161], v[212:215], v[102:105]
	s_setprio 0
	s_setprio 1
	v_mfma_f32_16x16x32_bf16 v[98:101], v[162:165], v[178:181], v[98:101]
	v_mfma_f32_16x16x32_bf16 v[94:97], v[170:173], v[178:181], v[94:97]
	v_mfma_f32_16x16x32_bf16 v[90:93], v[162:165], v[186:189], v[90:93]
	v_mfma_f32_16x16x32_bf16 v[86:89], v[170:173], v[186:189], v[86:89]
	v_mfma_f32_16x16x32_bf16 v[82:85], v[162:165], v[200:203], v[82:85]
	v_mfma_f32_16x16x32_bf16 v[78:81], v[170:173], v[200:203], v[78:81]
	v_mfma_f32_16x16x32_bf16 v[74:77], v[162:165], v[208:211], v[74:77]
	v_mfma_f32_16x16x32_bf16 v[70:73], v[170:173], v[208:211], v[70:73]
	v_mfma_f32_16x16x32_bf16 v[98:101], v[166:169], v[182:185], v[98:101]
	v_mfma_f32_16x16x32_bf16 v[94:97], v[174:177], v[182:185], v[94:97]
	v_mfma_f32_16x16x32_bf16 v[90:93], v[166:169], v[190:193], v[90:93]
	v_mfma_f32_16x16x32_bf16 v[86:89], v[174:177], v[190:193], v[86:89]
	v_mfma_f32_16x16x32_bf16 v[82:85], v[166:169], v[204:207], v[82:85]
	v_mfma_f32_16x16x32_bf16 v[78:81], v[174:177], v[204:207], v[78:81]
	v_mfma_f32_16x16x32_bf16 v[74:77], v[166:169], v[212:215], v[74:77]
	v_mfma_f32_16x16x32_bf16 v[70:73], v[174:177], v[212:215], v[70:73]
	s_barrier
	s_setprio 0
	s_add_i32 s25, s33, s47
	v_lshl_add_u64 v[194:195], s[30:31], 0, v[136:137]
	s_mov_b32 m0, s25
	ds_read_b128 v[178:181], v249 offset:16384
	ds_read_b128 v[182:185], v249 offset:17408
	ds_read_b128 v[186:189], v249 offset:18432
	ds_read_b128 v[190:193], v249 offset:19456
	ds_read_b128 v[200:203], v249 offset:20480
	ds_read_b128 v[204:207], v249 offset:21504
	ds_read_b128 v[208:211], v249 offset:22528
	ds_read_b128 v[212:215], v249 offset:23552
	global_load_lds_dwordx4 v[194:195], off
	s_add_i32 m0, s25, 0x2000
	s_add_u32 s36, s30, 0x40000
	v_lshl_add_u64 v[216:217], s[30:31], 0, v[140:141]
	s_addc_u32 s37, s31, 0
	s_add_i32 s6, s6, s47
	global_load_lds_dwordx4 v[216:217], off
	v_lshl_add_u64 v[4:5], s[36:37], 0, v[136:137]
	s_mov_b32 m0, s6
	v_lshl_add_u64 v[218:219], s[34:35], 0, v[134:135]
	global_load_lds_dwordx4 v[4:5], off
	v_lshl_add_u64 v[4:5], s[36:37], 0, v[140:141]
	s_add_i32 m0, s6, 0x2000
	v_lshl_add_u64 v[220:221], s[34:35], 0, v[138:139]
	global_load_lds_dwordx4 v[4:5], off
	s_mov_b32 m0, s52
	s_nop 0
	global_load_lds_dwordx4 v[218:219], off
	s_mov_b32 m0, s53
	s_nop 0
	global_load_lds_dwordx4 v[220:221], off
	s_nop 0
	s_waitcnt vmcnt(8)
	s_waitcnt lgkmcnt(0)
	s_setprio 1
	s_barrier
	v_mfma_f32_16x16x32_bf16 v[66:69], v[146:149], v[178:181], v[66:69]
	v_mfma_f32_16x16x32_bf16 v[62:65], v[154:157], v[178:181], v[62:65]
	v_mfma_f32_16x16x32_bf16 v[58:61], v[146:149], v[186:189], v[58:61]
	v_mfma_f32_16x16x32_bf16 v[54:57], v[154:157], v[186:189], v[54:57]
	v_mfma_f32_16x16x32_bf16 v[50:53], v[146:149], v[200:203], v[50:53]
	v_mfma_f32_16x16x32_bf16 v[46:49], v[154:157], v[200:203], v[46:49]
	v_mfma_f32_16x16x32_bf16 v[42:45], v[146:149], v[208:211], v[42:45]
	v_mfma_f32_16x16x32_bf16 v[38:41], v[154:157], v[208:211], v[38:41]
	v_mfma_f32_16x16x32_bf16 v[66:69], v[150:153], v[182:185], v[66:69]
	v_mfma_f32_16x16x32_bf16 v[62:65], v[158:161], v[182:185], v[62:65]
	v_mfma_f32_16x16x32_bf16 v[58:61], v[150:153], v[190:193], v[58:61]
	v_mfma_f32_16x16x32_bf16 v[54:57], v[158:161], v[190:193], v[54:57]
	v_mfma_f32_16x16x32_bf16 v[50:53], v[150:153], v[204:207], v[50:53]
	v_mfma_f32_16x16x32_bf16 v[46:49], v[158:161], v[204:207], v[46:49]
	v_mfma_f32_16x16x32_bf16 v[42:45], v[150:153], v[212:215], v[42:45]
	v_mfma_f32_16x16x32_bf16 v[38:41], v[158:161], v[212:215], v[38:41]
	s_setprio 0
	s_setprio 1
	v_mfma_f32_16x16x32_bf16 v[34:37], v[162:165], v[178:181], v[34:37]
	v_mfma_f32_16x16x32_bf16 v[30:33], v[170:173], v[178:181], v[30:33]
	v_mfma_f32_16x16x32_bf16 v[26:29], v[162:165], v[186:189], v[26:29]
	v_mfma_f32_16x16x32_bf16 v[22:25], v[170:173], v[186:189], v[22:25]
	v_mfma_f32_16x16x32_bf16 v[18:21], v[162:165], v[200:203], v[18:21]
	v_mfma_f32_16x16x32_bf16 v[14:17], v[170:173], v[200:203], v[14:17]
	v_mfma_f32_16x16x32_bf16 v[10:13], v[162:165], v[208:211], v[10:13]
	v_mfma_f32_16x16x32_bf16 v[4:7], v[170:173], v[208:211], v[6:9]
	v_mfma_f32_16x16x32_bf16 v[34:37], v[166:169], v[182:185], v[34:37]
	v_mfma_f32_16x16x32_bf16 v[30:33], v[174:177], v[182:185], v[30:33]
	v_mfma_f32_16x16x32_bf16 v[26:29], v[166:169], v[190:193], v[26:29]
	v_mfma_f32_16x16x32_bf16 v[22:25], v[174:177], v[190:193], v[22:25]
	v_mfma_f32_16x16x32_bf16 v[18:21], v[166:169], v[204:207], v[18:21]
	v_mfma_f32_16x16x32_bf16 v[14:17], v[174:177], v[204:207], v[14:17]
	v_mfma_f32_16x16x32_bf16 v[10:13], v[166:169], v[212:215], v[10:13]
	v_mfma_f32_16x16x32_bf16 v[4:7], v[174:177], v[212:215], v[4:7]
	s_barrier
	s_setprio 0
	s_add_i32 s6, 0, 0x18000
	v_add_u32_e32 v3, s6, v237
	s_add_i32 s25, 0, 0x1c000
	ds_read_b128 v[146:149], v3
	ds_read_b128 v[150:153], v3 offset:1024
	ds_read_b128 v[154:157], v3 offset:2048
	ds_read_b128 v[158:161], v3 offset:3072
	v_add_u32_e32 v3, s25, v237
	ds_read_b128 v[162:165], v3
	ds_read_b128 v[166:169], v3 offset:1024
	ds_read_b128 v[170:173], v3 offset:2048
	ds_read_b128 v[174:177], v3 offset:3072
	s_add_u32 s34, s34, 0x40000
	s_addc_u32 s35, s35, 0
	s_mov_b32 m0, s59
	v_lshl_add_u64 v[8:9], s[34:35], 0, v[134:135]
	ds_read_b128 v[178:181], v249 offset:32768
	ds_read_b128 v[182:185], v249 offset:33792
	ds_read_b128 v[186:189], v249 offset:34816
	ds_read_b128 v[190:193], v249 offset:35840
	ds_read_b128 v[200:203], v249 offset:36864
	ds_read_b128 v[204:207], v249 offset:37888
	ds_read_b128 v[208:211], v249 offset:38912
	ds_read_b128 v[212:215], v249 offset:39936
	global_load_lds_dwordx4 v[8:9], off
	v_lshl_add_u64 v[8:9], s[34:35], 0, v[138:139]
	s_mov_b32 m0, s63
	s_nop 0
	global_load_lds_dwordx4 v[8:9], off
	s_waitcnt vmcnt(8)
	s_waitcnt lgkmcnt(0)
	s_setprio 1
	s_barrier
	v_mfma_f32_16x16x32_bf16 v[130:133], v[146:149], v[178:181], v[130:133]
	v_mfma_f32_16x16x32_bf16 v[126:129], v[154:157], v[178:181], v[126:129]
	v_mfma_f32_16x16x32_bf16 v[122:125], v[146:149], v[186:189], v[122:125]
	v_mfma_f32_16x16x32_bf16 v[118:121], v[154:157], v[186:189], v[118:121]
	v_mfma_f32_16x16x32_bf16 v[114:117], v[146:149], v[200:203], v[114:117]
	v_mfma_f32_16x16x32_bf16 v[110:113], v[154:157], v[200:203], v[110:113]
	v_mfma_f32_16x16x32_bf16 v[106:109], v[146:149], v[208:211], v[106:109]
	v_mfma_f32_16x16x32_bf16 v[102:105], v[154:157], v[208:211], v[102:105]
	v_mfma_f32_16x16x32_bf16 v[130:133], v[150:153], v[182:185], v[130:133]
	v_mfma_f32_16x16x32_bf16 v[126:129], v[158:161], v[182:185], v[126:129]
	v_mfma_f32_16x16x32_bf16 v[122:125], v[150:153], v[190:193], v[122:125]
	v_mfma_f32_16x16x32_bf16 v[118:121], v[158:161], v[190:193], v[118:121]
	v_mfma_f32_16x16x32_bf16 v[114:117], v[150:153], v[204:207], v[114:117]
	v_mfma_f32_16x16x32_bf16 v[110:113], v[158:161], v[204:207], v[110:113]
	v_mfma_f32_16x16x32_bf16 v[106:109], v[150:153], v[212:215], v[106:109]
	v_mfma_f32_16x16x32_bf16 v[102:105], v[158:161], v[212:215], v[102:105]
	s_setprio 0
	s_setprio 1
	v_mfma_f32_16x16x32_bf16 v[98:101], v[162:165], v[178:181], v[98:101]
	v_mfma_f32_16x16x32_bf16 v[94:97], v[170:173], v[178:181], v[94:97]
	v_mfma_f32_16x16x32_bf16 v[90:93], v[162:165], v[186:189], v[90:93]
	v_mfma_f32_16x16x32_bf16 v[86:89], v[170:173], v[186:189], v[86:89]
	v_mfma_f32_16x16x32_bf16 v[82:85], v[162:165], v[200:203], v[82:85]
	v_mfma_f32_16x16x32_bf16 v[78:81], v[170:173], v[200:203], v[78:81]
	v_mfma_f32_16x16x32_bf16 v[74:77], v[162:165], v[208:211], v[74:77]
	v_mfma_f32_16x16x32_bf16 v[70:73], v[170:173], v[208:211], v[70:73]
	v_mfma_f32_16x16x32_bf16 v[98:101], v[166:169], v[182:185], v[98:101]
	v_mfma_f32_16x16x32_bf16 v[94:97], v[174:177], v[182:185], v[94:97]
	v_mfma_f32_16x16x32_bf16 v[90:93], v[166:169], v[190:193], v[90:93]
	v_mfma_f32_16x16x32_bf16 v[86:89], v[174:177], v[190:193], v[86:89]
	v_mfma_f32_16x16x32_bf16 v[82:85], v[166:169], v[204:207], v[82:85]
	v_mfma_f32_16x16x32_bf16 v[78:81], v[174:177], v[204:207], v[78:81]
	v_mfma_f32_16x16x32_bf16 v[74:77], v[166:169], v[212:215], v[74:77]
	v_mfma_f32_16x16x32_bf16 v[70:73], v[174:177], v[212:215], v[70:73]
	s_barrier
	s_setprio 0
	s_add_i32 s6, s6, s47
	v_lshl_add_u64 v[8:9], v[194:195], 0, s[90:91]
	s_mov_b32 m0, s6
	ds_read_b128 v[178:181], v249 offset:49152
	ds_read_b128 v[182:185], v249 offset:50176
	ds_read_b128 v[186:189], v249 offset:51200
	ds_read_b128 v[190:193], v249 offset:52224
	ds_read_b128 v[200:203], v249 offset:53248
	ds_read_b128 v[204:207], v249 offset:54272
	ds_read_b128 v[208:211], v249 offset:55296
	ds_read_b128 v[212:215], v249 offset:56320
	global_load_lds_dwordx4 v[8:9], off
	s_add_i32 m0, s6, 0x2000
	s_add_u32 s30, s30, 0x40080
	v_lshl_add_u64 v[8:9], v[216:217], 0, s[90:91]
	s_addc_u32 s31, s31, 0
	s_add_i32 s6, s25, s47
	global_load_lds_dwordx4 v[8:9], off
	v_lshl_add_u64 v[8:9], s[30:31], 0, v[136:137]
	s_mov_b32 m0, s6
	s_nop 0
	global_load_lds_dwordx4 v[8:9], off
	v_lshl_add_u64 v[8:9], s[30:31], 0, v[140:141]
	s_add_i32 m0, s6, 0x2000
	s_nop 0
	global_load_lds_dwordx4 v[8:9], off
	v_lshl_add_u64 v[8:9], v[218:219], 0, s[90:91]
	s_mov_b32 m0, s80
	s_nop 0
	global_load_lds_dwordx4 v[8:9], off
	v_lshl_add_u64 v[8:9], v[220:221], 0, s[90:91]
	s_mov_b32 m0, s81
	s_nop 0
	global_load_lds_dwordx4 v[8:9], off
	s_nop 0
	s_waitcnt vmcnt(8)
	s_waitcnt lgkmcnt(0)
	s_setprio 1
	s_barrier
	v_mfma_f32_16x16x32_bf16 v[66:69], v[146:149], v[178:181], v[66:69]
	v_mfma_f32_16x16x32_bf16 v[62:65], v[154:157], v[178:181], v[62:65]
	v_mfma_f32_16x16x32_bf16 v[58:61], v[146:149], v[186:189], v[58:61]
	v_mfma_f32_16x16x32_bf16 v[54:57], v[154:157], v[186:189], v[54:57]
	v_mfma_f32_16x16x32_bf16 v[50:53], v[146:149], v[200:203], v[50:53]
	v_mfma_f32_16x16x32_bf16 v[46:49], v[154:157], v[200:203], v[46:49]
	v_mfma_f32_16x16x32_bf16 v[42:45], v[146:149], v[208:211], v[42:45]
	v_mfma_f32_16x16x32_bf16 v[38:41], v[154:157], v[208:211], v[38:41]
	v_mfma_f32_16x16x32_bf16 v[66:69], v[150:153], v[182:185], v[66:69]
	v_mfma_f32_16x16x32_bf16 v[62:65], v[158:161], v[182:185], v[62:65]
	v_mfma_f32_16x16x32_bf16 v[58:61], v[150:153], v[190:193], v[58:61]
	v_mfma_f32_16x16x32_bf16 v[54:57], v[158:161], v[190:193], v[54:57]
	v_mfma_f32_16x16x32_bf16 v[50:53], v[150:153], v[204:207], v[50:53]
	v_mfma_f32_16x16x32_bf16 v[46:49], v[158:161], v[204:207], v[46:49]
	v_mfma_f32_16x16x32_bf16 v[42:45], v[150:153], v[212:215], v[42:45]
	v_mfma_f32_16x16x32_bf16 v[38:41], v[158:161], v[212:215], v[38:41]
	s_setprio 0
	s_setprio 1
	v_mfma_f32_16x16x32_bf16 v[34:37], v[162:165], v[178:181], v[34:37]
	v_mfma_f32_16x16x32_bf16 v[30:33], v[170:173], v[178:181], v[30:33]
	v_mfma_f32_16x16x32_bf16 v[26:29], v[162:165], v[186:189], v[26:29]
	v_mfma_f32_16x16x32_bf16 v[22:25], v[170:173], v[186:189], v[22:25]
	v_mfma_f32_16x16x32_bf16 v[18:21], v[162:165], v[200:203], v[18:21]
	v_mfma_f32_16x16x32_bf16 v[14:17], v[170:173], v[200:203], v[14:17]
	v_mfma_f32_16x16x32_bf16 v[8:11], v[162:165], v[208:211], v[10:13]
	v_mfma_f32_16x16x32_bf16 v[4:7], v[170:173], v[208:211], v[4:7]
	v_mfma_f32_16x16x32_bf16 v[34:37], v[166:169], v[182:185], v[34:37]
	v_mfma_f32_16x16x32_bf16 v[30:33], v[174:177], v[182:185], v[30:33]
	v_mfma_f32_16x16x32_bf16 v[26:29], v[166:169], v[190:193], v[26:29]
	v_mfma_f32_16x16x32_bf16 v[22:25], v[174:177], v[190:193], v[22:25]
	v_mfma_f32_16x16x32_bf16 v[18:21], v[166:169], v[204:207], v[18:21]
	v_mfma_f32_16x16x32_bf16 v[14:17], v[174:177], v[204:207], v[14:17]
	v_mfma_f32_16x16x32_bf16 v[10:13], v[166:169], v[212:215], v[8:11]
	v_mfma_f32_16x16x32_bf16 v[6:9], v[174:177], v[212:215], v[4:7]
	s_barrier
	s_setprio 0
	s_add_u32 s66, s66, 0x100
	s_addc_u32 s67, s67, 0
	s_add_u32 s15, s15, 0x100
	s_addc_u32 s24, s24, 0
	s_cmp_ge_i32 s0, s1
	s_mov_b32 s6, s0
	s_cbranch_scc0 .LBB0_747

.LBB0_967:
	s_add_u32 s0, s36, 0xfff80080
	s_addc_u32 s6, s37, -1
	s_add_i32 s49, 0, 0x10000
	s_cmp_eq_u32 s55, 28
	s_cselect_b32 s35, s65, s6
	s_cselect_b32 s34, s64, s0
	s_cselect_b32 s31, s67, s39
	s_cselect_b32 s30, s66, s38
	s_add_i32 s0, 0, 0x14000
	v_add_u32_e32 v144, s49, v3
	v_add_u32_e32 v160, s0, v3
	ds_read_b128 v[124:127], v144
	ds_read_b128 v[128:131], v144 offset:1024
	ds_read_b128 v[140:143], v144 offset:2048
	ds_read_b128 v[144:147], v144 offset:3072
	ds_read_b128 v[148:151], v160
	ds_read_b128 v[152:155], v160 offset:1024
	ds_read_b128 v[156:159], v160 offset:2048
	ds_read_b128 v[160:163], v160 offset:3072
	v_lshl_add_u64 v[198:199], s[36:37], 0, v[212:213]
	s_add_i32 m0, s4, 0xc000
	ds_read_b128 v[164:167], v250
	ds_read_b128 v[168:171], v250 offset:1024
	ds_read_b128 v[172:175], v250 offset:2048
	ds_read_b128 v[176:179], v250 offset:3072
	ds_read_b128 v[180:183], v250 offset:4096
	ds_read_b128 v[184:187], v250 offset:5120
	ds_read_b128 v[188:191], v250 offset:6144
	ds_read_b128 v[192:195], v250 offset:7168
	global_load_lds_dwordx4 v[198:199], off
	v_lshl_add_u64 v[198:199], s[36:37], 0, v[214:215]
	s_add_i32 m0, s4, 0xe000
	s_nop 0
	global_load_lds_dwordx4 v[198:199], off
	s_waitcnt vmcnt(8)
	s_waitcnt lgkmcnt(0)
	s_setprio 1
	s_barrier
	v_mfma_f32_16x16x32_bf16 v[136:139], v[124:127], v[164:167], v[136:139]
	v_mfma_f32_16x16x32_bf16 v[132:135], v[140:143], v[164:167], v[132:135]
	v_mfma_f32_16x16x32_bf16 v[112:115], v[124:127], v[172:175], v[112:115]
	v_mfma_f32_16x16x32_bf16 v[108:111], v[140:143], v[172:175], v[108:111]
	v_mfma_f32_16x16x32_bf16 v[96:99], v[124:127], v[180:183], v[96:99]
	v_mfma_f32_16x16x32_bf16 v[92:95], v[140:143], v[180:183], v[92:95]
	v_mfma_f32_16x16x32_bf16 v[80:83], v[124:127], v[188:191], v[80:83]
	v_mfma_f32_16x16x32_bf16 v[76:79], v[140:143], v[188:191], v[76:79]
	v_mfma_f32_16x16x32_bf16 v[136:139], v[128:131], v[168:171], v[136:139]
	v_mfma_f32_16x16x32_bf16 v[132:135], v[144:147], v[168:171], v[132:135]
	v_mfma_f32_16x16x32_bf16 v[112:115], v[128:131], v[176:179], v[112:115]
	v_mfma_f32_16x16x32_bf16 v[108:111], v[144:147], v[176:179], v[108:111]
	v_mfma_f32_16x16x32_bf16 v[96:99], v[128:131], v[184:187], v[96:99]
	v_mfma_f32_16x16x32_bf16 v[92:95], v[144:147], v[184:187], v[92:95]
	v_mfma_f32_16x16x32_bf16 v[80:83], v[128:131], v[192:195], v[80:83]
	v_mfma_f32_16x16x32_bf16 v[76:79], v[144:147], v[192:195], v[76:79]
	s_setprio 0
	s_setprio 1
	v_mfma_f32_16x16x32_bf16 v[120:123], v[148:151], v[164:167], v[120:123]
	v_mfma_f32_16x16x32_bf16 v[116:119], v[156:159], v[164:167], v[116:119]
	v_mfma_f32_16x16x32_bf16 v[104:107], v[148:151], v[172:175], v[104:107]
	v_mfma_f32_16x16x32_bf16 v[100:103], v[156:159], v[172:175], v[100:103]
	v_mfma_f32_16x16x32_bf16 v[88:91], v[148:151], v[180:183], v[88:91]
	v_mfma_f32_16x16x32_bf16 v[84:87], v[156:159], v[180:183], v[84:87]
	v_mfma_f32_16x16x32_bf16 v[72:75], v[148:151], v[188:191], v[72:75]
	v_mfma_f32_16x16x32_bf16 v[68:71], v[156:159], v[188:191], v[68:71]
	v_mfma_f32_16x16x32_bf16 v[120:123], v[152:155], v[168:171], v[120:123]
	v_mfma_f32_16x16x32_bf16 v[116:119], v[160:163], v[168:171], v[116:119]
	v_mfma_f32_16x16x32_bf16 v[104:107], v[152:155], v[176:179], v[104:107]
	v_mfma_f32_16x16x32_bf16 v[100:103], v[160:163], v[176:179], v[100:103]
	v_mfma_f32_16x16x32_bf16 v[88:91], v[152:155], v[184:187], v[88:91]
	v_mfma_f32_16x16x32_bf16 v[84:87], v[160:163], v[184:187], v[84:87]
	v_mfma_f32_16x16x32_bf16 v[72:75], v[152:155], v[192:195], v[72:75]
	v_mfma_f32_16x16x32_bf16 v[68:71], v[160:163], v[192:195], v[68:71]
	s_barrier
	s_setprio 0
	s_add_i32 s6, s49, s1
	v_lshl_add_u64 v[198:199], s[30:31], 0, v[204:205]
	s_mov_b32 m0, s6
	ds_read_b128 v[164:167], v250 offset:16384
	ds_read_b128 v[168:171], v250 offset:17408
	ds_read_b128 v[172:175], v250 offset:18432
	ds_read_b128 v[176:179], v250 offset:19456
	ds_read_b128 v[180:183], v250 offset:20480
	ds_read_b128 v[184:187], v250 offset:21504
	ds_read_b128 v[188:191], v250 offset:22528
	ds_read_b128 v[192:195], v250 offset:23552
	global_load_lds_dwordx4 v[198:199], off
	s_add_i32 m0, s6, 0x2000
	s_add_u32 s68, s30, 0x80000
	v_lshl_add_u64 v[216:217], s[30:31], 0, v[200:201]
	s_addc_u32 s69, s31, 0
	s_add_i32 s0, s0, s1
	global_load_lds_dwordx4 v[216:217], off
	v_lshl_add_u64 v[218:219], s[68:69], 0, v[204:205]
	s_mov_b32 m0, s0
	v_lshl_add_u64 v[220:221], s[34:35], 0, v[202:203]
	global_load_lds_dwordx4 v[218:219], off
	v_lshl_add_u64 v[218:219], s[68:69], 0, v[200:201]
	s_add_i32 m0, s0, 0x2000
	s_nop 0
	global_load_lds_dwordx4 v[218:219], off
	v_lshl_add_u64 v[218:219], s[34:35], 0, v[206:207]
	s_mov_b32 m0, s4
	s_nop 0
	global_load_lds_dwordx4 v[218:219], off
	s_mov_b32 m0, s24
	s_nop 0
	global_load_lds_dwordx4 v[220:221], off
	s_waitcnt vmcnt(8)
	s_waitcnt lgkmcnt(0)
	s_setprio 1
	s_barrier
	v_mfma_f32_16x16x32_bf16 v[64:67], v[124:127], v[164:167], v[64:67]
	v_mfma_f32_16x16x32_bf16 v[60:63], v[140:143], v[164:167], v[60:63]
	v_mfma_f32_16x16x32_bf16 v[48:51], v[124:127], v[172:175], v[48:51]
	v_mfma_f32_16x16x32_bf16 v[44:47], v[140:143], v[172:175], v[44:47]
	v_mfma_f32_16x16x32_bf16 v[32:35], v[124:127], v[180:183], v[32:35]
	v_mfma_f32_16x16x32_bf16 v[28:31], v[140:143], v[180:183], v[28:31]
	v_mfma_f32_16x16x32_bf16 v[16:19], v[124:127], v[188:191], v[16:19]
	v_mfma_f32_16x16x32_bf16 v[12:15], v[140:143], v[188:191], v[12:15]
	v_mfma_f32_16x16x32_bf16 v[64:67], v[128:131], v[168:171], v[64:67]
	v_mfma_f32_16x16x32_bf16 v[60:63], v[144:147], v[168:171], v[60:63]
	v_mfma_f32_16x16x32_bf16 v[48:51], v[128:131], v[176:179], v[48:51]
	v_mfma_f32_16x16x32_bf16 v[44:47], v[144:147], v[176:179], v[44:47]
	v_mfma_f32_16x16x32_bf16 v[32:35], v[128:131], v[184:187], v[32:35]
	v_mfma_f32_16x16x32_bf16 v[28:31], v[144:147], v[184:187], v[28:31]
	v_mfma_f32_16x16x32_bf16 v[16:19], v[128:131], v[192:195], v[16:19]
	v_mfma_f32_16x16x32_bf16 v[12:15], v[144:147], v[192:195], v[12:15]
	s_setprio 0
	s_setprio 1
	v_mfma_f32_16x16x32_bf16 v[56:59], v[148:151], v[164:167], v[56:59]
	v_mfma_f32_16x16x32_bf16 v[52:55], v[156:159], v[164:167], v[52:55]
	v_mfma_f32_16x16x32_bf16 v[40:43], v[148:151], v[172:175], v[40:43]
	v_mfma_f32_16x16x32_bf16 v[36:39], v[156:159], v[172:175], v[36:39]
	v_mfma_f32_16x16x32_bf16 v[24:27], v[148:151], v[180:183], v[24:27]
	v_mfma_f32_16x16x32_bf16 v[20:23], v[156:159], v[180:183], v[20:23]
	v_mfma_f32_16x16x32_bf16 v[8:11], v[148:151], v[188:191], v[8:11]
	v_mfma_f32_16x16x32_bf16 v[4:7], v[156:159], v[188:191], v[4:7]
	v_mfma_f32_16x16x32_bf16 v[56:59], v[152:155], v[168:171], v[56:59]
	v_mfma_f32_16x16x32_bf16 v[52:55], v[160:163], v[168:171], v[52:55]
	v_mfma_f32_16x16x32_bf16 v[40:43], v[152:155], v[176:179], v[40:43]
	v_mfma_f32_16x16x32_bf16 v[36:39], v[160:163], v[176:179], v[36:39]
	v_mfma_f32_16x16x32_bf16 v[24:27], v[152:155], v[184:187], v[24:27]
	v_mfma_f32_16x16x32_bf16 v[20:23], v[160:163], v[184:187], v[20:23]
	v_mfma_f32_16x16x32_bf16 v[8:11], v[152:155], v[192:195], v[8:11]
	v_mfma_f32_16x16x32_bf16 v[4:7], v[160:163], v[192:195], v[4:7]
	s_barrier
	s_setprio 0
	s_add_i32 s0, 0, 0x18000
	s_add_i32 s6, 0, 0x1c000
	v_add_u32_e32 v144, s0, v3
	v_add_u32_e32 v160, s6, v3
	ds_read_b128 v[124:127], v144
	ds_read_b128 v[128:131], v144 offset:1024
	ds_read_b128 v[140:143], v144 offset:2048
	ds_read_b128 v[144:147], v144 offset:3072
	ds_read_b128 v[148:151], v160
	ds_read_b128 v[152:155], v160 offset:1024
	ds_read_b128 v[156:159], v160 offset:2048
	ds_read_b128 v[160:163], v160 offset:3072
	s_add_u32 s34, s34, 0x80000
	s_addc_u32 s35, s35, 0
	s_mov_b32 m0, s25
	v_lshl_add_u64 v[222:223], s[34:35], 0, v[206:207]
	ds_read_b128 v[164:167], v250 offset:32768
	ds_read_b128 v[168:171], v250 offset:33792
	ds_read_b128 v[172:175], v250 offset:34816
	ds_read_b128 v[176:179], v250 offset:35840
	ds_read_b128 v[180:183], v250 offset:36864
	ds_read_b128 v[184:187], v250 offset:37888
	ds_read_b128 v[188:191], v250 offset:38912
	ds_read_b128 v[192:195], v250 offset:39936
	global_load_lds_dwordx4 v[222:223], off
	v_lshl_add_u64 v[222:223], s[34:35], 0, v[202:203]
	s_mov_b32 m0, s29
	s_nop 0
	global_load_lds_dwordx4 v[222:223], off
	s_waitcnt vmcnt(8)
	s_waitcnt lgkmcnt(0)
	s_setprio 1
	s_barrier
	v_mfma_f32_16x16x32_bf16 v[136:139], v[124:127], v[164:167], v[136:139]
	v_mfma_f32_16x16x32_bf16 v[132:135], v[140:143], v[164:167], v[132:135]
	v_mfma_f32_16x16x32_bf16 v[112:115], v[124:127], v[172:175], v[112:115]
	v_mfma_f32_16x16x32_bf16 v[108:111], v[140:143], v[172:175], v[108:111]
	v_mfma_f32_16x16x32_bf16 v[96:99], v[124:127], v[180:183], v[96:99]
	v_mfma_f32_16x16x32_bf16 v[92:95], v[140:143], v[180:183], v[92:95]
	v_mfma_f32_16x16x32_bf16 v[80:83], v[124:127], v[188:191], v[80:83]
	v_mfma_f32_16x16x32_bf16 v[76:79], v[140:143], v[188:191], v[76:79]
	v_mfma_f32_16x16x32_bf16 v[136:139], v[128:131], v[168:171], v[136:139]
	v_mfma_f32_16x16x32_bf16 v[132:135], v[144:147], v[168:171], v[132:135]
	v_mfma_f32_16x16x32_bf16 v[112:115], v[128:131], v[176:179], v[112:115]
	v_mfma_f32_16x16x32_bf16 v[108:111], v[144:147], v[176:179], v[108:111]
	v_mfma_f32_16x16x32_bf16 v[96:99], v[128:131], v[184:187], v[96:99]
	v_mfma_f32_16x16x32_bf16 v[92:95], v[144:147], v[184:187], v[92:95]
	v_mfma_f32_16x16x32_bf16 v[80:83], v[128:131], v[192:195], v[80:83]
	v_mfma_f32_16x16x32_bf16 v[76:79], v[144:147], v[192:195], v[76:79]
	s_setprio 0
	s_setprio 1
	v_mfma_f32_16x16x32_bf16 v[120:123], v[148:151], v[164:167], v[120:123]
	v_mfma_f32_16x16x32_bf16 v[116:119], v[156:159], v[164:167], v[116:119]
	v_mfma_f32_16x16x32_bf16 v[104:107], v[148:151], v[172:175], v[104:107]
	v_mfma_f32_16x16x32_bf16 v[100:103], v[156:159], v[172:175], v[100:103]
	v_mfma_f32_16x16x32_bf16 v[88:91], v[148:151], v[180:183], v[88:91]
	v_mfma_f32_16x16x32_bf16 v[84:87], v[156:159], v[180:183], v[84:87]
	v_mfma_f32_16x16x32_bf16 v[72:75], v[148:151], v[188:191], v[72:75]
	v_mfma_f32_16x16x32_bf16 v[68:71], v[156:159], v[188:191], v[68:71]
	v_mfma_f32_16x16x32_bf16 v[120:123], v[152:155], v[168:171], v[120:123]
	v_mfma_f32_16x16x32_bf16 v[116:119], v[160:163], v[168:171], v[116:119]
	v_mfma_f32_16x16x32_bf16 v[104:107], v[152:155], v[176:179], v[104:107]
	v_mfma_f32_16x16x32_bf16 v[100:103], v[160:163], v[176:179], v[100:103]
	v_mfma_f32_16x16x32_bf16 v[88:91], v[152:155], v[184:187], v[88:91]
	v_mfma_f32_16x16x32_bf16 v[84:87], v[160:163], v[184:187], v[84:87]
	v_mfma_f32_16x16x32_bf16 v[72:75], v[152:155], v[192:195], v[72:75]
	v_mfma_f32_16x16x32_bf16 v[68:71], v[160:163], v[192:195], v[68:71]
	s_barrier
	s_setprio 0
	s_add_i32 s0, s0, s1
	v_lshl_add_u64 v[198:199], v[198:199], 0, s[90:91]
	s_mov_b32 m0, s0
	ds_read_b128 v[164:167], v250 offset:49152
	ds_read_b128 v[168:171], v250 offset:50176
	ds_read_b128 v[172:175], v250 offset:51200
	ds_read_b128 v[176:179], v250 offset:52224
	ds_read_b128 v[180:183], v250 offset:53248
	ds_read_b128 v[184:187], v250 offset:54272
	ds_read_b128 v[188:191], v250 offset:55296
	ds_read_b128 v[192:195], v250 offset:56320
	global_load_lds_dwordx4 v[198:199], off
	s_add_i32 m0, s0, 0x2000
	s_add_u32 s30, s30, 0x80080
	v_lshl_add_u64 v[198:199], v[216:217], 0, s[90:91]
	s_addc_u32 s31, s31, 0
	s_add_i32 s0, s6, s1
	global_load_lds_dwordx4 v[198:199], off
	v_lshl_add_u64 v[198:199], s[30:31], 0, v[204:205]
	s_mov_b32 m0, s0
	s_nop 0
	global_load_lds_dwordx4 v[198:199], off
	v_lshl_add_u64 v[198:199], s[30:31], 0, v[200:201]
	s_add_i32 m0, s0, 0x2000
	s_nop 0
	global_load_lds_dwordx4 v[198:199], off
	v_lshl_add_u64 v[198:199], v[218:219], 0, s[90:91]
	s_mov_b32 m0, s33
	s_nop 0
	global_load_lds_dwordx4 v[198:199], off
	v_lshl_add_u64 v[198:199], v[220:221], 0, s[90:91]
	s_mov_b32 m0, s40
	s_nop 0
	global_load_lds_dwordx4 v[198:199], off
	s_nop 0
	s_waitcnt vmcnt(8)
	s_waitcnt lgkmcnt(0)
	s_setprio 1
	s_barrier
	v_mfma_f32_16x16x32_bf16 v[64:67], v[124:127], v[164:167], v[64:67]
	v_mfma_f32_16x16x32_bf16 v[60:63], v[140:143], v[164:167], v[60:63]
	v_mfma_f32_16x16x32_bf16 v[48:51], v[124:127], v[172:175], v[48:51]
	v_mfma_f32_16x16x32_bf16 v[44:47], v[140:143], v[172:175], v[44:47]
	v_mfma_f32_16x16x32_bf16 v[32:35], v[124:127], v[180:183], v[32:35]
	v_mfma_f32_16x16x32_bf16 v[28:31], v[140:143], v[180:183], v[28:31]
	v_mfma_f32_16x16x32_bf16 v[16:19], v[124:127], v[188:191], v[16:19]
	v_mfma_f32_16x16x32_bf16 v[12:15], v[140:143], v[188:191], v[12:15]
	v_mfma_f32_16x16x32_bf16 v[64:67], v[128:131], v[168:171], v[64:67]
	v_mfma_f32_16x16x32_bf16 v[60:63], v[144:147], v[168:171], v[60:63]
	v_mfma_f32_16x16x32_bf16 v[48:51], v[128:131], v[176:179], v[48:51]
	v_mfma_f32_16x16x32_bf16 v[44:47], v[144:147], v[176:179], v[44:47]
	v_mfma_f32_16x16x32_bf16 v[32:35], v[128:131], v[184:187], v[32:35]
	v_mfma_f32_16x16x32_bf16 v[28:31], v[144:147], v[184:187], v[28:31]
	v_mfma_f32_16x16x32_bf16 v[16:19], v[128:131], v[192:195], v[16:19]
	v_mfma_f32_16x16x32_bf16 v[12:15], v[144:147], v[192:195], v[12:15]
	s_setprio 0
	s_setprio 1
	v_mfma_f32_16x16x32_bf16 v[56:59], v[148:151], v[164:167], v[56:59]
	v_mfma_f32_16x16x32_bf16 v[52:55], v[156:159], v[164:167], v[52:55]
	v_mfma_f32_16x16x32_bf16 v[40:43], v[148:151], v[172:175], v[40:43]
	v_mfma_f32_16x16x32_bf16 v[36:39], v[156:159], v[172:175], v[36:39]
	v_mfma_f32_16x16x32_bf16 v[24:27], v[148:151], v[180:183], v[24:27]
	v_mfma_f32_16x16x32_bf16 v[20:23], v[156:159], v[180:183], v[20:23]
	v_mfma_f32_16x16x32_bf16 v[8:11], v[148:151], v[188:191], v[8:11]
	v_mfma_f32_16x16x32_bf16 v[4:7], v[156:159], v[188:191], v[4:7]
	v_mfma_f32_16x16x32_bf16 v[56:59], v[152:155], v[168:171], v[56:59]
	v_mfma_f32_16x16x32_bf16 v[52:55], v[160:163], v[168:171], v[52:55]
	v_mfma_f32_16x16x32_bf16 v[40:43], v[152:155], v[176:179], v[40:43]
	v_mfma_f32_16x16x32_bf16 v[36:39], v[160:163], v[176:179], v[36:39]
	v_mfma_f32_16x16x32_bf16 v[24:27], v[152:155], v[184:187], v[24:27]
	v_mfma_f32_16x16x32_bf16 v[20:23], v[160:163], v[184:187], v[20:23]
	v_mfma_f32_16x16x32_bf16 v[8:11], v[152:155], v[192:195], v[8:11]
	v_mfma_f32_16x16x32_bf16 v[4:7], v[160:163], v[192:195], v[4:7]
	s_barrier
	s_setprio 0
	s_add_i32 s55, s55, 2
	s_add_u32 s36, s36, 0x100
	s_addc_u32 s37, s37, 0
	s_add_u32 s38, s38, 0x100
	s_addc_u32 s39, s39, 0
	s_cmp_gt_u32 s55, 29
	s_cbranch_scc0 .LBB0_967
	s_and_b64 vcc, exec, s[44:45]
	s_cbranch_vccz .LBB0_970
	s_barrier

.LBB0_1017:
	s_add_u32 s0, s68, s30
	s_addc_u32 s6, s69, 0
	s_add_u32 s31, s0, 0x100
	s_addc_u32 s38, s6, 0
	s_and_b64 s[34:35], s[36:37], exec
	s_cselect_b32 vcc_hi, s65, s38
	s_cselect_b32 vcc_lo, s64, s31
	s_add_u32 s30, s74, s30
	s_addc_u32 s31, s75, 0
	s_add_u32 s34, s30, 0x100
	s_addc_u32 s35, s31, 0
	s_add_i32 s78, 0, 0x10000
	s_and_b64 s[30:31], s[36:37], exec
	s_cselect_b32 s53, s67, s35
	s_cselect_b32 s52, s66, s34
	s_add_i32 s37, 0, 0x14000
	s_add_u32 s34, s0, 0x80080
	s_addc_u32 s35, s6, 0
	s_add_i32 s73, s78, s1
	s_add_i32 m0, s4, 0xc000
	s_add_i32 s83, s4, 0xe000
	s_add_i32 s6, s73, 0x2000
	s_add_u32 s30, s52, 0x80000
	v_add_u32_e32 v144, s78, v3
	v_add_u32_e32 v160, s37, v3
	s_addc_u32 s31, s53, 0
	s_add_i32 s49, s37, s1
	ds_read_b128 v[132:135], v144
	ds_read_b128 v[136:139], v144 offset:1024
	ds_read_b128 v[140:143], v144 offset:2048
	ds_read_b128 v[144:147], v144 offset:3072
	ds_read_b128 v[148:151], v160
	ds_read_b128 v[152:155], v160 offset:1024
	ds_read_b128 v[156:159], v160 offset:2048
	ds_read_b128 v[160:163], v160 offset:3072
	s_add_i32 s63, s49, 0x2000
	s_add_i32 s54, 0, 0x18000
	s_add_i32 s61, 0, 0x1c000
	s_add_u32 s38, vcc_lo, 0x80000
	s_addc_u32 s39, vcc_hi, 0
	s_add_i32 s0, s54, s1
	s_add_i32 s45, s0, 0x2000
	s_add_u32 s36, s52, 0x80080
	s_addc_u32 s37, s53, 0
	s_add_i32 s82, s61, s1
	s_add_i32 s78, s82, 0x2000
	v_lshl_add_u64 v[198:199], s[34:35], 0, v[206:207]
	ds_read_b128 v[164:167], v236
	ds_read_b128 v[168:171], v236 offset:1024
	ds_read_b128 v[172:175], v236 offset:2048
	ds_read_b128 v[176:179], v236 offset:3072
	ds_read_b128 v[180:183], v236 offset:4096
	ds_read_b128 v[184:187], v236 offset:5120
	ds_read_b128 v[188:191], v236 offset:6144
	ds_read_b128 v[192:195], v236 offset:7168
	global_load_lds_dwordx4 v[198:199], off
	v_lshl_add_u64 v[198:199], s[34:35], 0, v[202:203]
	s_mov_b32 m0, s83
	s_nop 0
	global_load_lds_dwordx4 v[198:199], off
	s_nop 0
	s_waitcnt vmcnt(8)
	s_waitcnt lgkmcnt(0)
	s_setprio 1
	s_barrier
	v_mfma_f32_16x16x32_bf16 v[128:131], v[132:135], v[164:167], v[128:131]
	v_mfma_f32_16x16x32_bf16 v[124:127], v[140:143], v[164:167], v[124:127]
	v_mfma_f32_16x16x32_bf16 v[112:115], v[132:135], v[172:175], v[112:115]
	v_mfma_f32_16x16x32_bf16 v[108:111], v[140:143], v[172:175], v[108:111]
	v_mfma_f32_16x16x32_bf16 v[96:99], v[132:135], v[180:183], v[96:99]
	v_mfma_f32_16x16x32_bf16 v[92:95], v[140:143], v[180:183], v[92:95]
	v_mfma_f32_16x16x32_bf16 v[80:83], v[132:135], v[188:191], v[80:83]
	v_mfma_f32_16x16x32_bf16 v[76:79], v[140:143], v[188:191], v[76:79]
	v_mfma_f32_16x16x32_bf16 v[128:131], v[136:139], v[168:171], v[128:131]
	v_mfma_f32_16x16x32_bf16 v[124:127], v[144:147], v[168:171], v[124:127]
	v_mfma_f32_16x16x32_bf16 v[112:115], v[136:139], v[176:179], v[112:115]
	v_mfma_f32_16x16x32_bf16 v[108:111], v[144:147], v[176:179], v[108:111]
	v_mfma_f32_16x16x32_bf16 v[96:99], v[136:139], v[184:187], v[96:99]
	v_mfma_f32_16x16x32_bf16 v[92:95], v[144:147], v[184:187], v[92:95]
	v_mfma_f32_16x16x32_bf16 v[80:83], v[136:139], v[192:195], v[80:83]
	v_mfma_f32_16x16x32_bf16 v[76:79], v[144:147], v[192:195], v[76:79]
	s_setprio 0
	s_setprio 1
	v_mfma_f32_16x16x32_bf16 v[120:123], v[148:151], v[164:167], v[120:123]
	v_mfma_f32_16x16x32_bf16 v[116:119], v[156:159], v[164:167], v[116:119]
	v_mfma_f32_16x16x32_bf16 v[104:107], v[148:151], v[172:175], v[104:107]
	v_mfma_f32_16x16x32_bf16 v[100:103], v[156:159], v[172:175], v[100:103]
	v_mfma_f32_16x16x32_bf16 v[88:91], v[148:151], v[180:183], v[88:91]
	v_mfma_f32_16x16x32_bf16 v[84:87], v[156:159], v[180:183], v[84:87]
	v_mfma_f32_16x16x32_bf16 v[72:75], v[148:151], v[188:191], v[72:75]
	v_mfma_f32_16x16x32_bf16 v[68:71], v[156:159], v[188:191], v[68:71]
	v_mfma_f32_16x16x32_bf16 v[120:123], v[152:155], v[168:171], v[120:123]
	v_mfma_f32_16x16x32_bf16 v[116:119], v[160:163], v[168:171], v[116:119]
	v_mfma_f32_16x16x32_bf16 v[104:107], v[152:155], v[176:179], v[104:107]
	v_mfma_f32_16x16x32_bf16 v[100:103], v[160:163], v[176:179], v[100:103]
	v_mfma_f32_16x16x32_bf16 v[88:91], v[152:155], v[184:187], v[88:91]
	v_mfma_f32_16x16x32_bf16 v[84:87], v[160:163], v[184:187], v[84:87]
	v_mfma_f32_16x16x32_bf16 v[72:75], v[152:155], v[192:195], v[72:75]
	v_mfma_f32_16x16x32_bf16 v[68:71], v[160:163], v[192:195], v[68:71]
	s_barrier
	s_setprio 0
	s_mov_b32 m0, s73
	v_lshl_add_u64 v[198:199], s[52:53], 0, v[204:205]
	ds_read_b128 v[164:167], v236 offset:16384
	ds_read_b128 v[168:171], v236 offset:17408
	ds_read_b128 v[172:175], v236 offset:18432
	ds_read_b128 v[176:179], v236 offset:19456
	ds_read_b128 v[180:183], v236 offset:20480
	ds_read_b128 v[184:187], v236 offset:21504
	ds_read_b128 v[188:191], v236 offset:22528
	ds_read_b128 v[192:195], v236 offset:23552
	global_load_lds_dwordx4 v[198:199], off
	v_lshl_add_u64 v[212:213], s[52:53], 0, v[200:201]
	s_mov_b32 m0, s6
	v_lshl_add_u64 v[214:215], s[30:31], 0, v[204:205]
	global_load_lds_dwordx4 v[212:213], off
	s_mov_b32 m0, s49
	v_lshl_add_u64 v[216:217], vcc, 0, v[202:203]
	global_load_lds_dwordx4 v[214:215], off
	v_lshl_add_u64 v[214:215], s[30:31], 0, v[200:201]
	s_mov_b32 m0, s63
	s_nop 0
	global_load_lds_dwordx4 v[214:215], off
	v_lshl_add_u64 v[214:215], vcc, 0, v[206:207]
	s_mov_b32 m0, s4
	s_nop 0
	global_load_lds_dwordx4 v[214:215], off
	s_mov_b32 m0, s24
	s_nop 0
	global_load_lds_dwordx4 v[216:217], off
	s_nop 0
	s_waitcnt vmcnt(8)
	s_waitcnt lgkmcnt(0)
	s_setprio 1
	s_barrier
	v_mfma_f32_16x16x32_bf16 v[64:67], v[132:135], v[164:167], v[64:67]
	v_mfma_f32_16x16x32_bf16 v[60:63], v[140:143], v[164:167], v[60:63]
	v_mfma_f32_16x16x32_bf16 v[48:51], v[132:135], v[172:175], v[48:51]
	v_mfma_f32_16x16x32_bf16 v[44:47], v[140:143], v[172:175], v[44:47]
	v_mfma_f32_16x16x32_bf16 v[32:35], v[132:135], v[180:183], v[32:35]
	v_mfma_f32_16x16x32_bf16 v[28:31], v[140:143], v[180:183], v[28:31]
	v_mfma_f32_16x16x32_bf16 v[16:19], v[132:135], v[188:191], v[16:19]
	v_mfma_f32_16x16x32_bf16 v[12:15], v[140:143], v[188:191], v[12:15]
	v_mfma_f32_16x16x32_bf16 v[64:67], v[136:139], v[168:171], v[64:67]
	v_mfma_f32_16x16x32_bf16 v[60:63], v[144:147], v[168:171], v[60:63]
	v_mfma_f32_16x16x32_bf16 v[48:51], v[136:139], v[176:179], v[48:51]
	v_mfma_f32_16x16x32_bf16 v[44:47], v[144:147], v[176:179], v[44:47]
	v_mfma_f32_16x16x32_bf16 v[32:35], v[136:139], v[184:187], v[32:35]
	v_mfma_f32_16x16x32_bf16 v[28:31], v[144:147], v[184:187], v[28:31]
	v_mfma_f32_16x16x32_bf16 v[16:19], v[136:139], v[192:195], v[16:19]
	v_mfma_f32_16x16x32_bf16 v[12:15], v[144:147], v[192:195], v[12:15]
	s_setprio 0
	s_setprio 1
	v_mfma_f32_16x16x32_bf16 v[56:59], v[148:151], v[164:167], v[56:59]
	v_mfma_f32_16x16x32_bf16 v[52:55], v[156:159], v[164:167], v[52:55]
	v_mfma_f32_16x16x32_bf16 v[40:43], v[148:151], v[172:175], v[40:43]
	v_mfma_f32_16x16x32_bf16 v[36:39], v[156:159], v[172:175], v[36:39]
	v_mfma_f32_16x16x32_bf16 v[24:27], v[148:151], v[180:183], v[24:27]
	v_mfma_f32_16x16x32_bf16 v[20:23], v[156:159], v[180:183], v[20:23]
	v_mfma_f32_16x16x32_bf16 v[8:11], v[148:151], v[188:191], v[8:11]
	v_mfma_f32_16x16x32_bf16 v[4:7], v[156:159], v[188:191], v[4:7]
	v_mfma_f32_16x16x32_bf16 v[56:59], v[152:155], v[168:171], v[56:59]
	v_mfma_f32_16x16x32_bf16 v[52:55], v[160:163], v[168:171], v[52:55]
	v_mfma_f32_16x16x32_bf16 v[40:43], v[152:155], v[176:179], v[40:43]
	v_mfma_f32_16x16x32_bf16 v[36:39], v[160:163], v[176:179], v[36:39]
	v_mfma_f32_16x16x32_bf16 v[24:27], v[152:155], v[184:187], v[24:27]
	v_mfma_f32_16x16x32_bf16 v[20:23], v[160:163], v[184:187], v[20:23]
	v_mfma_f32_16x16x32_bf16 v[8:11], v[152:155], v[192:195], v[8:11]
	v_mfma_f32_16x16x32_bf16 v[4:7], v[160:163], v[192:195], v[4:7]
	s_barrier
	s_setprio 0
	v_add_u32_e32 v144, s54, v3
	v_add_u32_e32 v160, s61, v3
	ds_read_b128 v[132:135], v144
	ds_read_b128 v[136:139], v144 offset:1024
	ds_read_b128 v[140:143], v144 offset:2048
	ds_read_b128 v[144:147], v144 offset:3072
	ds_read_b128 v[148:151], v160
	ds_read_b128 v[152:155], v160 offset:1024
	ds_read_b128 v[156:159], v160 offset:2048
	ds_read_b128 v[160:163], v160 offset:3072
	s_mov_b32 m0, s25
	v_lshl_add_u64 v[218:219], s[38:39], 0, v[206:207]
	ds_read_b128 v[164:167], v236 offset:32768
	ds_read_b128 v[168:171], v236 offset:33792
	ds_read_b128 v[172:175], v236 offset:34816
	ds_read_b128 v[176:179], v236 offset:35840
	ds_read_b128 v[180:183], v236 offset:36864
	ds_read_b128 v[184:187], v236 offset:37888
	ds_read_b128 v[188:191], v236 offset:38912
	ds_read_b128 v[192:195], v236 offset:39936
	global_load_lds_dwordx4 v[218:219], off
	v_lshl_add_u64 v[218:219], s[38:39], 0, v[202:203]
	s_mov_b32 m0, s33
	s_nop 0
	global_load_lds_dwordx4 v[218:219], off
	s_nop 0
	s_waitcnt vmcnt(8)
	s_waitcnt lgkmcnt(0)
	s_setprio 1
	s_barrier
	v_mfma_f32_16x16x32_bf16 v[128:131], v[132:135], v[164:167], v[128:131]
	v_mfma_f32_16x16x32_bf16 v[124:127], v[140:143], v[164:167], v[124:127]
	v_mfma_f32_16x16x32_bf16 v[112:115], v[132:135], v[172:175], v[112:115]
	v_mfma_f32_16x16x32_bf16 v[108:111], v[140:143], v[172:175], v[108:111]
	v_mfma_f32_16x16x32_bf16 v[96:99], v[132:135], v[180:183], v[96:99]
	v_mfma_f32_16x16x32_bf16 v[92:95], v[140:143], v[180:183], v[92:95]
	v_mfma_f32_16x16x32_bf16 v[80:83], v[132:135], v[188:191], v[80:83]
	v_mfma_f32_16x16x32_bf16 v[76:79], v[140:143], v[188:191], v[76:79]
	v_mfma_f32_16x16x32_bf16 v[128:131], v[136:139], v[168:171], v[128:131]
	v_mfma_f32_16x16x32_bf16 v[124:127], v[144:147], v[168:171], v[124:127]
	v_mfma_f32_16x16x32_bf16 v[112:115], v[136:139], v[176:179], v[112:115]
	v_mfma_f32_16x16x32_bf16 v[108:111], v[144:147], v[176:179], v[108:111]
	v_mfma_f32_16x16x32_bf16 v[96:99], v[136:139], v[184:187], v[96:99]
	v_mfma_f32_16x16x32_bf16 v[92:95], v[144:147], v[184:187], v[92:95]
	v_mfma_f32_16x16x32_bf16 v[80:83], v[136:139], v[192:195], v[80:83]
	v_mfma_f32_16x16x32_bf16 v[76:79], v[144:147], v[192:195], v[76:79]
	s_setprio 0
	s_setprio 1
	v_mfma_f32_16x16x32_bf16 v[120:123], v[148:151], v[164:167], v[120:123]
	v_mfma_f32_16x16x32_bf16 v[116:119], v[156:159], v[164:167], v[116:119]
	v_mfma_f32_16x16x32_bf16 v[104:107], v[148:151], v[172:175], v[104:107]
	v_mfma_f32_16x16x32_bf16 v[100:103], v[156:159], v[172:175], v[100:103]
	v_mfma_f32_16x16x32_bf16 v[88:91], v[148:151], v[180:183], v[88:91]
	v_mfma_f32_16x16x32_bf16 v[84:87], v[156:159], v[180:183], v[84:87]
	v_mfma_f32_16x16x32_bf16 v[72:75], v[148:151], v[188:191], v[72:75]
	v_mfma_f32_16x16x32_bf16 v[68:71], v[156:159], v[188:191], v[68:71]
	v_mfma_f32_16x16x32_bf16 v[120:123], v[152:155], v[168:171], v[120:123]
	v_mfma_f32_16x16x32_bf16 v[116:119], v[160:163], v[168:171], v[116:119]
	v_mfma_f32_16x16x32_bf16 v[104:107], v[152:155], v[176:179], v[104:107]
	v_mfma_f32_16x16x32_bf16 v[100:103], v[160:163], v[176:179], v[100:103]
	v_mfma_f32_16x16x32_bf16 v[88:91], v[152:155], v[184:187], v[88:91]
	v_mfma_f32_16x16x32_bf16 v[84:87], v[160:163], v[184:187], v[84:87]
	v_mfma_f32_16x16x32_bf16 v[72:75], v[152:155], v[192:195], v[72:75]
	v_mfma_f32_16x16x32_bf16 v[68:71], v[160:163], v[192:195], v[68:71]
	s_barrier
	s_setprio 0
	s_mov_b32 m0, s0
	v_lshl_add_u64 v[198:199], v[198:199], 0, s[90:91]
	ds_read_b128 v[164:167], v236 offset:49152
	ds_read_b128 v[168:171], v236 offset:50176
	ds_read_b128 v[172:175], v236 offset:51200
	ds_read_b128 v[176:179], v236 offset:52224
	ds_read_b128 v[180:183], v236 offset:53248
	ds_read_b128 v[184:187], v236 offset:54272
	ds_read_b128 v[188:191], v236 offset:55296
	ds_read_b128 v[192:195], v236 offset:56320
	global_load_lds_dwordx4 v[198:199], off
	v_lshl_add_u64 v[198:199], v[212:213], 0, s[90:91]
	s_mov_b32 m0, s45
	s_nop 0
	global_load_lds_dwordx4 v[198:199], off
	v_lshl_add_u64 v[198:199], s[36:37], 0, v[204:205]
	s_mov_b32 m0, s82
	s_nop 0
	global_load_lds_dwordx4 v[198:199], off
	v_lshl_add_u64 v[198:199], s[36:37], 0, v[200:201]
	s_mov_b32 m0, s78
	s_nop 0
	global_load_lds_dwordx4 v[198:199], off
	v_lshl_add_u64 v[198:199], v[214:215], 0, s[90:91]
	s_mov_b32 m0, s40
	s_nop 0
	global_load_lds_dwordx4 v[198:199], off
	v_lshl_add_u64 v[198:199], v[216:217], 0, s[90:91]
	s_mov_b32 m0, s50
	s_nop 0
	global_load_lds_dwordx4 v[198:199], off
	s_nop 0
	s_waitcnt vmcnt(8)
	s_waitcnt lgkmcnt(0)
	s_setprio 1
	s_barrier
	v_mfma_f32_16x16x32_bf16 v[64:67], v[132:135], v[164:167], v[64:67]
	v_mfma_f32_16x16x32_bf16 v[60:63], v[140:143], v[164:167], v[60:63]
	v_mfma_f32_16x16x32_bf16 v[48:51], v[132:135], v[172:175], v[48:51]
	v_mfma_f32_16x16x32_bf16 v[44:47], v[140:143], v[172:175], v[44:47]
	v_mfma_f32_16x16x32_bf16 v[32:35], v[132:135], v[180:183], v[32:35]
	v_mfma_f32_16x16x32_bf16 v[28:31], v[140:143], v[180:183], v[28:31]
	v_mfma_f32_16x16x32_bf16 v[16:19], v[132:135], v[188:191], v[16:19]
	v_mfma_f32_16x16x32_bf16 v[12:15], v[140:143], v[188:191], v[12:15]
	v_mfma_f32_16x16x32_bf16 v[64:67], v[136:139], v[168:171], v[64:67]
	v_mfma_f32_16x16x32_bf16 v[60:63], v[144:147], v[168:171], v[60:63]
	v_mfma_f32_16x16x32_bf16 v[48:51], v[136:139], v[176:179], v[48:51]
	v_mfma_f32_16x16x32_bf16 v[44:47], v[144:147], v[176:179], v[44:47]
	v_mfma_f32_16x16x32_bf16 v[32:35], v[136:139], v[184:187], v[32:35]
	v_mfma_f32_16x16x32_bf16 v[28:31], v[144:147], v[184:187], v[28:31]
	v_mfma_f32_16x16x32_bf16 v[16:19], v[136:139], v[192:195], v[16:19]
	v_mfma_f32_16x16x32_bf16 v[12:15], v[144:147], v[192:195], v[12:15]
	s_setprio 0
	s_setprio 1
	v_mfma_f32_16x16x32_bf16 v[56:59], v[148:151], v[164:167], v[56:59]
	v_mfma_f32_16x16x32_bf16 v[52:55], v[156:159], v[164:167], v[52:55]
	v_mfma_f32_16x16x32_bf16 v[40:43], v[148:151], v[172:175], v[40:43]
	v_mfma_f32_16x16x32_bf16 v[36:39], v[156:159], v[172:175], v[36:39]
	v_mfma_f32_16x16x32_bf16 v[24:27], v[148:151], v[180:183], v[24:27]
	v_mfma_f32_16x16x32_bf16 v[20:23], v[156:159], v[180:183], v[20:23]
	v_mfma_f32_16x16x32_bf16 v[8:11], v[148:151], v[188:191], v[8:11]
	v_mfma_f32_16x16x32_bf16 v[4:7], v[156:159], v[188:191], v[4:7]
	v_mfma_f32_16x16x32_bf16 v[56:59], v[152:155], v[168:171], v[56:59]
	v_mfma_f32_16x16x32_bf16 v[52:55], v[160:163], v[168:171], v[52:55]
	v_mfma_f32_16x16x32_bf16 v[40:43], v[152:155], v[176:179], v[40:43]
	v_mfma_f32_16x16x32_bf16 v[36:39], v[160:163], v[176:179], v[36:39]
	v_mfma_f32_16x16x32_bf16 v[24:27], v[152:155], v[184:187], v[24:27]
	v_mfma_f32_16x16x32_bf16 v[20:23], v[160:163], v[184:187], v[20:23]
	v_mfma_f32_16x16x32_bf16 v[8:11], v[152:155], v[192:195], v[8:11]
	v_mfma_f32_16x16x32_bf16 v[4:7], v[160:163], v[192:195], v[4:7]
	s_barrier
	s_setprio 0
	s_movk_i32 s30, 0x100
	s_andn2_b64 vcc, exec, s[80:81]
	s_mov_b64 s[36:37], -1
	s_mov_b64 s[80:81], 0
	s_cbranch_vccz .LBB0_1017
	s_and_b64 vcc, exec, s[42:43]
	s_cbranch_vccz .LBB0_1020
	s_barrier

.LBB0_1137:
	s_add_u32 s0, s36, 0xfff80080
	s_addc_u32 s6, s37, -1
	s_add_i32 s49, 0, 0x10000
	s_cmp_eq_u32 s66, 28
	s_cselect_b32 s35, s29, s6
	s_cselect_b32 s34, s64, s0
	v_add_u32_e32 v156, s49, v157
	s_cselect_b32 s31, s23, s39
	s_cselect_b32 s30, s65, s38
	s_add_i32 s0, 0, 0x14000
	ds_read_b128 v[144:147], v156
	ds_read_b128 v[148:151], v156 offset:1024
	ds_read_b128 v[152:155], v156 offset:2048
	ds_read_b128 v[162:165], v156 offset:3072
	v_add_u32_e32 v156, s0, v157
	ds_read_b128 v[166:169], v156
	ds_read_b128 v[170:173], v156 offset:1024
	ds_read_b128 v[174:177], v156 offset:2048
	ds_read_b128 v[178:181], v156 offset:3072
	v_lshl_add_u64 v[194:195], s[36:37], 0, v[140:141]
	s_add_i32 m0, s33, 0xc000
	ds_read_b128 v[182:185], v161
	ds_read_b128 v[186:189], v161 offset:1024
	ds_read_b128 v[190:193], v161 offset:2048
	ds_read_b128 v[200:203], v161 offset:3072
	ds_read_b128 v[204:207], v161 offset:4096
	ds_read_b128 v[208:211], v161 offset:5120
	ds_read_b128 v[212:215], v161 offset:6144
	ds_read_b128 v[216:219], v161 offset:7168
	global_load_lds_dwordx4 v[194:195], off
	v_lshl_add_u64 v[194:195], s[36:37], 0, v[142:143]
	s_add_i32 m0, s33, 0xe000
	s_nop 0
	global_load_lds_dwordx4 v[194:195], off
	s_nop 0
	s_waitcnt vmcnt(8)
	s_waitcnt lgkmcnt(0)
	s_setprio 1
	s_barrier
	v_mfma_f32_16x16x32_bf16 v[128:131], v[144:147], v[182:185], v[128:131]
	v_mfma_f32_16x16x32_bf16 v[124:127], v[152:155], v[182:185], v[124:127]
	v_mfma_f32_16x16x32_bf16 v[112:115], v[144:147], v[190:193], v[112:115]
	v_mfma_f32_16x16x32_bf16 v[108:111], v[152:155], v[190:193], v[108:111]
	v_mfma_f32_16x16x32_bf16 v[96:99], v[144:147], v[204:207], v[96:99]
	v_mfma_f32_16x16x32_bf16 v[92:95], v[152:155], v[204:207], v[92:95]
	v_mfma_f32_16x16x32_bf16 v[80:83], v[144:147], v[212:215], v[80:83]
	v_mfma_f32_16x16x32_bf16 v[76:79], v[152:155], v[212:215], v[76:79]
	v_mfma_f32_16x16x32_bf16 v[128:131], v[148:151], v[186:189], v[128:131]
	v_mfma_f32_16x16x32_bf16 v[124:127], v[162:165], v[186:189], v[124:127]
	v_mfma_f32_16x16x32_bf16 v[112:115], v[148:151], v[200:203], v[112:115]
	v_mfma_f32_16x16x32_bf16 v[108:111], v[162:165], v[200:203], v[108:111]
	v_mfma_f32_16x16x32_bf16 v[96:99], v[148:151], v[208:211], v[96:99]
	v_mfma_f32_16x16x32_bf16 v[92:95], v[162:165], v[208:211], v[92:95]
	v_mfma_f32_16x16x32_bf16 v[80:83], v[148:151], v[216:219], v[80:83]
	v_mfma_f32_16x16x32_bf16 v[76:79], v[162:165], v[216:219], v[76:79]
	s_setprio 0
	s_setprio 1
	v_mfma_f32_16x16x32_bf16 v[120:123], v[166:169], v[182:185], v[120:123]
	v_mfma_f32_16x16x32_bf16 v[116:119], v[174:177], v[182:185], v[116:119]
	v_mfma_f32_16x16x32_bf16 v[104:107], v[166:169], v[190:193], v[104:107]
	v_mfma_f32_16x16x32_bf16 v[100:103], v[174:177], v[190:193], v[100:103]
	v_mfma_f32_16x16x32_bf16 v[88:91], v[166:169], v[204:207], v[88:91]
	v_mfma_f32_16x16x32_bf16 v[84:87], v[174:177], v[204:207], v[84:87]
	v_mfma_f32_16x16x32_bf16 v[72:75], v[166:169], v[212:215], v[72:75]
	v_mfma_f32_16x16x32_bf16 v[68:71], v[174:177], v[212:215], v[68:71]
	v_mfma_f32_16x16x32_bf16 v[120:123], v[170:173], v[186:189], v[120:123]
	v_mfma_f32_16x16x32_bf16 v[116:119], v[178:181], v[186:189], v[116:119]
	v_mfma_f32_16x16x32_bf16 v[104:107], v[170:173], v[200:203], v[104:107]
	v_mfma_f32_16x16x32_bf16 v[100:103], v[178:181], v[200:203], v[100:103]
	v_mfma_f32_16x16x32_bf16 v[88:91], v[170:173], v[208:211], v[88:91]
	v_mfma_f32_16x16x32_bf16 v[84:87], v[178:181], v[208:211], v[84:87]
	v_mfma_f32_16x16x32_bf16 v[72:75], v[170:173], v[216:219], v[72:75]
	v_mfma_f32_16x16x32_bf16 v[68:71], v[178:181], v[216:219], v[68:71]
	s_barrier
	s_setprio 0
	s_add_i32 s6, s49, s25
	v_lshl_add_u64 v[194:195], s[30:31], 0, v[136:137]
	s_mov_b32 m0, s6
	ds_read_b128 v[182:185], v161 offset:16384
	ds_read_b128 v[186:189], v161 offset:17408
	ds_read_b128 v[190:193], v161 offset:18432
	ds_read_b128 v[200:203], v161 offset:19456
	ds_read_b128 v[204:207], v161 offset:20480
	ds_read_b128 v[208:211], v161 offset:21504
	ds_read_b128 v[212:215], v161 offset:22528
	ds_read_b128 v[216:219], v161 offset:23552
	global_load_lds_dwordx4 v[194:195], off
	s_add_i32 m0, s6, 0x2000
	s_add_u32 s68, s30, 0x80000
	v_lshl_add_u64 v[198:199], s[30:31], 0, v[132:133]
	s_addc_u32 s69, s31, 0
	s_add_i32 s0, s0, s25
	global_load_lds_dwordx4 v[198:199], off
	v_lshl_add_u64 v[220:221], s[68:69], 0, v[136:137]
	s_mov_b32 m0, s0
	v_lshl_add_u64 v[222:223], s[34:35], 0, v[134:135]
	global_load_lds_dwordx4 v[220:221], off
	v_lshl_add_u64 v[220:221], s[68:69], 0, v[132:133]
	s_add_i32 m0, s0, 0x2000
	s_nop 0
	global_load_lds_dwordx4 v[220:221], off
	v_lshl_add_u64 v[220:221], s[34:35], 0, v[138:139]
	s_mov_b32 m0, s33
	s_nop 0
	global_load_lds_dwordx4 v[220:221], off
	s_mov_b32 m0, s40
	s_nop 0
	global_load_lds_dwordx4 v[222:223], off
	s_waitcnt vmcnt(8)
	s_waitcnt lgkmcnt(0)
	s_setprio 1
	s_barrier
	v_mfma_f32_16x16x32_bf16 v[64:67], v[144:147], v[182:185], v[64:67]
	v_mfma_f32_16x16x32_bf16 v[60:63], v[152:155], v[182:185], v[60:63]
	v_mfma_f32_16x16x32_bf16 v[48:51], v[144:147], v[190:193], v[48:51]
	v_mfma_f32_16x16x32_bf16 v[44:47], v[152:155], v[190:193], v[44:47]
	v_mfma_f32_16x16x32_bf16 v[32:35], v[144:147], v[204:207], v[32:35]
	v_mfma_f32_16x16x32_bf16 v[28:31], v[152:155], v[204:207], v[28:31]
	v_mfma_f32_16x16x32_bf16 v[16:19], v[144:147], v[212:215], v[16:19]
	v_mfma_f32_16x16x32_bf16 v[12:15], v[152:155], v[212:215], v[12:15]
	v_mfma_f32_16x16x32_bf16 v[64:67], v[148:151], v[186:189], v[64:67]
	v_mfma_f32_16x16x32_bf16 v[60:63], v[162:165], v[186:189], v[60:63]
	v_mfma_f32_16x16x32_bf16 v[48:51], v[148:151], v[200:203], v[48:51]
	v_mfma_f32_16x16x32_bf16 v[44:47], v[162:165], v[200:203], v[44:47]
	v_mfma_f32_16x16x32_bf16 v[32:35], v[148:151], v[208:211], v[32:35]
	v_mfma_f32_16x16x32_bf16 v[28:31], v[162:165], v[208:211], v[28:31]
	v_mfma_f32_16x16x32_bf16 v[16:19], v[148:151], v[216:219], v[16:19]
	v_mfma_f32_16x16x32_bf16 v[12:15], v[162:165], v[216:219], v[12:15]
	s_setprio 0
	s_setprio 1
	v_mfma_f32_16x16x32_bf16 v[56:59], v[166:169], v[182:185], v[56:59]
	v_mfma_f32_16x16x32_bf16 v[52:55], v[174:177], v[182:185], v[52:55]
	v_mfma_f32_16x16x32_bf16 v[40:43], v[166:169], v[190:193], v[40:43]
	v_mfma_f32_16x16x32_bf16 v[36:39], v[174:177], v[190:193], v[36:39]
	v_mfma_f32_16x16x32_bf16 v[24:27], v[166:169], v[204:207], v[24:27]
	v_mfma_f32_16x16x32_bf16 v[20:23], v[174:177], v[204:207], v[20:23]
	v_mfma_f32_16x16x32_bf16 v[8:11], v[166:169], v[212:215], v[8:11]
	v_mfma_f32_16x16x32_bf16 v[4:7], v[174:177], v[212:215], v[4:7]
	v_mfma_f32_16x16x32_bf16 v[56:59], v[170:173], v[186:189], v[56:59]
	v_mfma_f32_16x16x32_bf16 v[52:55], v[178:181], v[186:189], v[52:55]
	v_mfma_f32_16x16x32_bf16 v[40:43], v[170:173], v[200:203], v[40:43]
	v_mfma_f32_16x16x32_bf16 v[36:39], v[178:181], v[200:203], v[36:39]
	v_mfma_f32_16x16x32_bf16 v[24:27], v[170:173], v[208:211], v[24:27]
	v_mfma_f32_16x16x32_bf16 v[20:23], v[178:181], v[208:211], v[20:23]
	v_mfma_f32_16x16x32_bf16 v[8:11], v[170:173], v[216:219], v[8:11]
	v_mfma_f32_16x16x32_bf16 v[4:7], v[178:181], v[216:219], v[4:7]
	s_barrier
	s_setprio 0
	s_add_i32 s0, 0, 0x18000
	v_add_u32_e32 v156, s0, v157
	s_add_i32 s6, 0, 0x1c000
	ds_read_b128 v[144:147], v156
	ds_read_b128 v[148:151], v156 offset:1024
	ds_read_b128 v[152:155], v156 offset:2048
	ds_read_b128 v[162:165], v156 offset:3072
	v_add_u32_e32 v156, s6, v157
	ds_read_b128 v[166:169], v156
	ds_read_b128 v[170:173], v156 offset:1024
	ds_read_b128 v[174:177], v156 offset:2048
	ds_read_b128 v[178:181], v156 offset:3072
	s_add_u32 s34, s34, 0x80000
	s_addc_u32 s35, s35, 0
	s_mov_b32 m0, s50
	v_lshl_add_u64 v[224:225], s[34:35], 0, v[138:139]
	ds_read_b128 v[182:185], v161 offset:32768
	ds_read_b128 v[186:189], v161 offset:33792
	ds_read_b128 v[190:193], v161 offset:34816
	ds_read_b128 v[200:203], v161 offset:35840
	ds_read_b128 v[204:207], v161 offset:36864
	ds_read_b128 v[208:211], v161 offset:37888
	ds_read_b128 v[212:215], v161 offset:38912
	ds_read_b128 v[216:219], v161 offset:39936
	global_load_lds_dwordx4 v[224:225], off
	v_lshl_add_u64 v[224:225], s[34:35], 0, v[134:135]
	s_mov_b32 m0, s51
	s_nop 0
	global_load_lds_dwordx4 v[224:225], off
	s_waitcnt vmcnt(8)
	s_waitcnt lgkmcnt(0)
	s_setprio 1
	s_barrier
	v_mfma_f32_16x16x32_bf16 v[128:131], v[144:147], v[182:185], v[128:131]
	v_mfma_f32_16x16x32_bf16 v[124:127], v[152:155], v[182:185], v[124:127]
	v_mfma_f32_16x16x32_bf16 v[112:115], v[144:147], v[190:193], v[112:115]
	v_mfma_f32_16x16x32_bf16 v[108:111], v[152:155], v[190:193], v[108:111]
	v_mfma_f32_16x16x32_bf16 v[96:99], v[144:147], v[204:207], v[96:99]
	v_mfma_f32_16x16x32_bf16 v[92:95], v[152:155], v[204:207], v[92:95]
	v_mfma_f32_16x16x32_bf16 v[80:83], v[144:147], v[212:215], v[80:83]
	v_mfma_f32_16x16x32_bf16 v[76:79], v[152:155], v[212:215], v[76:79]
	v_mfma_f32_16x16x32_bf16 v[128:131], v[148:151], v[186:189], v[128:131]
	v_mfma_f32_16x16x32_bf16 v[124:127], v[162:165], v[186:189], v[124:127]
	v_mfma_f32_16x16x32_bf16 v[112:115], v[148:151], v[200:203], v[112:115]
	v_mfma_f32_16x16x32_bf16 v[108:111], v[162:165], v[200:203], v[108:111]
	v_mfma_f32_16x16x32_bf16 v[96:99], v[148:151], v[208:211], v[96:99]
	v_mfma_f32_16x16x32_bf16 v[92:95], v[162:165], v[208:211], v[92:95]
	v_mfma_f32_16x16x32_bf16 v[80:83], v[148:151], v[216:219], v[80:83]
	v_mfma_f32_16x16x32_bf16 v[76:79], v[162:165], v[216:219], v[76:79]
	s_setprio 0
	s_setprio 1
	v_mfma_f32_16x16x32_bf16 v[120:123], v[166:169], v[182:185], v[120:123]
	v_mfma_f32_16x16x32_bf16 v[116:119], v[174:177], v[182:185], v[116:119]
	v_mfma_f32_16x16x32_bf16 v[104:107], v[166:169], v[190:193], v[104:107]
	v_mfma_f32_16x16x32_bf16 v[100:103], v[174:177], v[190:193], v[100:103]
	v_mfma_f32_16x16x32_bf16 v[88:91], v[166:169], v[204:207], v[88:91]
	v_mfma_f32_16x16x32_bf16 v[84:87], v[174:177], v[204:207], v[84:87]
	v_mfma_f32_16x16x32_bf16 v[72:75], v[166:169], v[212:215], v[72:75]
	v_mfma_f32_16x16x32_bf16 v[68:71], v[174:177], v[212:215], v[68:71]
	v_mfma_f32_16x16x32_bf16 v[120:123], v[170:173], v[186:189], v[120:123]
	v_mfma_f32_16x16x32_bf16 v[116:119], v[178:181], v[186:189], v[116:119]
	v_mfma_f32_16x16x32_bf16 v[104:107], v[170:173], v[200:203], v[104:107]
	v_mfma_f32_16x16x32_bf16 v[100:103], v[178:181], v[200:203], v[100:103]
	v_mfma_f32_16x16x32_bf16 v[88:91], v[170:173], v[208:211], v[88:91]
	v_mfma_f32_16x16x32_bf16 v[84:87], v[178:181], v[208:211], v[84:87]
	v_mfma_f32_16x16x32_bf16 v[72:75], v[170:173], v[216:219], v[72:75]
	v_mfma_f32_16x16x32_bf16 v[68:71], v[178:181], v[216:219], v[68:71]
	s_barrier
	s_setprio 0
	s_add_i32 s0, s0, s25
	v_lshl_add_u64 v[194:195], v[194:195], 0, s[90:91]
	s_mov_b32 m0, s0
	ds_read_b128 v[182:185], v161 offset:49152
	ds_read_b128 v[186:189], v161 offset:50176
	ds_read_b128 v[190:193], v161 offset:51200
	ds_read_b128 v[200:203], v161 offset:52224
	ds_read_b128 v[204:207], v161 offset:53248
	ds_read_b128 v[208:211], v161 offset:54272
	ds_read_b128 v[212:215], v161 offset:55296
	ds_read_b128 v[216:219], v161 offset:56320
	global_load_lds_dwordx4 v[194:195], off
	s_add_i32 m0, s0, 0x2000
	s_add_u32 s30, s30, 0x80080
	v_lshl_add_u64 v[194:195], v[198:199], 0, s[90:91]
	s_addc_u32 s31, s31, 0
	s_add_i32 s0, s6, s25
	global_load_lds_dwordx4 v[194:195], off
	v_lshl_add_u64 v[194:195], s[30:31], 0, v[136:137]
	s_mov_b32 m0, s0
	s_nop 0
	global_load_lds_dwordx4 v[194:195], off
	v_lshl_add_u64 v[194:195], s[30:31], 0, v[132:133]
	s_add_i32 m0, s0, 0x2000
	s_nop 0
	global_load_lds_dwordx4 v[194:195], off
	v_lshl_add_u64 v[194:195], v[220:221], 0, s[90:91]
	s_mov_b32 m0, s55
	s_nop 0
	global_load_lds_dwordx4 v[194:195], off
	v_lshl_add_u64 v[194:195], v[222:223], 0, s[90:91]
	s_mov_b32 m0, s60
	s_nop 0
	global_load_lds_dwordx4 v[194:195], off
	s_nop 0
	s_waitcnt vmcnt(8)
	s_waitcnt lgkmcnt(0)
	s_setprio 1
	s_barrier
	v_mfma_f32_16x16x32_bf16 v[64:67], v[144:147], v[182:185], v[64:67]
	v_mfma_f32_16x16x32_bf16 v[60:63], v[152:155], v[182:185], v[60:63]
	v_mfma_f32_16x16x32_bf16 v[48:51], v[144:147], v[190:193], v[48:51]
	v_mfma_f32_16x16x32_bf16 v[44:47], v[152:155], v[190:193], v[44:47]
	v_mfma_f32_16x16x32_bf16 v[32:35], v[144:147], v[204:207], v[32:35]
	v_mfma_f32_16x16x32_bf16 v[28:31], v[152:155], v[204:207], v[28:31]
	v_mfma_f32_16x16x32_bf16 v[16:19], v[144:147], v[212:215], v[16:19]
	v_mfma_f32_16x16x32_bf16 v[12:15], v[152:155], v[212:215], v[12:15]
	v_mfma_f32_16x16x32_bf16 v[64:67], v[148:151], v[186:189], v[64:67]
	v_mfma_f32_16x16x32_bf16 v[60:63], v[162:165], v[186:189], v[60:63]
	v_mfma_f32_16x16x32_bf16 v[48:51], v[148:151], v[200:203], v[48:51]
	v_mfma_f32_16x16x32_bf16 v[44:47], v[162:165], v[200:203], v[44:47]
	v_mfma_f32_16x16x32_bf16 v[32:35], v[148:151], v[208:211], v[32:35]
	v_mfma_f32_16x16x32_bf16 v[28:31], v[162:165], v[208:211], v[28:31]
	v_mfma_f32_16x16x32_bf16 v[16:19], v[148:151], v[216:219], v[16:19]
	v_mfma_f32_16x16x32_bf16 v[12:15], v[162:165], v[216:219], v[12:15]
	s_setprio 0
	s_setprio 1
	v_mfma_f32_16x16x32_bf16 v[56:59], v[166:169], v[182:185], v[56:59]
	v_mfma_f32_16x16x32_bf16 v[52:55], v[174:177], v[182:185], v[52:55]
	v_mfma_f32_16x16x32_bf16 v[40:43], v[166:169], v[190:193], v[40:43]
	v_mfma_f32_16x16x32_bf16 v[36:39], v[174:177], v[190:193], v[36:39]
	v_mfma_f32_16x16x32_bf16 v[24:27], v[166:169], v[204:207], v[24:27]
	v_mfma_f32_16x16x32_bf16 v[20:23], v[174:177], v[204:207], v[20:23]
	v_mfma_f32_16x16x32_bf16 v[8:11], v[166:169], v[212:215], v[8:11]
	v_mfma_f32_16x16x32_bf16 v[4:7], v[174:177], v[212:215], v[4:7]
	v_mfma_f32_16x16x32_bf16 v[56:59], v[170:173], v[186:189], v[56:59]
	v_mfma_f32_16x16x32_bf16 v[52:55], v[178:181], v[186:189], v[52:55]
	v_mfma_f32_16x16x32_bf16 v[40:43], v[170:173], v[200:203], v[40:43]
	v_mfma_f32_16x16x32_bf16 v[36:39], v[178:181], v[200:203], v[36:39]
	v_mfma_f32_16x16x32_bf16 v[24:27], v[170:173], v[208:211], v[24:27]
	v_mfma_f32_16x16x32_bf16 v[20:23], v[178:181], v[208:211], v[20:23]
	v_mfma_f32_16x16x32_bf16 v[8:11], v[170:173], v[216:219], v[8:11]
	v_mfma_f32_16x16x32_bf16 v[4:7], v[178:181], v[216:219], v[4:7]
	s_barrier
	s_setprio 0
	s_add_i32 s66, s66, 2
	s_add_u32 s36, s36, 0x100
	s_addc_u32 s37, s37, 0
	s_add_u32 s38, s38, 0x100
	s_addc_u32 s39, s39, 0
	s_cmp_gt_u32 s66, 29
	s_cbranch_scc0 .LBB0_1137
	s_and_b64 vcc, exec, s[20:21]
	s_cbranch_vccz .LBB0_1140
	s_barrier

.LBB0_1167:
	s_add_u32 s0, s36, 0xfff80080
	s_addc_u32 s6, s37, -1
	s_add_i32 s49, 0, 0x10000
	s_cmp_eq_u32 s67, 28
	s_cselect_b32 s35, s43, s6
	s_cselect_b32 s34, s65, s0
	v_add_u32_e32 v156, s49, v157
	s_cselect_b32 s31, s29, s39
	s_cselect_b32 s30, s66, s38
	s_add_i32 s0, 0, 0x14000
	ds_read_b128 v[144:147], v156
	ds_read_b128 v[148:151], v156 offset:1024
	ds_read_b128 v[152:155], v156 offset:2048
	ds_read_b128 v[162:165], v156 offset:3072
	v_add_u32_e32 v156, s0, v157
	ds_read_b128 v[166:169], v156
	ds_read_b128 v[170:173], v156 offset:1024
	ds_read_b128 v[174:177], v156 offset:2048
	ds_read_b128 v[178:181], v156 offset:3072
	v_lshl_add_u64 v[194:195], s[36:37], 0, v[140:141]
	s_add_i32 m0, s25, 0xc000
	ds_read_b128 v[182:185], v161
	ds_read_b128 v[186:189], v161 offset:1024
	ds_read_b128 v[190:193], v161 offset:2048
	ds_read_b128 v[200:203], v161 offset:3072
	ds_read_b128 v[204:207], v161 offset:4096
	ds_read_b128 v[208:211], v161 offset:5120
	ds_read_b128 v[212:215], v161 offset:6144
	ds_read_b128 v[216:219], v161 offset:7168
	global_load_lds_dwordx4 v[194:195], off
	v_lshl_add_u64 v[194:195], s[36:37], 0, v[142:143]
	s_add_i32 m0, s25, 0xe000
	s_nop 0
	global_load_lds_dwordx4 v[194:195], off
	s_nop 0
	s_waitcnt vmcnt(8)
	s_waitcnt lgkmcnt(0)
	s_setprio 1
	s_barrier
	v_mfma_f32_16x16x32_bf16 v[128:131], v[144:147], v[182:185], v[128:131]
	v_mfma_f32_16x16x32_bf16 v[124:127], v[152:155], v[182:185], v[124:127]
	v_mfma_f32_16x16x32_bf16 v[112:115], v[144:147], v[190:193], v[112:115]
	v_mfma_f32_16x16x32_bf16 v[108:111], v[152:155], v[190:193], v[108:111]
	v_mfma_f32_16x16x32_bf16 v[96:99], v[144:147], v[204:207], v[96:99]
	v_mfma_f32_16x16x32_bf16 v[92:95], v[152:155], v[204:207], v[92:95]
	v_mfma_f32_16x16x32_bf16 v[80:83], v[144:147], v[212:215], v[80:83]
	v_mfma_f32_16x16x32_bf16 v[76:79], v[152:155], v[212:215], v[76:79]
	v_mfma_f32_16x16x32_bf16 v[128:131], v[148:151], v[186:189], v[128:131]
	v_mfma_f32_16x16x32_bf16 v[124:127], v[162:165], v[186:189], v[124:127]
	v_mfma_f32_16x16x32_bf16 v[112:115], v[148:151], v[200:203], v[112:115]
	v_mfma_f32_16x16x32_bf16 v[108:111], v[162:165], v[200:203], v[108:111]
	v_mfma_f32_16x16x32_bf16 v[96:99], v[148:151], v[208:211], v[96:99]
	v_mfma_f32_16x16x32_bf16 v[92:95], v[162:165], v[208:211], v[92:95]
	v_mfma_f32_16x16x32_bf16 v[80:83], v[148:151], v[216:219], v[80:83]
	v_mfma_f32_16x16x32_bf16 v[76:79], v[162:165], v[216:219], v[76:79]
	s_setprio 0
	s_setprio 1
	v_mfma_f32_16x16x32_bf16 v[120:123], v[166:169], v[182:185], v[120:123]
	v_mfma_f32_16x16x32_bf16 v[116:119], v[174:177], v[182:185], v[116:119]
	v_mfma_f32_16x16x32_bf16 v[104:107], v[166:169], v[190:193], v[104:107]
	v_mfma_f32_16x16x32_bf16 v[100:103], v[174:177], v[190:193], v[100:103]
	v_mfma_f32_16x16x32_bf16 v[88:91], v[166:169], v[204:207], v[88:91]
	v_mfma_f32_16x16x32_bf16 v[84:87], v[174:177], v[204:207], v[84:87]
	v_mfma_f32_16x16x32_bf16 v[72:75], v[166:169], v[212:215], v[72:75]
	v_mfma_f32_16x16x32_bf16 v[68:71], v[174:177], v[212:215], v[68:71]
	v_mfma_f32_16x16x32_bf16 v[120:123], v[170:173], v[186:189], v[120:123]
	v_mfma_f32_16x16x32_bf16 v[116:119], v[178:181], v[186:189], v[116:119]
	v_mfma_f32_16x16x32_bf16 v[104:107], v[170:173], v[200:203], v[104:107]
	v_mfma_f32_16x16x32_bf16 v[100:103], v[178:181], v[200:203], v[100:103]
	v_mfma_f32_16x16x32_bf16 v[88:91], v[170:173], v[208:211], v[88:91]
	v_mfma_f32_16x16x32_bf16 v[84:87], v[178:181], v[208:211], v[84:87]
	v_mfma_f32_16x16x32_bf16 v[72:75], v[170:173], v[216:219], v[72:75]
	v_mfma_f32_16x16x32_bf16 v[68:71], v[178:181], v[216:219], v[68:71]
	s_barrier
	s_setprio 0
	s_add_i32 s6, s49, s1
	v_lshl_add_u64 v[194:195], s[30:31], 0, v[136:137]
	s_mov_b32 m0, s6
	ds_read_b128 v[182:185], v161 offset:16384
	ds_read_b128 v[186:189], v161 offset:17408
	ds_read_b128 v[190:193], v161 offset:18432
	ds_read_b128 v[200:203], v161 offset:19456
	ds_read_b128 v[204:207], v161 offset:20480
	ds_read_b128 v[208:211], v161 offset:21504
	ds_read_b128 v[212:215], v161 offset:22528
	ds_read_b128 v[216:219], v161 offset:23552
	global_load_lds_dwordx4 v[194:195], off
	s_add_i32 m0, s6, 0x2000
	s_add_u32 s68, s30, 0x80000
	v_lshl_add_u64 v[198:199], s[30:31], 0, v[132:133]
	s_addc_u32 s69, s31, 0
	s_add_i32 s0, s0, s1
	global_load_lds_dwordx4 v[198:199], off
	v_lshl_add_u64 v[220:221], s[68:69], 0, v[136:137]
	s_mov_b32 m0, s0
	v_lshl_add_u64 v[222:223], s[34:35], 0, v[134:135]
	global_load_lds_dwordx4 v[220:221], off
	v_lshl_add_u64 v[220:221], s[68:69], 0, v[132:133]
	s_add_i32 m0, s0, 0x2000
	s_nop 0
	global_load_lds_dwordx4 v[220:221], off
	v_lshl_add_u64 v[220:221], s[34:35], 0, v[138:139]
	s_mov_b32 m0, s25
	s_nop 0
	global_load_lds_dwordx4 v[220:221], off
	s_mov_b32 m0, s33
	s_nop 0
	global_load_lds_dwordx4 v[222:223], off
	s_waitcnt vmcnt(8)
	s_waitcnt lgkmcnt(0)
	s_setprio 1
	s_barrier
	v_mfma_f32_16x16x32_bf16 v[64:67], v[144:147], v[182:185], v[64:67]
	v_mfma_f32_16x16x32_bf16 v[60:63], v[152:155], v[182:185], v[60:63]
	v_mfma_f32_16x16x32_bf16 v[48:51], v[144:147], v[190:193], v[48:51]
	v_mfma_f32_16x16x32_bf16 v[44:47], v[152:155], v[190:193], v[44:47]
	v_mfma_f32_16x16x32_bf16 v[32:35], v[144:147], v[204:207], v[32:35]
	v_mfma_f32_16x16x32_bf16 v[28:31], v[152:155], v[204:207], v[28:31]
	v_mfma_f32_16x16x32_bf16 v[16:19], v[144:147], v[212:215], v[16:19]
	v_mfma_f32_16x16x32_bf16 v[12:15], v[152:155], v[212:215], v[12:15]
	v_mfma_f32_16x16x32_bf16 v[64:67], v[148:151], v[186:189], v[64:67]
	v_mfma_f32_16x16x32_bf16 v[60:63], v[162:165], v[186:189], v[60:63]
	v_mfma_f32_16x16x32_bf16 v[48:51], v[148:151], v[200:203], v[48:51]
	v_mfma_f32_16x16x32_bf16 v[44:47], v[162:165], v[200:203], v[44:47]
	v_mfma_f32_16x16x32_bf16 v[32:35], v[148:151], v[208:211], v[32:35]
	v_mfma_f32_16x16x32_bf16 v[28:31], v[162:165], v[208:211], v[28:31]
	v_mfma_f32_16x16x32_bf16 v[16:19], v[148:151], v[216:219], v[16:19]
	v_mfma_f32_16x16x32_bf16 v[12:15], v[162:165], v[216:219], v[12:15]
	s_setprio 0
	s_setprio 1
	v_mfma_f32_16x16x32_bf16 v[56:59], v[166:169], v[182:185], v[56:59]
	v_mfma_f32_16x16x32_bf16 v[52:55], v[174:177], v[182:185], v[52:55]
	v_mfma_f32_16x16x32_bf16 v[40:43], v[166:169], v[190:193], v[40:43]
	v_mfma_f32_16x16x32_bf16 v[36:39], v[174:177], v[190:193], v[36:39]
	v_mfma_f32_16x16x32_bf16 v[24:27], v[166:169], v[204:207], v[24:27]
	v_mfma_f32_16x16x32_bf16 v[20:23], v[174:177], v[204:207], v[20:23]
	v_mfma_f32_16x16x32_bf16 v[8:11], v[166:169], v[212:215], v[8:11]
	v_mfma_f32_16x16x32_bf16 v[4:7], v[174:177], v[212:215], v[4:7]
	v_mfma_f32_16x16x32_bf16 v[56:59], v[170:173], v[186:189], v[56:59]
	v_mfma_f32_16x16x32_bf16 v[52:55], v[178:181], v[186:189], v[52:55]
	v_mfma_f32_16x16x32_bf16 v[40:43], v[170:173], v[200:203], v[40:43]
	v_mfma_f32_16x16x32_bf16 v[36:39], v[178:181], v[200:203], v[36:39]
	v_mfma_f32_16x16x32_bf16 v[24:27], v[170:173], v[208:211], v[24:27]
	v_mfma_f32_16x16x32_bf16 v[20:23], v[178:181], v[208:211], v[20:23]
	v_mfma_f32_16x16x32_bf16 v[8:11], v[170:173], v[216:219], v[8:11]
	v_mfma_f32_16x16x32_bf16 v[4:7], v[178:181], v[216:219], v[4:7]
	s_barrier
	s_setprio 0
	s_add_i32 s0, 0, 0x18000
	v_add_u32_e32 v156, s0, v157
	s_add_i32 s6, 0, 0x1c000
	ds_read_b128 v[144:147], v156
	ds_read_b128 v[148:151], v156 offset:1024
	ds_read_b128 v[152:155], v156 offset:2048
	ds_read_b128 v[162:165], v156 offset:3072
	v_add_u32_e32 v156, s6, v157
	ds_read_b128 v[166:169], v156
	ds_read_b128 v[170:173], v156 offset:1024
	ds_read_b128 v[174:177], v156 offset:2048
	ds_read_b128 v[178:181], v156 offset:3072
	s_add_u32 s34, s34, 0x80000
	s_addc_u32 s35, s35, 0
	s_mov_b32 m0, s40
	v_lshl_add_u64 v[224:225], s[34:35], 0, v[138:139]
	ds_read_b128 v[182:185], v161 offset:32768
	ds_read_b128 v[186:189], v161 offset:33792
	ds_read_b128 v[190:193], v161 offset:34816
	ds_read_b128 v[200:203], v161 offset:35840
	ds_read_b128 v[204:207], v161 offset:36864
	ds_read_b128 v[208:211], v161 offset:37888
	ds_read_b128 v[212:215], v161 offset:38912
	ds_read_b128 v[216:219], v161 offset:39936
	global_load_lds_dwordx4 v[224:225], off
	v_lshl_add_u64 v[224:225], s[34:35], 0, v[134:135]
	s_mov_b32 m0, s50
	s_nop 0
	global_load_lds_dwordx4 v[224:225], off
	s_waitcnt vmcnt(8)
	s_waitcnt lgkmcnt(0)
	s_setprio 1
	s_barrier
	v_mfma_f32_16x16x32_bf16 v[128:131], v[144:147], v[182:185], v[128:131]
	v_mfma_f32_16x16x32_bf16 v[124:127], v[152:155], v[182:185], v[124:127]
	v_mfma_f32_16x16x32_bf16 v[112:115], v[144:147], v[190:193], v[112:115]
	v_mfma_f32_16x16x32_bf16 v[108:111], v[152:155], v[190:193], v[108:111]
	v_mfma_f32_16x16x32_bf16 v[96:99], v[144:147], v[204:207], v[96:99]
	v_mfma_f32_16x16x32_bf16 v[92:95], v[152:155], v[204:207], v[92:95]
	v_mfma_f32_16x16x32_bf16 v[80:83], v[144:147], v[212:215], v[80:83]
	v_mfma_f32_16x16x32_bf16 v[76:79], v[152:155], v[212:215], v[76:79]
	v_mfma_f32_16x16x32_bf16 v[128:131], v[148:151], v[186:189], v[128:131]
	v_mfma_f32_16x16x32_bf16 v[124:127], v[162:165], v[186:189], v[124:127]
	v_mfma_f32_16x16x32_bf16 v[112:115], v[148:151], v[200:203], v[112:115]
	v_mfma_f32_16x16x32_bf16 v[108:111], v[162:165], v[200:203], v[108:111]
	v_mfma_f32_16x16x32_bf16 v[96:99], v[148:151], v[208:211], v[96:99]
	v_mfma_f32_16x16x32_bf16 v[92:95], v[162:165], v[208:211], v[92:95]
	v_mfma_f32_16x16x32_bf16 v[80:83], v[148:151], v[216:219], v[80:83]
	v_mfma_f32_16x16x32_bf16 v[76:79], v[162:165], v[216:219], v[76:79]
	s_setprio 0
	s_setprio 1
	v_mfma_f32_16x16x32_bf16 v[120:123], v[166:169], v[182:185], v[120:123]
	v_mfma_f32_16x16x32_bf16 v[116:119], v[174:177], v[182:185], v[116:119]
	v_mfma_f32_16x16x32_bf16 v[104:107], v[166:169], v[190:193], v[104:107]
	v_mfma_f32_16x16x32_bf16 v[100:103], v[174:177], v[190:193], v[100:103]
	v_mfma_f32_16x16x32_bf16 v[88:91], v[166:169], v[204:207], v[88:91]
	v_mfma_f32_16x16x32_bf16 v[84:87], v[174:177], v[204:207], v[84:87]
	v_mfma_f32_16x16x32_bf16 v[72:75], v[166:169], v[212:215], v[72:75]
	v_mfma_f32_16x16x32_bf16 v[68:71], v[174:177], v[212:215], v[68:71]
	v_mfma_f32_16x16x32_bf16 v[120:123], v[170:173], v[186:189], v[120:123]
	v_mfma_f32_16x16x32_bf16 v[116:119], v[178:181], v[186:189], v[116:119]
	v_mfma_f32_16x16x32_bf16 v[104:107], v[170:173], v[200:203], v[104:107]
	v_mfma_f32_16x16x32_bf16 v[100:103], v[178:181], v[200:203], v[100:103]
	v_mfma_f32_16x16x32_bf16 v[88:91], v[170:173], v[208:211], v[88:91]
	v_mfma_f32_16x16x32_bf16 v[84:87], v[178:181], v[208:211], v[84:87]
	v_mfma_f32_16x16x32_bf16 v[72:75], v[170:173], v[216:219], v[72:75]
	v_mfma_f32_16x16x32_bf16 v[68:71], v[178:181], v[216:219], v[68:71]
	s_barrier
	s_setprio 0
	s_add_i32 s0, s0, s1
	v_lshl_add_u64 v[194:195], v[194:195], 0, s[90:91]
	s_mov_b32 m0, s0
	ds_read_b128 v[182:185], v161 offset:49152
	ds_read_b128 v[186:189], v161 offset:50176
	ds_read_b128 v[190:193], v161 offset:51200
	ds_read_b128 v[200:203], v161 offset:52224
	ds_read_b128 v[204:207], v161 offset:53248
	ds_read_b128 v[208:211], v161 offset:54272
	ds_read_b128 v[212:215], v161 offset:55296
	ds_read_b128 v[216:219], v161 offset:56320
	global_load_lds_dwordx4 v[194:195], off
	s_add_i32 m0, s0, 0x2000
	s_add_u32 s30, s30, 0x80080
	v_lshl_add_u64 v[194:195], v[198:199], 0, s[90:91]
	s_addc_u32 s31, s31, 0
	s_add_i32 s0, s6, s1
	global_load_lds_dwordx4 v[194:195], off
	v_lshl_add_u64 v[194:195], s[30:31], 0, v[136:137]
	s_mov_b32 m0, s0
	s_nop 0
	global_load_lds_dwordx4 v[194:195], off
	v_lshl_add_u64 v[194:195], s[30:31], 0, v[132:133]
	s_add_i32 m0, s0, 0x2000
	s_nop 0
	global_load_lds_dwordx4 v[194:195], off
	v_lshl_add_u64 v[194:195], v[220:221], 0, s[90:91]
	s_mov_b32 m0, s51
	s_nop 0
	global_load_lds_dwordx4 v[194:195], off
	v_lshl_add_u64 v[194:195], v[222:223], 0, s[90:91]
	s_mov_b32 m0, s55
	s_nop 0
	global_load_lds_dwordx4 v[194:195], off
	s_nop 0
	s_waitcnt vmcnt(8)
	s_waitcnt lgkmcnt(0)
	s_setprio 1
	s_barrier
	v_mfma_f32_16x16x32_bf16 v[64:67], v[144:147], v[182:185], v[64:67]
	v_mfma_f32_16x16x32_bf16 v[60:63], v[152:155], v[182:185], v[60:63]
	v_mfma_f32_16x16x32_bf16 v[48:51], v[144:147], v[190:193], v[48:51]
	v_mfma_f32_16x16x32_bf16 v[44:47], v[152:155], v[190:193], v[44:47]
	v_mfma_f32_16x16x32_bf16 v[32:35], v[144:147], v[204:207], v[32:35]
	v_mfma_f32_16x16x32_bf16 v[28:31], v[152:155], v[204:207], v[28:31]
	v_mfma_f32_16x16x32_bf16 v[16:19], v[144:147], v[212:215], v[16:19]
	v_mfma_f32_16x16x32_bf16 v[12:15], v[152:155], v[212:215], v[12:15]
	v_mfma_f32_16x16x32_bf16 v[64:67], v[148:151], v[186:189], v[64:67]
	v_mfma_f32_16x16x32_bf16 v[60:63], v[162:165], v[186:189], v[60:63]
	v_mfma_f32_16x16x32_bf16 v[48:51], v[148:151], v[200:203], v[48:51]
	v_mfma_f32_16x16x32_bf16 v[44:47], v[162:165], v[200:203], v[44:47]
	v_mfma_f32_16x16x32_bf16 v[32:35], v[148:151], v[208:211], v[32:35]
	v_mfma_f32_16x16x32_bf16 v[28:31], v[162:165], v[208:211], v[28:31]
	v_mfma_f32_16x16x32_bf16 v[16:19], v[148:151], v[216:219], v[16:19]
	v_mfma_f32_16x16x32_bf16 v[12:15], v[162:165], v[216:219], v[12:15]
	s_setprio 0
	s_setprio 1
	v_mfma_f32_16x16x32_bf16 v[56:59], v[166:169], v[182:185], v[56:59]
	v_mfma_f32_16x16x32_bf16 v[52:55], v[174:177], v[182:185], v[52:55]
	v_mfma_f32_16x16x32_bf16 v[40:43], v[166:169], v[190:193], v[40:43]
	v_mfma_f32_16x16x32_bf16 v[36:39], v[174:177], v[190:193], v[36:39]
	v_mfma_f32_16x16x32_bf16 v[24:27], v[166:169], v[204:207], v[24:27]
	v_mfma_f32_16x16x32_bf16 v[20:23], v[174:177], v[204:207], v[20:23]
	v_mfma_f32_16x16x32_bf16 v[8:11], v[166:169], v[212:215], v[8:11]
	v_mfma_f32_16x16x32_bf16 v[4:7], v[174:177], v[212:215], v[4:7]
	v_mfma_f32_16x16x32_bf16 v[56:59], v[170:173], v[186:189], v[56:59]
	v_mfma_f32_16x16x32_bf16 v[52:55], v[178:181], v[186:189], v[52:55]
	v_mfma_f32_16x16x32_bf16 v[40:43], v[170:173], v[200:203], v[40:43]
	v_mfma_f32_16x16x32_bf16 v[36:39], v[178:181], v[200:203], v[36:39]
	v_mfma_f32_16x16x32_bf16 v[24:27], v[170:173], v[208:211], v[24:27]
	v_mfma_f32_16x16x32_bf16 v[20:23], v[178:181], v[208:211], v[20:23]
	v_mfma_f32_16x16x32_bf16 v[8:11], v[170:173], v[216:219], v[8:11]
	v_mfma_f32_16x16x32_bf16 v[4:7], v[178:181], v[216:219], v[4:7]
	s_barrier
	s_setprio 0
	s_add_i32 s67, s67, 2
	s_add_u32 s36, s36, 0x100
	s_addc_u32 s37, s37, 0
	s_add_u32 s38, s38, 0x100
	s_addc_u32 s39, s39, 0
	s_cmp_gt_u32 s67, 29
	s_cbranch_scc0 .LBB0_1167
	s_and_b64 vcc, exec, s[20:21]
	s_cbranch_vccz .LBB0_1170
	s_barrier

.LBB0_1186:
	s_add_u32 s0, s64, s30
	s_addc_u32 s6, s65, 0
	s_add_u32 s31, s0, 0x100
	s_addc_u32 s38, s6, 0
	s_and_b64 s[34:35], s[36:37], exec
	s_cselect_b32 s69, s29, s38
	s_cselect_b32 s68, s77, s31
	s_add_u32 s30, s62, s30
	s_addc_u32 s31, s63, 0
	s_add_u32 s34, s30, 0x100
	s_addc_u32 s35, s31, 0
	s_add_i32 s82, 0, 0x10000
	s_and_b64 s[30:31], s[36:37], exec
	s_cselect_b32 s53, s23, s35
	s_cselect_b32 s52, s78, s34
	s_add_i32 s37, 0, 0x14000
	s_add_u32 s34, s0, 0x10080
	s_addc_u32 s35, s6, 0
	s_add_i32 s84, s82, s4
	s_add_i32 m0, s46, 0xc000
	s_add_i32 s85, s46, 0xe000
	s_add_i32 s6, s84, 0x2000
	v_add_u32_e32 v140, s82, v142
	s_add_u32 s30, s52, 0x10000
	ds_read_b128 v[146:149], v140
	ds_read_b128 v[150:153], v140 offset:1024
	ds_read_b128 v[154:157], v140 offset:2048
	ds_read_b128 v[158:161], v140 offset:3072
	v_add_u32_e32 v140, s37, v142
	s_addc_u32 s31, s53, 0
	s_add_i32 s49, s37, s4
	ds_read_b128 v[162:165], v140
	ds_read_b128 v[166:169], v140 offset:1024
	ds_read_b128 v[170:173], v140 offset:2048
	ds_read_b128 v[174:177], v140 offset:3072
	s_add_i32 s81, s49, 0x2000
	s_add_i32 s54, 0, 0x18000
	s_add_i32 s73, 0, 0x1c000
	s_add_u32 s38, s68, 0x10000
	s_addc_u32 s39, s69, 0
	s_add_i32 s0, s54, s4
	s_add_i32 s80, s0, 0x2000
	s_add_u32 s36, s52, 0x10080
	s_addc_u32 s37, s53, 0
	s_add_i32 s83, s73, s4
	s_add_i32 s82, s83, 0x2000
	v_lshl_add_u64 v[140:141], s[34:35], 0, v[138:139]
	ds_read_b128 v[178:181], v144
	ds_read_b128 v[182:185], v144 offset:1024
	ds_read_b128 v[186:189], v144 offset:2048
	ds_read_b128 v[190:193], v144 offset:3072
	ds_read_b128 v[200:203], v144 offset:4096
	ds_read_b128 v[204:207], v144 offset:5120
	ds_read_b128 v[208:211], v144 offset:6144
	ds_read_b128 v[212:215], v144 offset:7168
	global_load_lds_dwordx4 v[140:141], off
	v_lshl_add_u64 v[140:141], s[34:35], 0, v[134:135]
	s_mov_b32 m0, s85
	s_nop 0
	global_load_lds_dwordx4 v[140:141], off
	s_waitcnt vmcnt(8)
	s_waitcnt lgkmcnt(0)
	s_setprio 1
	s_barrier
	v_mfma_f32_16x16x32_bf16 v[128:131], v[146:149], v[178:181], v[128:131]
	v_mfma_f32_16x16x32_bf16 v[124:127], v[154:157], v[178:181], v[124:127]
	v_mfma_f32_16x16x32_bf16 v[120:123], v[146:149], v[186:189], v[120:123]
	v_mfma_f32_16x16x32_bf16 v[112:115], v[154:157], v[186:189], v[112:115]
	v_mfma_f32_16x16x32_bf16 v[104:107], v[146:149], v[200:203], v[104:107]
	v_mfma_f32_16x16x32_bf16 v[96:99], v[154:157], v[200:203], v[96:99]
	v_mfma_f32_16x16x32_bf16 v[88:91], v[146:149], v[208:211], v[88:91]
	v_mfma_f32_16x16x32_bf16 v[80:83], v[154:157], v[208:211], v[80:83]
	v_mfma_f32_16x16x32_bf16 v[128:131], v[150:153], v[182:185], v[128:131]
	v_mfma_f32_16x16x32_bf16 v[124:127], v[158:161], v[182:185], v[124:127]
	v_mfma_f32_16x16x32_bf16 v[120:123], v[150:153], v[190:193], v[120:123]
	v_mfma_f32_16x16x32_bf16 v[112:115], v[158:161], v[190:193], v[112:115]
	v_mfma_f32_16x16x32_bf16 v[104:107], v[150:153], v[204:207], v[104:107]
	v_mfma_f32_16x16x32_bf16 v[96:99], v[158:161], v[204:207], v[96:99]
	v_mfma_f32_16x16x32_bf16 v[88:91], v[150:153], v[212:215], v[88:91]
	v_mfma_f32_16x16x32_bf16 v[80:83], v[158:161], v[212:215], v[80:83]
	s_setprio 0
	s_setprio 1
	v_mfma_f32_16x16x32_bf16 v[116:119], v[162:165], v[178:181], v[116:119]
	v_mfma_f32_16x16x32_bf16 v[108:111], v[170:173], v[178:181], v[108:111]
	v_mfma_f32_16x16x32_bf16 v[100:103], v[162:165], v[186:189], v[100:103]
	v_mfma_f32_16x16x32_bf16 v[92:95], v[170:173], v[186:189], v[92:95]
	v_mfma_f32_16x16x32_bf16 v[84:87], v[162:165], v[200:203], v[84:87]
	v_mfma_f32_16x16x32_bf16 v[76:79], v[170:173], v[200:203], v[76:79]
	v_mfma_f32_16x16x32_bf16 v[72:75], v[162:165], v[208:211], v[72:75]
	v_mfma_f32_16x16x32_bf16 v[68:71], v[170:173], v[208:211], v[68:71]
	v_mfma_f32_16x16x32_bf16 v[116:119], v[166:169], v[182:185], v[116:119]
	v_mfma_f32_16x16x32_bf16 v[108:111], v[174:177], v[182:185], v[108:111]
	v_mfma_f32_16x16x32_bf16 v[100:103], v[166:169], v[190:193], v[100:103]
	v_mfma_f32_16x16x32_bf16 v[92:95], v[174:177], v[190:193], v[92:95]
	v_mfma_f32_16x16x32_bf16 v[84:87], v[166:169], v[204:207], v[84:87]
	v_mfma_f32_16x16x32_bf16 v[76:79], v[174:177], v[204:207], v[76:79]
	v_mfma_f32_16x16x32_bf16 v[72:75], v[166:169], v[212:215], v[72:75]
	v_mfma_f32_16x16x32_bf16 v[68:71], v[174:177], v[212:215], v[68:71]
	s_barrier
	s_setprio 0
	s_mov_b32 m0, s84
	v_lshl_add_u64 v[140:141], s[52:53], 0, v[136:137]
	ds_read_b128 v[178:181], v144 offset:16384
	ds_read_b128 v[182:185], v144 offset:17408
	ds_read_b128 v[186:189], v144 offset:18432
	ds_read_b128 v[190:193], v144 offset:19456
	ds_read_b128 v[200:203], v144 offset:20480
	ds_read_b128 v[204:207], v144 offset:21504
	ds_read_b128 v[208:211], v144 offset:22528
	ds_read_b128 v[212:215], v144 offset:23552
	global_load_lds_dwordx4 v[140:141], off
	v_lshl_add_u64 v[194:195], s[52:53], 0, v[132:133]
	s_mov_b32 m0, s6
	v_lshl_add_u64 v[198:199], s[30:31], 0, v[136:137]
	global_load_lds_dwordx4 v[194:195], off
	s_mov_b32 m0, s49
	v_lshl_add_u64 v[216:217], s[68:69], 0, v[134:135]
	global_load_lds_dwordx4 v[198:199], off
	v_lshl_add_u64 v[198:199], s[30:31], 0, v[132:133]
	s_mov_b32 m0, s81
	s_nop 0
	global_load_lds_dwordx4 v[198:199], off
	v_lshl_add_u64 v[198:199], s[68:69], 0, v[138:139]
	s_mov_b32 m0, s46
	s_nop 0
	global_load_lds_dwordx4 v[198:199], off
	s_mov_b32 m0, s47
	s_nop 0
	global_load_lds_dwordx4 v[216:217], off
	s_nop 0
	s_waitcnt vmcnt(8)
	s_waitcnt lgkmcnt(0)
	s_setprio 1
	s_barrier
	v_mfma_f32_16x16x32_bf16 v[64:67], v[146:149], v[178:181], v[64:67]
	v_mfma_f32_16x16x32_bf16 v[60:63], v[154:157], v[178:181], v[60:63]
	v_mfma_f32_16x16x32_bf16 v[56:59], v[146:149], v[186:189], v[56:59]
	v_mfma_f32_16x16x32_bf16 v[48:51], v[154:157], v[186:189], v[48:51]
	v_mfma_f32_16x16x32_bf16 v[40:43], v[146:149], v[200:203], v[40:43]
	v_mfma_f32_16x16x32_bf16 v[32:35], v[154:157], v[200:203], v[32:35]
	v_mfma_f32_16x16x32_bf16 v[24:27], v[146:149], v[208:211], v[24:27]
	v_mfma_f32_16x16x32_bf16 v[16:19], v[154:157], v[208:211], v[16:19]
	v_mfma_f32_16x16x32_bf16 v[64:67], v[150:153], v[182:185], v[64:67]
	v_mfma_f32_16x16x32_bf16 v[60:63], v[158:161], v[182:185], v[60:63]
	v_mfma_f32_16x16x32_bf16 v[56:59], v[150:153], v[190:193], v[56:59]
	v_mfma_f32_16x16x32_bf16 v[48:51], v[158:161], v[190:193], v[48:51]
	v_mfma_f32_16x16x32_bf16 v[40:43], v[150:153], v[204:207], v[40:43]
	v_mfma_f32_16x16x32_bf16 v[32:35], v[158:161], v[204:207], v[32:35]
	v_mfma_f32_16x16x32_bf16 v[24:27], v[150:153], v[212:215], v[24:27]
	v_mfma_f32_16x16x32_bf16 v[16:19], v[158:161], v[212:215], v[16:19]
	s_setprio 0
	s_setprio 1
	v_mfma_f32_16x16x32_bf16 v[52:55], v[162:165], v[178:181], v[52:55]
	v_mfma_f32_16x16x32_bf16 v[44:47], v[170:173], v[178:181], v[44:47]
	v_mfma_f32_16x16x32_bf16 v[36:39], v[162:165], v[186:189], v[36:39]
	v_mfma_f32_16x16x32_bf16 v[28:31], v[170:173], v[186:189], v[28:31]
	v_mfma_f32_16x16x32_bf16 v[20:23], v[162:165], v[200:203], v[20:23]
	v_mfma_f32_16x16x32_bf16 v[12:15], v[170:173], v[200:203], v[12:15]
	v_mfma_f32_16x16x32_bf16 v[8:11], v[162:165], v[208:211], v[8:11]
	v_mfma_f32_16x16x32_bf16 v[4:7], v[170:173], v[208:211], v[4:7]
	v_mfma_f32_16x16x32_bf16 v[52:55], v[166:169], v[182:185], v[52:55]
	v_mfma_f32_16x16x32_bf16 v[44:47], v[174:177], v[182:185], v[44:47]
	v_mfma_f32_16x16x32_bf16 v[36:39], v[166:169], v[190:193], v[36:39]
	v_mfma_f32_16x16x32_bf16 v[28:31], v[174:177], v[190:193], v[28:31]
	v_mfma_f32_16x16x32_bf16 v[20:23], v[166:169], v[204:207], v[20:23]
	v_mfma_f32_16x16x32_bf16 v[12:15], v[174:177], v[204:207], v[12:15]
	v_mfma_f32_16x16x32_bf16 v[8:11], v[166:169], v[212:215], v[8:11]
	v_mfma_f32_16x16x32_bf16 v[4:7], v[174:177], v[212:215], v[4:7]
	s_barrier
	s_setprio 0
	v_add_u32_e32 v145, s54, v142
	ds_read_b128 v[146:149], v145
	ds_read_b128 v[150:153], v145 offset:1024
	ds_read_b128 v[154:157], v145 offset:2048
	ds_read_b128 v[158:161], v145 offset:3072
	v_add_u32_e32 v145, s73, v142
	ds_read_b128 v[162:165], v145
	ds_read_b128 v[166:169], v145 offset:1024
	ds_read_b128 v[170:173], v145 offset:2048
	ds_read_b128 v[174:177], v145 offset:3072
	s_mov_b32 m0, s50
	v_lshl_add_u64 v[218:219], s[38:39], 0, v[138:139]
	ds_read_b128 v[178:181], v144 offset:32768
	ds_read_b128 v[182:185], v144 offset:33792
	ds_read_b128 v[186:189], v144 offset:34816
	ds_read_b128 v[190:193], v144 offset:35840
	ds_read_b128 v[200:203], v144 offset:36864
	ds_read_b128 v[204:207], v144 offset:37888
	ds_read_b128 v[208:211], v144 offset:38912
	ds_read_b128 v[212:215], v144 offset:39936
	global_load_lds_dwordx4 v[218:219], off
	v_lshl_add_u64 v[218:219], s[38:39], 0, v[134:135]
	s_mov_b32 m0, s51
	s_nop 0
	global_load_lds_dwordx4 v[218:219], off
	s_nop 0
	s_waitcnt vmcnt(8)
	s_waitcnt lgkmcnt(0)
	s_setprio 1
	s_barrier
	v_mfma_f32_16x16x32_bf16 v[128:131], v[146:149], v[178:181], v[128:131]
	v_mfma_f32_16x16x32_bf16 v[124:127], v[154:157], v[178:181], v[124:127]
	v_mfma_f32_16x16x32_bf16 v[120:123], v[146:149], v[186:189], v[120:123]
	v_mfma_f32_16x16x32_bf16 v[112:115], v[154:157], v[186:189], v[112:115]
	v_mfma_f32_16x16x32_bf16 v[104:107], v[146:149], v[200:203], v[104:107]
	v_mfma_f32_16x16x32_bf16 v[96:99], v[154:157], v[200:203], v[96:99]
	v_mfma_f32_16x16x32_bf16 v[88:91], v[146:149], v[208:211], v[88:91]
	v_mfma_f32_16x16x32_bf16 v[80:83], v[154:157], v[208:211], v[80:83]
	v_mfma_f32_16x16x32_bf16 v[128:131], v[150:153], v[182:185], v[128:131]
	v_mfma_f32_16x16x32_bf16 v[124:127], v[158:161], v[182:185], v[124:127]
	v_mfma_f32_16x16x32_bf16 v[120:123], v[150:153], v[190:193], v[120:123]
	v_mfma_f32_16x16x32_bf16 v[112:115], v[158:161], v[190:193], v[112:115]
	v_mfma_f32_16x16x32_bf16 v[104:107], v[150:153], v[204:207], v[104:107]
	v_mfma_f32_16x16x32_bf16 v[96:99], v[158:161], v[204:207], v[96:99]
	v_mfma_f32_16x16x32_bf16 v[88:91], v[150:153], v[212:215], v[88:91]
	v_mfma_f32_16x16x32_bf16 v[80:83], v[158:161], v[212:215], v[80:83]
	s_setprio 0
	s_setprio 1
	v_mfma_f32_16x16x32_bf16 v[116:119], v[162:165], v[178:181], v[116:119]
	v_mfma_f32_16x16x32_bf16 v[108:111], v[170:173], v[178:181], v[108:111]
	v_mfma_f32_16x16x32_bf16 v[100:103], v[162:165], v[186:189], v[100:103]
	v_mfma_f32_16x16x32_bf16 v[92:95], v[170:173], v[186:189], v[92:95]
	v_mfma_f32_16x16x32_bf16 v[84:87], v[162:165], v[200:203], v[84:87]
	v_mfma_f32_16x16x32_bf16 v[76:79], v[170:173], v[200:203], v[76:79]
	v_mfma_f32_16x16x32_bf16 v[72:75], v[162:165], v[208:211], v[72:75]
	v_mfma_f32_16x16x32_bf16 v[68:71], v[170:173], v[208:211], v[68:71]
	v_mfma_f32_16x16x32_bf16 v[116:119], v[166:169], v[182:185], v[116:119]
	v_mfma_f32_16x16x32_bf16 v[108:111], v[174:177], v[182:185], v[108:111]
	v_mfma_f32_16x16x32_bf16 v[100:103], v[166:169], v[190:193], v[100:103]
	v_mfma_f32_16x16x32_bf16 v[92:95], v[174:177], v[190:193], v[92:95]
	v_mfma_f32_16x16x32_bf16 v[84:87], v[166:169], v[204:207], v[84:87]
	v_mfma_f32_16x16x32_bf16 v[76:79], v[174:177], v[204:207], v[76:79]
	v_mfma_f32_16x16x32_bf16 v[72:75], v[166:169], v[212:215], v[72:75]
	v_mfma_f32_16x16x32_bf16 v[68:71], v[174:177], v[212:215], v[68:71]
	s_barrier
	s_setprio 0
	s_mov_b32 m0, s0
	v_lshl_add_u64 v[140:141], v[140:141], 0, s[90:91]
	ds_read_b128 v[178:181], v144 offset:49152
	ds_read_b128 v[182:185], v144 offset:50176
	ds_read_b128 v[186:189], v144 offset:51200
	ds_read_b128 v[190:193], v144 offset:52224
	ds_read_b128 v[200:203], v144 offset:53248
	ds_read_b128 v[204:207], v144 offset:54272
	ds_read_b128 v[208:211], v144 offset:55296
	ds_read_b128 v[212:215], v144 offset:56320
	global_load_lds_dwordx4 v[140:141], off
	v_lshl_add_u64 v[140:141], v[194:195], 0, s[90:91]
	s_mov_b32 m0, s80
	s_nop 0
	global_load_lds_dwordx4 v[140:141], off
	v_lshl_add_u64 v[140:141], s[36:37], 0, v[136:137]
	s_mov_b32 m0, s83
	s_nop 0
	global_load_lds_dwordx4 v[140:141], off
	v_lshl_add_u64 v[140:141], s[36:37], 0, v[132:133]
	s_mov_b32 m0, s82
	s_nop 0
	global_load_lds_dwordx4 v[140:141], off
	v_lshl_add_u64 v[140:141], v[198:199], 0, s[90:91]
	s_mov_b32 m0, s61
	s_nop 0
	global_load_lds_dwordx4 v[140:141], off
	v_lshl_add_u64 v[140:141], v[216:217], 0, s[90:91]
	s_mov_b32 m0, s74
	s_nop 0
	global_load_lds_dwordx4 v[140:141], off
	s_nop 0
	s_waitcnt vmcnt(8)
	s_waitcnt lgkmcnt(0)
	s_setprio 1
	s_barrier
	v_mfma_f32_16x16x32_bf16 v[64:67], v[146:149], v[178:181], v[64:67]
	v_mfma_f32_16x16x32_bf16 v[60:63], v[154:157], v[178:181], v[60:63]
	v_mfma_f32_16x16x32_bf16 v[56:59], v[146:149], v[186:189], v[56:59]
	v_mfma_f32_16x16x32_bf16 v[48:51], v[154:157], v[186:189], v[48:51]
	v_mfma_f32_16x16x32_bf16 v[40:43], v[146:149], v[200:203], v[40:43]
	v_mfma_f32_16x16x32_bf16 v[32:35], v[154:157], v[200:203], v[32:35]
	v_mfma_f32_16x16x32_bf16 v[24:27], v[146:149], v[208:211], v[24:27]
	v_mfma_f32_16x16x32_bf16 v[16:19], v[154:157], v[208:211], v[16:19]
	v_mfma_f32_16x16x32_bf16 v[64:67], v[150:153], v[182:185], v[64:67]
	v_mfma_f32_16x16x32_bf16 v[60:63], v[158:161], v[182:185], v[60:63]
	v_mfma_f32_16x16x32_bf16 v[56:59], v[150:153], v[190:193], v[56:59]
	v_mfma_f32_16x16x32_bf16 v[48:51], v[158:161], v[190:193], v[48:51]
	v_mfma_f32_16x16x32_bf16 v[40:43], v[150:153], v[204:207], v[40:43]
	v_mfma_f32_16x16x32_bf16 v[32:35], v[158:161], v[204:207], v[32:35]
	v_mfma_f32_16x16x32_bf16 v[24:27], v[150:153], v[212:215], v[24:27]
	v_mfma_f32_16x16x32_bf16 v[16:19], v[158:161], v[212:215], v[16:19]
	s_setprio 0
	s_setprio 1
	v_mfma_f32_16x16x32_bf16 v[52:55], v[162:165], v[178:181], v[52:55]
	v_mfma_f32_16x16x32_bf16 v[44:47], v[170:173], v[178:181], v[44:47]
	v_mfma_f32_16x16x32_bf16 v[36:39], v[162:165], v[186:189], v[36:39]
	v_mfma_f32_16x16x32_bf16 v[28:31], v[170:173], v[186:189], v[28:31]
	v_mfma_f32_16x16x32_bf16 v[20:23], v[162:165], v[200:203], v[20:23]
	v_mfma_f32_16x16x32_bf16 v[12:15], v[170:173], v[200:203], v[12:15]
	v_mfma_f32_16x16x32_bf16 v[8:11], v[162:165], v[208:211], v[8:11]
	v_mfma_f32_16x16x32_bf16 v[4:7], v[170:173], v[208:211], v[4:7]
	v_mfma_f32_16x16x32_bf16 v[52:55], v[166:169], v[182:185], v[52:55]
	v_mfma_f32_16x16x32_bf16 v[44:47], v[174:177], v[182:185], v[44:47]
	v_mfma_f32_16x16x32_bf16 v[36:39], v[166:169], v[190:193], v[36:39]
	v_mfma_f32_16x16x32_bf16 v[28:31], v[174:177], v[190:193], v[28:31]
	v_mfma_f32_16x16x32_bf16 v[20:23], v[166:169], v[204:207], v[20:23]
	v_mfma_f32_16x16x32_bf16 v[12:15], v[174:177], v[204:207], v[12:15]
	v_mfma_f32_16x16x32_bf16 v[8:11], v[166:169], v[212:215], v[8:11]
	v_mfma_f32_16x16x32_bf16 v[4:7], v[174:177], v[212:215], v[4:7]
	s_barrier
	s_setprio 0
	s_movk_i32 s30, 0x100
	s_andn2_b64 vcc, exec, s[66:67]
	s_mov_b64 s[36:37], -1
	s_mov_b64 s[66:67], 0
	s_cbranch_vccz .LBB0_1186
	s_and_b64 vcc, exec, s[20:21]
	s_cbranch_vccz .LBB0_1189
	s_barrier

.LBB0_1273:
	s_add_i32 s74, s30, 2
	s_add_u32 s62, s36, 0x100
	s_addc_u32 s63, s37, 0
	s_add_i32 s0, 0, 0x10000
	s_cmp_eq_u32 s29, s30
	s_cselect_b32 s35, s43, s63
	s_cselect_b32 s34, s42, s62
	s_cselect_b32 s31, s45, s72
	s_cselect_b32 s30, s44, s69
	s_add_i32 s6, 0, 0x14000
	v_add_u32_e32 v144, s0, v3
	v_add_u32_e32 v160, s6, v3
	ds_read_b128 v[124:127], v144
	ds_read_b128 v[128:131], v144 offset:1024
	ds_read_b128 v[140:143], v144 offset:2048
	ds_read_b128 v[144:147], v144 offset:3072
	ds_read_b128 v[148:151], v160
	ds_read_b128 v[152:155], v160 offset:1024
	ds_read_b128 v[156:159], v160 offset:2048
	ds_read_b128 v[160:163], v160 offset:3072
	v_lshl_add_u64 v[198:199], s[36:37], 0, v[212:213]
	s_add_i32 m0, s33, 0xc000
	ds_read_b128 v[164:167], v250
	ds_read_b128 v[168:171], v250 offset:1024
	ds_read_b128 v[172:175], v250 offset:2048
	ds_read_b128 v[176:179], v250 offset:3072
	ds_read_b128 v[180:183], v250 offset:4096
	ds_read_b128 v[184:187], v250 offset:5120
	ds_read_b128 v[188:191], v250 offset:6144
	ds_read_b128 v[192:195], v250 offset:7168
	global_load_lds_dwordx4 v[198:199], off
	v_lshl_add_u64 v[198:199], s[36:37], 0, v[214:215]
	s_add_i32 m0, s33, 0xe000
	s_nop 0
	global_load_lds_dwordx4 v[198:199], off
	s_nop 0
	s_waitcnt vmcnt(8)
	s_waitcnt lgkmcnt(0)
	s_setprio 1
	s_barrier
	v_mfma_f32_16x16x32_bf16 v[136:139], v[124:127], v[164:167], v[136:139]
	v_mfma_f32_16x16x32_bf16 v[132:135], v[140:143], v[164:167], v[132:135]
	v_mfma_f32_16x16x32_bf16 v[112:115], v[124:127], v[172:175], v[112:115]
	v_mfma_f32_16x16x32_bf16 v[108:111], v[140:143], v[172:175], v[108:111]
	v_mfma_f32_16x16x32_bf16 v[96:99], v[124:127], v[180:183], v[96:99]
	v_mfma_f32_16x16x32_bf16 v[92:95], v[140:143], v[180:183], v[92:95]
	v_mfma_f32_16x16x32_bf16 v[80:83], v[124:127], v[188:191], v[80:83]
	v_mfma_f32_16x16x32_bf16 v[76:79], v[140:143], v[188:191], v[76:79]
	v_mfma_f32_16x16x32_bf16 v[136:139], v[128:131], v[168:171], v[136:139]
	v_mfma_f32_16x16x32_bf16 v[132:135], v[144:147], v[168:171], v[132:135]
	v_mfma_f32_16x16x32_bf16 v[112:115], v[128:131], v[176:179], v[112:115]
	v_mfma_f32_16x16x32_bf16 v[108:111], v[144:147], v[176:179], v[108:111]
	v_mfma_f32_16x16x32_bf16 v[96:99], v[128:131], v[184:187], v[96:99]
	v_mfma_f32_16x16x32_bf16 v[92:95], v[144:147], v[184:187], v[92:95]
	v_mfma_f32_16x16x32_bf16 v[80:83], v[128:131], v[192:195], v[80:83]
	v_mfma_f32_16x16x32_bf16 v[76:79], v[144:147], v[192:195], v[76:79]
	s_setprio 0
	s_setprio 1
	v_mfma_f32_16x16x32_bf16 v[120:123], v[148:151], v[164:167], v[120:123]
	v_mfma_f32_16x16x32_bf16 v[116:119], v[156:159], v[164:167], v[116:119]
	v_mfma_f32_16x16x32_bf16 v[104:107], v[148:151], v[172:175], v[104:107]
	v_mfma_f32_16x16x32_bf16 v[100:103], v[156:159], v[172:175], v[100:103]
	v_mfma_f32_16x16x32_bf16 v[88:91], v[148:151], v[180:183], v[88:91]
	v_mfma_f32_16x16x32_bf16 v[84:87], v[156:159], v[180:183], v[84:87]
	v_mfma_f32_16x16x32_bf16 v[72:75], v[148:151], v[188:191], v[72:75]
	v_mfma_f32_16x16x32_bf16 v[68:71], v[156:159], v[188:191], v[68:71]
	v_mfma_f32_16x16x32_bf16 v[120:123], v[152:155], v[168:171], v[120:123]
	v_mfma_f32_16x16x32_bf16 v[116:119], v[160:163], v[168:171], v[116:119]
	v_mfma_f32_16x16x32_bf16 v[104:107], v[152:155], v[176:179], v[104:107]
	v_mfma_f32_16x16x32_bf16 v[100:103], v[160:163], v[176:179], v[100:103]
	v_mfma_f32_16x16x32_bf16 v[88:91], v[152:155], v[184:187], v[88:91]
	v_mfma_f32_16x16x32_bf16 v[84:87], v[160:163], v[184:187], v[84:87]
	v_mfma_f32_16x16x32_bf16 v[72:75], v[152:155], v[192:195], v[72:75]
	v_mfma_f32_16x16x32_bf16 v[68:71], v[160:163], v[192:195], v[68:71]
	s_barrier
	s_setprio 0
	s_add_i32 s0, s0, s27
	v_lshl_add_u64 v[198:199], s[30:31], 0, v[202:203]
	s_mov_b32 m0, s0
	ds_read_b128 v[164:167], v250 offset:16384
	ds_read_b128 v[168:171], v250 offset:17408
	ds_read_b128 v[172:175], v250 offset:18432
	ds_read_b128 v[176:179], v250 offset:19456
	ds_read_b128 v[180:183], v250 offset:20480
	ds_read_b128 v[184:187], v250 offset:21504
	ds_read_b128 v[188:191], v250 offset:22528
	ds_read_b128 v[192:195], v250 offset:23552
	global_load_lds_dwordx4 v[198:199], off
	s_add_i32 m0, s0, 0x2000
	s_add_u32 s36, s30, 0x204000
	v_lshl_add_u64 v[216:217], s[30:31], 0, v[206:207]
	s_addc_u32 s37, s31, 0
	s_add_i32 s0, s6, s27
	global_load_lds_dwordx4 v[216:217], off
	v_lshl_add_u64 v[218:219], s[36:37], 0, v[202:203]
	s_mov_b32 m0, s0
	v_lshl_add_u64 v[220:221], s[34:35], 0, v[204:205]
	global_load_lds_dwordx4 v[218:219], off
	v_lshl_add_u64 v[218:219], s[36:37], 0, v[206:207]
	s_add_i32 m0, s0, 0x2000
	s_nop 0
	global_load_lds_dwordx4 v[218:219], off
	v_lshl_add_u64 v[218:219], s[34:35], 0, v[200:201]
	s_mov_b32 m0, s33
	s_nop 0
	global_load_lds_dwordx4 v[218:219], off
	s_mov_b32 m0, s38
	s_nop 0
	global_load_lds_dwordx4 v[220:221], off
	s_waitcnt vmcnt(8)
	s_waitcnt lgkmcnt(0)
	s_setprio 1
	s_barrier
	v_mfma_f32_16x16x32_bf16 v[64:67], v[124:127], v[164:167], v[64:67]
	v_mfma_f32_16x16x32_bf16 v[60:63], v[140:143], v[164:167], v[60:63]
	v_mfma_f32_16x16x32_bf16 v[48:51], v[124:127], v[172:175], v[48:51]
	v_mfma_f32_16x16x32_bf16 v[44:47], v[140:143], v[172:175], v[44:47]
	v_mfma_f32_16x16x32_bf16 v[32:35], v[124:127], v[180:183], v[32:35]
	v_mfma_f32_16x16x32_bf16 v[28:31], v[140:143], v[180:183], v[28:31]
	v_mfma_f32_16x16x32_bf16 v[16:19], v[124:127], v[188:191], v[16:19]
	v_mfma_f32_16x16x32_bf16 v[12:15], v[140:143], v[188:191], v[12:15]
	v_mfma_f32_16x16x32_bf16 v[64:67], v[128:131], v[168:171], v[64:67]
	v_mfma_f32_16x16x32_bf16 v[60:63], v[144:147], v[168:171], v[60:63]
	v_mfma_f32_16x16x32_bf16 v[48:51], v[128:131], v[176:179], v[48:51]
	v_mfma_f32_16x16x32_bf16 v[44:47], v[144:147], v[176:179], v[44:47]
	v_mfma_f32_16x16x32_bf16 v[32:35], v[128:131], v[184:187], v[32:35]
	v_mfma_f32_16x16x32_bf16 v[28:31], v[144:147], v[184:187], v[28:31]
	v_mfma_f32_16x16x32_bf16 v[16:19], v[128:131], v[192:195], v[16:19]
	v_mfma_f32_16x16x32_bf16 v[12:15], v[144:147], v[192:195], v[12:15]
	s_setprio 0
	s_setprio 1
	v_mfma_f32_16x16x32_bf16 v[56:59], v[148:151], v[164:167], v[56:59]
	v_mfma_f32_16x16x32_bf16 v[52:55], v[156:159], v[164:167], v[52:55]
	v_mfma_f32_16x16x32_bf16 v[40:43], v[148:151], v[172:175], v[40:43]
	v_mfma_f32_16x16x32_bf16 v[36:39], v[156:159], v[172:175], v[36:39]
	v_mfma_f32_16x16x32_bf16 v[24:27], v[148:151], v[180:183], v[24:27]
	v_mfma_f32_16x16x32_bf16 v[20:23], v[156:159], v[180:183], v[20:23]
	v_mfma_f32_16x16x32_bf16 v[8:11], v[148:151], v[188:191], v[8:11]
	v_mfma_f32_16x16x32_bf16 v[4:7], v[156:159], v[188:191], v[4:7]
	v_mfma_f32_16x16x32_bf16 v[56:59], v[152:155], v[168:171], v[56:59]
	v_mfma_f32_16x16x32_bf16 v[52:55], v[160:163], v[168:171], v[52:55]
	v_mfma_f32_16x16x32_bf16 v[40:43], v[152:155], v[176:179], v[40:43]
	v_mfma_f32_16x16x32_bf16 v[36:39], v[160:163], v[176:179], v[36:39]
	v_mfma_f32_16x16x32_bf16 v[24:27], v[152:155], v[184:187], v[24:27]
	v_mfma_f32_16x16x32_bf16 v[20:23], v[160:163], v[184:187], v[20:23]
	v_mfma_f32_16x16x32_bf16 v[8:11], v[152:155], v[192:195], v[8:11]
	v_mfma_f32_16x16x32_bf16 v[4:7], v[160:163], v[192:195], v[4:7]
	s_barrier
	s_setprio 0
	s_add_i32 s0, 0, 0x18000
	s_add_i32 s6, 0, 0x1c000
	v_add_u32_e32 v144, s0, v3
	v_add_u32_e32 v160, s6, v3
	ds_read_b128 v[124:127], v144
	ds_read_b128 v[128:131], v144 offset:1024
	ds_read_b128 v[140:143], v144 offset:2048
	ds_read_b128 v[144:147], v144 offset:3072
	ds_read_b128 v[148:151], v160
	ds_read_b128 v[152:155], v160 offset:1024
	ds_read_b128 v[156:159], v160 offset:2048
	ds_read_b128 v[160:163], v160 offset:3072
	s_add_u32 s34, s34, 0x204000
	s_addc_u32 s35, s35, 0
	s_mov_b32 m0, s39
	v_lshl_add_u64 v[222:223], s[34:35], 0, v[200:201]
	ds_read_b128 v[164:167], v250 offset:32768
	ds_read_b128 v[168:171], v250 offset:33792
	ds_read_b128 v[172:175], v250 offset:34816
	ds_read_b128 v[176:179], v250 offset:35840
	ds_read_b128 v[180:183], v250 offset:36864
	ds_read_b128 v[184:187], v250 offset:37888
	ds_read_b128 v[188:191], v250 offset:38912
	ds_read_b128 v[192:195], v250 offset:39936
	global_load_lds_dwordx4 v[222:223], off
	v_lshl_add_u64 v[222:223], s[34:35], 0, v[204:205]
	s_mov_b32 m0, s40
	s_nop 0
	global_load_lds_dwordx4 v[222:223], off
	s_waitcnt vmcnt(8)
	s_waitcnt lgkmcnt(0)
	s_setprio 1
	s_barrier
	v_mfma_f32_16x16x32_bf16 v[136:139], v[124:127], v[164:167], v[136:139]
	v_mfma_f32_16x16x32_bf16 v[132:135], v[140:143], v[164:167], v[132:135]
	v_mfma_f32_16x16x32_bf16 v[112:115], v[124:127], v[172:175], v[112:115]
	v_mfma_f32_16x16x32_bf16 v[108:111], v[140:143], v[172:175], v[108:111]
	v_mfma_f32_16x16x32_bf16 v[96:99], v[124:127], v[180:183], v[96:99]
	v_mfma_f32_16x16x32_bf16 v[92:95], v[140:143], v[180:183], v[92:95]
	v_mfma_f32_16x16x32_bf16 v[80:83], v[124:127], v[188:191], v[80:83]
	v_mfma_f32_16x16x32_bf16 v[76:79], v[140:143], v[188:191], v[76:79]
	v_mfma_f32_16x16x32_bf16 v[136:139], v[128:131], v[168:171], v[136:139]
	v_mfma_f32_16x16x32_bf16 v[132:135], v[144:147], v[168:171], v[132:135]
	v_mfma_f32_16x16x32_bf16 v[112:115], v[128:131], v[176:179], v[112:115]
	v_mfma_f32_16x16x32_bf16 v[108:111], v[144:147], v[176:179], v[108:111]
	v_mfma_f32_16x16x32_bf16 v[96:99], v[128:131], v[184:187], v[96:99]
	v_mfma_f32_16x16x32_bf16 v[92:95], v[144:147], v[184:187], v[92:95]
	v_mfma_f32_16x16x32_bf16 v[80:83], v[128:131], v[192:195], v[80:83]
	v_mfma_f32_16x16x32_bf16 v[76:79], v[144:147], v[192:195], v[76:79]
	s_setprio 0
	s_setprio 1
	v_mfma_f32_16x16x32_bf16 v[120:123], v[148:151], v[164:167], v[120:123]
	v_mfma_f32_16x16x32_bf16 v[116:119], v[156:159], v[164:167], v[116:119]
	v_mfma_f32_16x16x32_bf16 v[104:107], v[148:151], v[172:175], v[104:107]
	v_mfma_f32_16x16x32_bf16 v[100:103], v[156:159], v[172:175], v[100:103]
	v_mfma_f32_16x16x32_bf16 v[88:91], v[148:151], v[180:183], v[88:91]
	v_mfma_f32_16x16x32_bf16 v[84:87], v[156:159], v[180:183], v[84:87]
	v_mfma_f32_16x16x32_bf16 v[72:75], v[148:151], v[188:191], v[72:75]
	v_mfma_f32_16x16x32_bf16 v[68:71], v[156:159], v[188:191], v[68:71]
	v_mfma_f32_16x16x32_bf16 v[120:123], v[152:155], v[168:171], v[120:123]
	v_mfma_f32_16x16x32_bf16 v[116:119], v[160:163], v[168:171], v[116:119]
	v_mfma_f32_16x16x32_bf16 v[104:107], v[152:155], v[176:179], v[104:107]
	v_mfma_f32_16x16x32_bf16 v[100:103], v[160:163], v[176:179], v[100:103]
	v_mfma_f32_16x16x32_bf16 v[88:91], v[152:155], v[184:187], v[88:91]
	v_mfma_f32_16x16x32_bf16 v[84:87], v[160:163], v[184:187], v[84:87]
	v_mfma_f32_16x16x32_bf16 v[72:75], v[152:155], v[192:195], v[72:75]
	v_mfma_f32_16x16x32_bf16 v[68:71], v[160:163], v[192:195], v[68:71]
	s_barrier
	s_setprio 0
	s_add_i32 s0, s0, s27
	v_lshl_add_u64 v[198:199], v[198:199], 0, s[90:91]
	s_mov_b32 m0, s0
	ds_read_b128 v[164:167], v250 offset:49152
	ds_read_b128 v[168:171], v250 offset:50176
	ds_read_b128 v[172:175], v250 offset:51200
	ds_read_b128 v[176:179], v250 offset:52224
	ds_read_b128 v[180:183], v250 offset:53248
	ds_read_b128 v[184:187], v250 offset:54272
	ds_read_b128 v[188:191], v250 offset:55296
	ds_read_b128 v[192:195], v250 offset:56320
	global_load_lds_dwordx4 v[198:199], off
	s_add_i32 m0, s0, 0x2000
	s_add_u32 s30, s30, 0x204080
	v_lshl_add_u64 v[198:199], v[216:217], 0, s[90:91]
	s_addc_u32 s31, s31, 0
	s_add_i32 s0, s6, s27
	global_load_lds_dwordx4 v[198:199], off
	v_lshl_add_u64 v[198:199], s[30:31], 0, v[202:203]
	s_mov_b32 m0, s0
	s_nop 0
	global_load_lds_dwordx4 v[198:199], off
	v_lshl_add_u64 v[198:199], s[30:31], 0, v[206:207]
	s_add_i32 m0, s0, 0x2000
	s_nop 0
	global_load_lds_dwordx4 v[198:199], off
	v_lshl_add_u64 v[198:199], v[218:219], 0, s[90:91]
	s_mov_b32 m0, s50
	s_nop 0
	global_load_lds_dwordx4 v[198:199], off
	v_lshl_add_u64 v[198:199], v[220:221], 0, s[90:91]
	s_mov_b32 m0, s51
	s_nop 0
	global_load_lds_dwordx4 v[198:199], off
	s_nop 0
	s_waitcnt vmcnt(8)
	s_waitcnt lgkmcnt(0)
	s_setprio 1
	s_barrier
	v_mfma_f32_16x16x32_bf16 v[64:67], v[124:127], v[164:167], v[64:67]
	v_mfma_f32_16x16x32_bf16 v[60:63], v[140:143], v[164:167], v[60:63]
	v_mfma_f32_16x16x32_bf16 v[48:51], v[124:127], v[172:175], v[48:51]
	v_mfma_f32_16x16x32_bf16 v[44:47], v[140:143], v[172:175], v[44:47]
	v_mfma_f32_16x16x32_bf16 v[32:35], v[124:127], v[180:183], v[32:35]
	v_mfma_f32_16x16x32_bf16 v[28:31], v[140:143], v[180:183], v[28:31]
	v_mfma_f32_16x16x32_bf16 v[16:19], v[124:127], v[188:191], v[16:19]
	v_mfma_f32_16x16x32_bf16 v[12:15], v[140:143], v[188:191], v[12:15]
	v_mfma_f32_16x16x32_bf16 v[64:67], v[128:131], v[168:171], v[64:67]
	v_mfma_f32_16x16x32_bf16 v[60:63], v[144:147], v[168:171], v[60:63]
	v_mfma_f32_16x16x32_bf16 v[48:51], v[128:131], v[176:179], v[48:51]
	v_mfma_f32_16x16x32_bf16 v[44:47], v[144:147], v[176:179], v[44:47]
	v_mfma_f32_16x16x32_bf16 v[32:35], v[128:131], v[184:187], v[32:35]
	v_mfma_f32_16x16x32_bf16 v[28:31], v[144:147], v[184:187], v[28:31]
	v_mfma_f32_16x16x32_bf16 v[16:19], v[128:131], v[192:195], v[16:19]
	v_mfma_f32_16x16x32_bf16 v[12:15], v[144:147], v[192:195], v[12:15]
	s_setprio 0
	s_setprio 1
	v_mfma_f32_16x16x32_bf16 v[56:59], v[148:151], v[164:167], v[56:59]
	v_mfma_f32_16x16x32_bf16 v[52:55], v[156:159], v[164:167], v[52:55]
	v_mfma_f32_16x16x32_bf16 v[40:43], v[148:151], v[172:175], v[40:43]
	v_mfma_f32_16x16x32_bf16 v[36:39], v[156:159], v[172:175], v[36:39]
	v_mfma_f32_16x16x32_bf16 v[24:27], v[148:151], v[180:183], v[24:27]
	v_mfma_f32_16x16x32_bf16 v[20:23], v[156:159], v[180:183], v[20:23]
	v_mfma_f32_16x16x32_bf16 v[8:11], v[148:151], v[188:191], v[8:11]
	v_mfma_f32_16x16x32_bf16 v[4:7], v[156:159], v[188:191], v[4:7]
	v_mfma_f32_16x16x32_bf16 v[56:59], v[152:155], v[168:171], v[56:59]
	v_mfma_f32_16x16x32_bf16 v[52:55], v[160:163], v[168:171], v[52:55]
	v_mfma_f32_16x16x32_bf16 v[40:43], v[152:155], v[176:179], v[40:43]
	v_mfma_f32_16x16x32_bf16 v[36:39], v[160:163], v[176:179], v[36:39]
	v_mfma_f32_16x16x32_bf16 v[24:27], v[152:155], v[184:187], v[24:27]
	v_mfma_f32_16x16x32_bf16 v[20:23], v[160:163], v[184:187], v[20:23]
	v_mfma_f32_16x16x32_bf16 v[8:11], v[152:155], v[192:195], v[8:11]
	v_mfma_f32_16x16x32_bf16 v[4:7], v[160:163], v[192:195], v[4:7]
	s_barrier
	s_setprio 0
	s_add_u32 s69, s69, 0x100
	s_addc_u32 s72, s72, 0
	s_cmp_ge_i32 s74, s61
	s_mov_b64 s[36:37], s[62:63]
	s_mov_b32 s30, s74
	s_cbranch_scc0 .LBB0_1273
	s_and_b64 vcc, exec, s[22:23]
	s_cbranch_vccz .LBB0_1276
	s_barrier

.LBB0_1395:
	s_add_u32 s0, s36, 0xfff80080
	s_addc_u32 s6, s37, -1
	s_add_i32 s49, 0, 0x10000
	s_cmp_eq_u32 s67, 28
	s_cselect_b32 s35, s25, s6
	s_cselect_b32 s34, s33, s0
	s_cselect_b32 s31, s43, s39
	s_cselect_b32 s30, s45, s38
	s_add_i32 s0, 0, 0x14000
	v_add_u32_e32 v144, s49, v3
	v_add_u32_e32 v176, s0, v3
	ds_read_b128 v[132:135], v144
	ds_read_b128 v[136:139], v144 offset:1024
	ds_read_b128 v[140:143], v144 offset:2048
	ds_read_b128 v[144:147], v144 offset:3072
	ds_read_b128 v[164:167], v176
	ds_read_b128 v[168:171], v176 offset:1024
	ds_read_b128 v[172:175], v176 offset:2048
	ds_read_b128 v[176:179], v176 offset:3072
	v_lshl_add_u64 v[198:199], s[36:37], 0, v[160:161]
	s_add_i32 m0, s47, 0xc000
	ds_read_b128 v[180:183], v190
	ds_read_b128 v[184:187], v190 offset:1024
	ds_read_b128 v[192:195], v190 offset:2048
	ds_read_b128 v[200:203], v190 offset:3072
	ds_read_b128 v[204:207], v190 offset:4096
	ds_read_b128 v[208:211], v190 offset:5120
	ds_read_b128 v[212:215], v190 offset:6144
	ds_read_b128 v[216:219], v190 offset:7168
	global_load_lds_dwordx4 v[198:199], off
	v_lshl_add_u64 v[198:199], s[36:37], 0, v[162:163]
	s_add_i32 m0, s47, 0xe000
	s_nop 0
	global_load_lds_dwordx4 v[198:199], off
	s_waitcnt vmcnt(8)
	s_waitcnt lgkmcnt(0)
	s_setprio 1
	s_barrier
	v_mfma_f32_16x16x32_bf16 v[128:131], v[132:135], v[180:183], v[128:131]
	v_mfma_f32_16x16x32_bf16 v[124:127], v[140:143], v[180:183], v[124:127]
	v_mfma_f32_16x16x32_bf16 v[112:115], v[132:135], v[192:195], v[112:115]
	v_mfma_f32_16x16x32_bf16 v[108:111], v[140:143], v[192:195], v[108:111]
	v_mfma_f32_16x16x32_bf16 v[96:99], v[132:135], v[204:207], v[96:99]
	v_mfma_f32_16x16x32_bf16 v[92:95], v[140:143], v[204:207], v[92:95]
	v_mfma_f32_16x16x32_bf16 v[80:83], v[132:135], v[212:215], v[80:83]
	v_mfma_f32_16x16x32_bf16 v[76:79], v[140:143], v[212:215], v[76:79]
	v_mfma_f32_16x16x32_bf16 v[128:131], v[136:139], v[184:187], v[128:131]
	v_mfma_f32_16x16x32_bf16 v[124:127], v[144:147], v[184:187], v[124:127]
	v_mfma_f32_16x16x32_bf16 v[112:115], v[136:139], v[200:203], v[112:115]
	v_mfma_f32_16x16x32_bf16 v[108:111], v[144:147], v[200:203], v[108:111]
	v_mfma_f32_16x16x32_bf16 v[96:99], v[136:139], v[208:211], v[96:99]
	v_mfma_f32_16x16x32_bf16 v[92:95], v[144:147], v[208:211], v[92:95]
	v_mfma_f32_16x16x32_bf16 v[80:83], v[136:139], v[216:219], v[80:83]
	v_mfma_f32_16x16x32_bf16 v[76:79], v[144:147], v[216:219], v[76:79]
	s_setprio 0
	s_setprio 1
	v_mfma_f32_16x16x32_bf16 v[120:123], v[164:167], v[180:183], v[120:123]
	v_mfma_f32_16x16x32_bf16 v[116:119], v[172:175], v[180:183], v[116:119]
	v_mfma_f32_16x16x32_bf16 v[104:107], v[164:167], v[192:195], v[104:107]
	v_mfma_f32_16x16x32_bf16 v[100:103], v[172:175], v[192:195], v[100:103]
	v_mfma_f32_16x16x32_bf16 v[88:91], v[164:167], v[204:207], v[88:91]
	v_mfma_f32_16x16x32_bf16 v[84:87], v[172:175], v[204:207], v[84:87]
	v_mfma_f32_16x16x32_bf16 v[72:75], v[164:167], v[212:215], v[72:75]
	v_mfma_f32_16x16x32_bf16 v[68:71], v[172:175], v[212:215], v[68:71]
	v_mfma_f32_16x16x32_bf16 v[120:123], v[168:171], v[184:187], v[120:123]
	v_mfma_f32_16x16x32_bf16 v[116:119], v[176:179], v[184:187], v[116:119]
	v_mfma_f32_16x16x32_bf16 v[104:107], v[168:171], v[200:203], v[104:107]
	v_mfma_f32_16x16x32_bf16 v[100:103], v[176:179], v[200:203], v[100:103]
	v_mfma_f32_16x16x32_bf16 v[88:91], v[168:171], v[208:211], v[88:91]
	v_mfma_f32_16x16x32_bf16 v[84:87], v[176:179], v[208:211], v[84:87]
	v_mfma_f32_16x16x32_bf16 v[72:75], v[168:171], v[216:219], v[72:75]
	v_mfma_f32_16x16x32_bf16 v[68:71], v[176:179], v[216:219], v[68:71]
	s_barrier
	s_setprio 0
	s_add_i32 s6, s49, s4
	v_lshl_add_u64 v[198:199], s[30:31], 0, v[152:153]
	s_mov_b32 m0, s6
	ds_read_b128 v[180:183], v190 offset:16384
	ds_read_b128 v[184:187], v190 offset:17408
	ds_read_b128 v[192:195], v190 offset:18432
	ds_read_b128 v[200:203], v190 offset:19456
	ds_read_b128 v[204:207], v190 offset:20480
	ds_read_b128 v[208:211], v190 offset:21504
	ds_read_b128 v[212:215], v190 offset:22528
	ds_read_b128 v[216:219], v190 offset:23552
	global_load_lds_dwordx4 v[198:199], off
	s_add_i32 m0, s6, 0x2000
	s_add_u32 s68, s30, 0x80000
	v_lshl_add_u64 v[220:221], s[30:31], 0, v[148:149]
	s_addc_u32 s69, s31, 0
	s_add_i32 s0, s0, s4
	global_load_lds_dwordx4 v[220:221], off
	v_lshl_add_u64 v[222:223], s[68:69], 0, v[152:153]
	s_mov_b32 m0, s0
	v_lshl_add_u64 v[224:225], s[34:35], 0, v[150:151]
	global_load_lds_dwordx4 v[222:223], off
	v_lshl_add_u64 v[222:223], s[68:69], 0, v[148:149]
	s_add_i32 m0, s0, 0x2000
	s_nop 0
	global_load_lds_dwordx4 v[222:223], off
	v_lshl_add_u64 v[222:223], s[34:35], 0, v[154:155]
	s_mov_b32 m0, s47
	s_nop 0
	global_load_lds_dwordx4 v[222:223], off
	s_mov_b32 m0, s52
	s_nop 0
	global_load_lds_dwordx4 v[224:225], off
	s_waitcnt vmcnt(8)
	s_waitcnt lgkmcnt(0)
	s_setprio 1
	s_barrier
	v_mfma_f32_16x16x32_bf16 v[64:67], v[132:135], v[180:183], v[64:67]
	v_mfma_f32_16x16x32_bf16 v[60:63], v[140:143], v[180:183], v[60:63]
	v_mfma_f32_16x16x32_bf16 v[48:51], v[132:135], v[192:195], v[48:51]
	v_mfma_f32_16x16x32_bf16 v[44:47], v[140:143], v[192:195], v[44:47]
	v_mfma_f32_16x16x32_bf16 v[32:35], v[132:135], v[204:207], v[32:35]
	v_mfma_f32_16x16x32_bf16 v[28:31], v[140:143], v[204:207], v[28:31]
	v_mfma_f32_16x16x32_bf16 v[16:19], v[132:135], v[212:215], v[16:19]
	v_mfma_f32_16x16x32_bf16 v[12:15], v[140:143], v[212:215], v[12:15]
	v_mfma_f32_16x16x32_bf16 v[64:67], v[136:139], v[184:187], v[64:67]
	v_mfma_f32_16x16x32_bf16 v[60:63], v[144:147], v[184:187], v[60:63]
	v_mfma_f32_16x16x32_bf16 v[48:51], v[136:139], v[200:203], v[48:51]
	v_mfma_f32_16x16x32_bf16 v[44:47], v[144:147], v[200:203], v[44:47]
	v_mfma_f32_16x16x32_bf16 v[32:35], v[136:139], v[208:211], v[32:35]
	v_mfma_f32_16x16x32_bf16 v[28:31], v[144:147], v[208:211], v[28:31]
	v_mfma_f32_16x16x32_bf16 v[16:19], v[136:139], v[216:219], v[16:19]
	v_mfma_f32_16x16x32_bf16 v[12:15], v[144:147], v[216:219], v[12:15]
	s_setprio 0
	s_setprio 1
	v_mfma_f32_16x16x32_bf16 v[56:59], v[164:167], v[180:183], v[56:59]
	v_mfma_f32_16x16x32_bf16 v[52:55], v[172:175], v[180:183], v[52:55]
	v_mfma_f32_16x16x32_bf16 v[40:43], v[164:167], v[192:195], v[40:43]
	v_mfma_f32_16x16x32_bf16 v[36:39], v[172:175], v[192:195], v[36:39]
	v_mfma_f32_16x16x32_bf16 v[24:27], v[164:167], v[204:207], v[24:27]
	v_mfma_f32_16x16x32_bf16 v[20:23], v[172:175], v[204:207], v[20:23]
	v_mfma_f32_16x16x32_bf16 v[8:11], v[164:167], v[212:215], v[8:11]
	v_mfma_f32_16x16x32_bf16 v[4:7], v[172:175], v[212:215], v[4:7]
	v_mfma_f32_16x16x32_bf16 v[56:59], v[168:171], v[184:187], v[56:59]
	v_mfma_f32_16x16x32_bf16 v[52:55], v[176:179], v[184:187], v[52:55]
	v_mfma_f32_16x16x32_bf16 v[40:43], v[168:171], v[200:203], v[40:43]
	v_mfma_f32_16x16x32_bf16 v[36:39], v[176:179], v[200:203], v[36:39]
	v_mfma_f32_16x16x32_bf16 v[24:27], v[168:171], v[208:211], v[24:27]
	v_mfma_f32_16x16x32_bf16 v[20:23], v[176:179], v[208:211], v[20:23]
	v_mfma_f32_16x16x32_bf16 v[8:11], v[168:171], v[216:219], v[8:11]
	v_mfma_f32_16x16x32_bf16 v[4:7], v[176:179], v[216:219], v[4:7]
	s_barrier
	s_setprio 0
	s_add_i32 s0, 0, 0x18000
	s_add_i32 s6, 0, 0x1c000
	v_add_u32_e32 v144, s0, v3
	v_add_u32_e32 v176, s6, v3
	ds_read_b128 v[132:135], v144
	ds_read_b128 v[136:139], v144 offset:1024
	ds_read_b128 v[140:143], v144 offset:2048
	ds_read_b128 v[144:147], v144 offset:3072
	ds_read_b128 v[164:167], v176
	ds_read_b128 v[168:171], v176 offset:1024
	ds_read_b128 v[172:175], v176 offset:2048
	ds_read_b128 v[176:179], v176 offset:3072
	s_add_u32 s34, s34, 0x80000
	s_addc_u32 s35, s35, 0
	s_mov_b32 m0, s53
	v_lshl_add_u64 v[226:227], s[34:35], 0, v[154:155]
	ds_read_b128 v[180:183], v190 offset:32768
	ds_read_b128 v[184:187], v190 offset:33792
	ds_read_b128 v[192:195], v190 offset:34816
	ds_read_b128 v[200:203], v190 offset:35840
	ds_read_b128 v[204:207], v190 offset:36864
	ds_read_b128 v[208:211], v190 offset:37888
	ds_read_b128 v[212:215], v190 offset:38912
	ds_read_b128 v[216:219], v190 offset:39936
	global_load_lds_dwordx4 v[226:227], off
	v_lshl_add_u64 v[226:227], s[34:35], 0, v[150:151]
	s_mov_b32 m0, s59
	s_nop 0
	global_load_lds_dwordx4 v[226:227], off
	s_waitcnt vmcnt(8)
	s_waitcnt lgkmcnt(0)
	s_setprio 1
	s_barrier
	v_mfma_f32_16x16x32_bf16 v[128:131], v[132:135], v[180:183], v[128:131]
	v_mfma_f32_16x16x32_bf16 v[124:127], v[140:143], v[180:183], v[124:127]
	v_mfma_f32_16x16x32_bf16 v[112:115], v[132:135], v[192:195], v[112:115]
	v_mfma_f32_16x16x32_bf16 v[108:111], v[140:143], v[192:195], v[108:111]
	v_mfma_f32_16x16x32_bf16 v[96:99], v[132:135], v[204:207], v[96:99]
	v_mfma_f32_16x16x32_bf16 v[92:95], v[140:143], v[204:207], v[92:95]
	v_mfma_f32_16x16x32_bf16 v[80:83], v[132:135], v[212:215], v[80:83]
	v_mfma_f32_16x16x32_bf16 v[76:79], v[140:143], v[212:215], v[76:79]
	v_mfma_f32_16x16x32_bf16 v[128:131], v[136:139], v[184:187], v[128:131]
	v_mfma_f32_16x16x32_bf16 v[124:127], v[144:147], v[184:187], v[124:127]
	v_mfma_f32_16x16x32_bf16 v[112:115], v[136:139], v[200:203], v[112:115]
	v_mfma_f32_16x16x32_bf16 v[108:111], v[144:147], v[200:203], v[108:111]
	v_mfma_f32_16x16x32_bf16 v[96:99], v[136:139], v[208:211], v[96:99]
	v_mfma_f32_16x16x32_bf16 v[92:95], v[144:147], v[208:211], v[92:95]
	v_mfma_f32_16x16x32_bf16 v[80:83], v[136:139], v[216:219], v[80:83]
	v_mfma_f32_16x16x32_bf16 v[76:79], v[144:147], v[216:219], v[76:79]
	s_setprio 0
	s_setprio 1
	v_mfma_f32_16x16x32_bf16 v[120:123], v[164:167], v[180:183], v[120:123]
	v_mfma_f32_16x16x32_bf16 v[116:119], v[172:175], v[180:183], v[116:119]
	v_mfma_f32_16x16x32_bf16 v[104:107], v[164:167], v[192:195], v[104:107]
	v_mfma_f32_16x16x32_bf16 v[100:103], v[172:175], v[192:195], v[100:103]
	v_mfma_f32_16x16x32_bf16 v[88:91], v[164:167], v[204:207], v[88:91]
	v_mfma_f32_16x16x32_bf16 v[84:87], v[172:175], v[204:207], v[84:87]
	v_mfma_f32_16x16x32_bf16 v[72:75], v[164:167], v[212:215], v[72:75]
	v_mfma_f32_16x16x32_bf16 v[68:71], v[172:175], v[212:215], v[68:71]
	v_mfma_f32_16x16x32_bf16 v[120:123], v[168:171], v[184:187], v[120:123]
	v_mfma_f32_16x16x32_bf16 v[116:119], v[176:179], v[184:187], v[116:119]
	v_mfma_f32_16x16x32_bf16 v[104:107], v[168:171], v[200:203], v[104:107]
	v_mfma_f32_16x16x32_bf16 v[100:103], v[176:179], v[200:203], v[100:103]
	v_mfma_f32_16x16x32_bf16 v[88:91], v[168:171], v[208:211], v[88:91]
	v_mfma_f32_16x16x32_bf16 v[84:87], v[176:179], v[208:211], v[84:87]
	v_mfma_f32_16x16x32_bf16 v[72:75], v[168:171], v[216:219], v[72:75]
	v_mfma_f32_16x16x32_bf16 v[68:71], v[176:179], v[216:219], v[68:71]
	s_barrier
	s_setprio 0
	s_add_i32 s0, s0, s4
	v_lshl_add_u64 v[198:199], v[198:199], 0, s[90:91]
	s_mov_b32 m0, s0
	ds_read_b128 v[180:183], v190 offset:49152
	ds_read_b128 v[184:187], v190 offset:50176
	ds_read_b128 v[192:195], v190 offset:51200
	ds_read_b128 v[200:203], v190 offset:52224
	ds_read_b128 v[204:207], v190 offset:53248
	ds_read_b128 v[208:211], v190 offset:54272
	ds_read_b128 v[212:215], v190 offset:55296
	ds_read_b128 v[216:219], v190 offset:56320
	global_load_lds_dwordx4 v[198:199], off
	s_add_i32 m0, s0, 0x2000
	s_add_u32 s30, s30, 0x80080
	v_lshl_add_u64 v[198:199], v[220:221], 0, s[90:91]
	s_addc_u32 s31, s31, 0
	s_add_i32 s0, s6, s4
	global_load_lds_dwordx4 v[198:199], off
	v_lshl_add_u64 v[198:199], s[30:31], 0, v[152:153]
	s_mov_b32 m0, s0
	s_nop 0
	global_load_lds_dwordx4 v[198:199], off
	v_lshl_add_u64 v[198:199], s[30:31], 0, v[148:149]
	s_add_i32 m0, s0, 0x2000
	s_nop 0
	global_load_lds_dwordx4 v[198:199], off
	v_lshl_add_u64 v[198:199], v[222:223], 0, s[90:91]
	s_mov_b32 m0, s40
	s_nop 0
	global_load_lds_dwordx4 v[198:199], off
	v_lshl_add_u64 v[198:199], v[224:225], 0, s[90:91]
	s_mov_b32 m0, s66
	s_nop 0
	global_load_lds_dwordx4 v[198:199], off
	s_nop 0
	s_waitcnt vmcnt(8)
	s_waitcnt lgkmcnt(0)
	s_setprio 1
	s_barrier
	v_mfma_f32_16x16x32_bf16 v[64:67], v[132:135], v[180:183], v[64:67]
	v_mfma_f32_16x16x32_bf16 v[60:63], v[140:143], v[180:183], v[60:63]
	v_mfma_f32_16x16x32_bf16 v[48:51], v[132:135], v[192:195], v[48:51]
	v_mfma_f32_16x16x32_bf16 v[44:47], v[140:143], v[192:195], v[44:47]
	v_mfma_f32_16x16x32_bf16 v[32:35], v[132:135], v[204:207], v[32:35]
	v_mfma_f32_16x16x32_bf16 v[28:31], v[140:143], v[204:207], v[28:31]
	v_mfma_f32_16x16x32_bf16 v[16:19], v[132:135], v[212:215], v[16:19]
	v_mfma_f32_16x16x32_bf16 v[12:15], v[140:143], v[212:215], v[12:15]
	v_mfma_f32_16x16x32_bf16 v[64:67], v[136:139], v[184:187], v[64:67]
	v_mfma_f32_16x16x32_bf16 v[60:63], v[144:147], v[184:187], v[60:63]
	v_mfma_f32_16x16x32_bf16 v[48:51], v[136:139], v[200:203], v[48:51]
	v_mfma_f32_16x16x32_bf16 v[44:47], v[144:147], v[200:203], v[44:47]
	v_mfma_f32_16x16x32_bf16 v[32:35], v[136:139], v[208:211], v[32:35]
	v_mfma_f32_16x16x32_bf16 v[28:31], v[144:147], v[208:211], v[28:31]
	v_mfma_f32_16x16x32_bf16 v[16:19], v[136:139], v[216:219], v[16:19]
	v_mfma_f32_16x16x32_bf16 v[12:15], v[144:147], v[216:219], v[12:15]
	s_setprio 0
	s_setprio 1
	v_mfma_f32_16x16x32_bf16 v[56:59], v[164:167], v[180:183], v[56:59]
	v_mfma_f32_16x16x32_bf16 v[52:55], v[172:175], v[180:183], v[52:55]
	v_mfma_f32_16x16x32_bf16 v[40:43], v[164:167], v[192:195], v[40:43]
	v_mfma_f32_16x16x32_bf16 v[36:39], v[172:175], v[192:195], v[36:39]
	v_mfma_f32_16x16x32_bf16 v[24:27], v[164:167], v[204:207], v[24:27]
	v_mfma_f32_16x16x32_bf16 v[20:23], v[172:175], v[204:207], v[20:23]
	v_mfma_f32_16x16x32_bf16 v[8:11], v[164:167], v[212:215], v[8:11]
	v_mfma_f32_16x16x32_bf16 v[4:7], v[172:175], v[212:215], v[4:7]
	v_mfma_f32_16x16x32_bf16 v[56:59], v[168:171], v[184:187], v[56:59]
	v_mfma_f32_16x16x32_bf16 v[52:55], v[176:179], v[184:187], v[52:55]
	v_mfma_f32_16x16x32_bf16 v[40:43], v[168:171], v[200:203], v[40:43]
	v_mfma_f32_16x16x32_bf16 v[36:39], v[176:179], v[200:203], v[36:39]
	v_mfma_f32_16x16x32_bf16 v[24:27], v[168:171], v[208:211], v[24:27]
	v_mfma_f32_16x16x32_bf16 v[20:23], v[176:179], v[208:211], v[20:23]
	v_mfma_f32_16x16x32_bf16 v[8:11], v[168:171], v[216:219], v[8:11]
	v_mfma_f32_16x16x32_bf16 v[4:7], v[176:179], v[216:219], v[4:7]
	s_barrier
	s_setprio 0
	s_add_i32 s67, s67, 2
	s_add_u32 s36, s36, 0x100
	s_addc_u32 s37, s37, 0
	s_add_u32 s38, s38, 0x100
	s_addc_u32 s39, s39, 0
	s_cmp_gt_u32 s67, 29
	s_cbranch_scc0 .LBB0_1395
	s_and_b64 vcc, exec, s[28:29]
	s_cbranch_vccz .LBB0_1398
	s_barrier

.LBB0_1441:
	s_add_u32 s0, s62, s30
	s_addc_u32 s6, s63, 0
	s_add_u32 s31, s0, 0x100
	s_addc_u32 s46, s6, 0
	s_and_b64 s[34:35], s[38:39], exec
	s_cselect_b32 s53, s43, s46
	s_cselect_b32 s52, s75, s31
	s_add_u32 s30, s66, s30
	s_addc_u32 s31, s67, 0
	s_add_u32 s34, s30, 0x100
	s_addc_u32 s35, s31, 0
	s_add_i32 s83, 0, 0x10000
	s_and_b64 s[30:31], s[38:39], exec
	s_cselect_b32 s31, s45, s35
	s_cselect_b32 s30, s81, s34
	s_add_i32 s39, 0, 0x14000
	s_add_u32 s46, s0, 0x80080
	s_addc_u32 s47, s6, 0
	s_add_i32 s49, s83, s4
	s_add_i32 m0, s59, 0xc000
	s_add_i32 s97, s59, 0xe000
	s_add_i32 s82, s49, 0x2000
	s_add_u32 s34, s30, 0x80000
	v_add_u32_e32 v144, s83, v3
	v_add_u32_e32 v172, s39, v3
	s_addc_u32 s35, s31, 0
	s_add_i32 s85, s39, s4
	ds_read_b128 v[132:135], v144
	ds_read_b128 v[136:139], v144 offset:1024
	ds_read_b128 v[140:143], v144 offset:2048
	ds_read_b128 v[144:147], v144 offset:3072
	ds_read_b128 v[160:163], v172
	ds_read_b128 v[164:167], v172 offset:1024
	ds_read_b128 v[168:171], v172 offset:2048
	ds_read_b128 v[172:175], v172 offset:3072
	s_add_i32 s84, s85, 0x2000
	s_add_i32 s0, 0, 0x18000
	s_add_i32 s54, 0, 0x1c000
	s_add_u32 vcc_lo, s52, 0x80000
	s_addc_u32 vcc_hi, s53, 0
	s_add_i32 s73, s0, s4
	s_add_i32 s6, s73, 0x2000
	s_add_u32 s38, s30, 0x80080
	s_addc_u32 s39, s31, 0
	s_add_i32 s83, s54, s4
	s_add_i32 s96, s83, 0x2000
	v_lshl_add_u64 v[198:199], s[46:47], 0, v[154:155]
	ds_read_b128 v[176:179], v186
	ds_read_b128 v[180:183], v186 offset:1024
	ds_read_b128 v[188:191], v186 offset:2048
	ds_read_b128 v[192:195], v186 offset:3072
	ds_read_b128 v[200:203], v186 offset:4096
	ds_read_b128 v[204:207], v186 offset:5120
	ds_read_b128 v[208:211], v186 offset:6144
	ds_read_b128 v[212:215], v186 offset:7168
	global_load_lds_dwordx4 v[198:199], off
	v_lshl_add_u64 v[198:199], s[46:47], 0, v[150:151]
	s_mov_b32 m0, s97
	s_nop 0
	global_load_lds_dwordx4 v[198:199], off
	s_nop 0
	s_waitcnt vmcnt(8)
	s_waitcnt lgkmcnt(0)
	s_setprio 1
	s_barrier
	v_mfma_f32_16x16x32_bf16 v[128:131], v[132:135], v[176:179], v[128:131]
	v_mfma_f32_16x16x32_bf16 v[124:127], v[140:143], v[176:179], v[124:127]
	v_mfma_f32_16x16x32_bf16 v[112:115], v[132:135], v[188:191], v[112:115]
	v_mfma_f32_16x16x32_bf16 v[108:111], v[140:143], v[188:191], v[108:111]
	v_mfma_f32_16x16x32_bf16 v[96:99], v[132:135], v[200:203], v[96:99]
	v_mfma_f32_16x16x32_bf16 v[92:95], v[140:143], v[200:203], v[92:95]
	v_mfma_f32_16x16x32_bf16 v[80:83], v[132:135], v[208:211], v[80:83]
	v_mfma_f32_16x16x32_bf16 v[76:79], v[140:143], v[208:211], v[76:79]
	v_mfma_f32_16x16x32_bf16 v[128:131], v[136:139], v[180:183], v[128:131]
	v_mfma_f32_16x16x32_bf16 v[124:127], v[144:147], v[180:183], v[124:127]
	v_mfma_f32_16x16x32_bf16 v[112:115], v[136:139], v[192:195], v[112:115]
	v_mfma_f32_16x16x32_bf16 v[108:111], v[144:147], v[192:195], v[108:111]
	v_mfma_f32_16x16x32_bf16 v[96:99], v[136:139], v[204:207], v[96:99]
	v_mfma_f32_16x16x32_bf16 v[92:95], v[144:147], v[204:207], v[92:95]
	v_mfma_f32_16x16x32_bf16 v[80:83], v[136:139], v[212:215], v[80:83]
	v_mfma_f32_16x16x32_bf16 v[76:79], v[144:147], v[212:215], v[76:79]
	s_setprio 0
	s_setprio 1
	v_mfma_f32_16x16x32_bf16 v[120:123], v[160:163], v[176:179], v[120:123]
	v_mfma_f32_16x16x32_bf16 v[116:119], v[168:171], v[176:179], v[116:119]
	v_mfma_f32_16x16x32_bf16 v[104:107], v[160:163], v[188:191], v[104:107]
	v_mfma_f32_16x16x32_bf16 v[100:103], v[168:171], v[188:191], v[100:103]
	v_mfma_f32_16x16x32_bf16 v[88:91], v[160:163], v[200:203], v[88:91]
	v_mfma_f32_16x16x32_bf16 v[84:87], v[168:171], v[200:203], v[84:87]
	v_mfma_f32_16x16x32_bf16 v[72:75], v[160:163], v[208:211], v[72:75]
	v_mfma_f32_16x16x32_bf16 v[68:71], v[168:171], v[208:211], v[68:71]
	v_mfma_f32_16x16x32_bf16 v[120:123], v[164:167], v[180:183], v[120:123]
	v_mfma_f32_16x16x32_bf16 v[116:119], v[172:175], v[180:183], v[116:119]
	v_mfma_f32_16x16x32_bf16 v[104:107], v[164:167], v[192:195], v[104:107]
	v_mfma_f32_16x16x32_bf16 v[100:103], v[172:175], v[192:195], v[100:103]
	v_mfma_f32_16x16x32_bf16 v[88:91], v[164:167], v[204:207], v[88:91]
	v_mfma_f32_16x16x32_bf16 v[84:87], v[172:175], v[204:207], v[84:87]
	v_mfma_f32_16x16x32_bf16 v[72:75], v[164:167], v[212:215], v[72:75]
	v_mfma_f32_16x16x32_bf16 v[68:71], v[172:175], v[212:215], v[68:71]
	s_barrier
	s_setprio 0
	s_mov_b32 m0, s49
	v_lshl_add_u64 v[198:199], s[30:31], 0, v[152:153]
	ds_read_b128 v[176:179], v186 offset:16384
	ds_read_b128 v[180:183], v186 offset:17408
	ds_read_b128 v[188:191], v186 offset:18432
	ds_read_b128 v[192:195], v186 offset:19456
	ds_read_b128 v[200:203], v186 offset:20480
	ds_read_b128 v[204:207], v186 offset:21504
	ds_read_b128 v[208:211], v186 offset:22528
	ds_read_b128 v[212:215], v186 offset:23552
	global_load_lds_dwordx4 v[198:199], off
	v_lshl_add_u64 v[216:217], s[30:31], 0, v[148:149]
	s_mov_b32 m0, s82
	v_lshl_add_u64 v[218:219], s[34:35], 0, v[152:153]
	global_load_lds_dwordx4 v[216:217], off
	s_mov_b32 m0, s85
	v_lshl_add_u64 v[220:221], s[52:53], 0, v[150:151]
	global_load_lds_dwordx4 v[218:219], off
	v_lshl_add_u64 v[218:219], s[34:35], 0, v[148:149]
	s_mov_b32 m0, s84
	s_nop 0
	global_load_lds_dwordx4 v[218:219], off
	v_lshl_add_u64 v[218:219], s[52:53], 0, v[154:155]
	s_mov_b32 m0, s59
	s_nop 0
	global_load_lds_dwordx4 v[218:219], off
	s_mov_b32 m0, s40
	s_nop 0
	global_load_lds_dwordx4 v[220:221], off
	s_nop 0
	s_waitcnt vmcnt(8)
	s_waitcnt lgkmcnt(0)
	s_setprio 1
	s_barrier
	v_mfma_f32_16x16x32_bf16 v[64:67], v[132:135], v[176:179], v[64:67]
	v_mfma_f32_16x16x32_bf16 v[60:63], v[140:143], v[176:179], v[60:63]
	v_mfma_f32_16x16x32_bf16 v[48:51], v[132:135], v[188:191], v[48:51]
	v_mfma_f32_16x16x32_bf16 v[44:47], v[140:143], v[188:191], v[44:47]
	v_mfma_f32_16x16x32_bf16 v[32:35], v[132:135], v[200:203], v[32:35]
	v_mfma_f32_16x16x32_bf16 v[28:31], v[140:143], v[200:203], v[28:31]
	v_mfma_f32_16x16x32_bf16 v[16:19], v[132:135], v[208:211], v[16:19]
	v_mfma_f32_16x16x32_bf16 v[12:15], v[140:143], v[208:211], v[12:15]
	v_mfma_f32_16x16x32_bf16 v[64:67], v[136:139], v[180:183], v[64:67]
	v_mfma_f32_16x16x32_bf16 v[60:63], v[144:147], v[180:183], v[60:63]
	v_mfma_f32_16x16x32_bf16 v[48:51], v[136:139], v[192:195], v[48:51]
	v_mfma_f32_16x16x32_bf16 v[44:47], v[144:147], v[192:195], v[44:47]
	v_mfma_f32_16x16x32_bf16 v[32:35], v[136:139], v[204:207], v[32:35]
	v_mfma_f32_16x16x32_bf16 v[28:31], v[144:147], v[204:207], v[28:31]
	v_mfma_f32_16x16x32_bf16 v[16:19], v[136:139], v[212:215], v[16:19]
	v_mfma_f32_16x16x32_bf16 v[12:15], v[144:147], v[212:215], v[12:15]
	s_setprio 0
	s_setprio 1
	v_mfma_f32_16x16x32_bf16 v[56:59], v[160:163], v[176:179], v[56:59]
	v_mfma_f32_16x16x32_bf16 v[52:55], v[168:171], v[176:179], v[52:55]
	v_mfma_f32_16x16x32_bf16 v[40:43], v[160:163], v[188:191], v[40:43]
	v_mfma_f32_16x16x32_bf16 v[36:39], v[168:171], v[188:191], v[36:39]
	v_mfma_f32_16x16x32_bf16 v[24:27], v[160:163], v[200:203], v[24:27]
	v_mfma_f32_16x16x32_bf16 v[20:23], v[168:171], v[200:203], v[20:23]
	v_mfma_f32_16x16x32_bf16 v[8:11], v[160:163], v[208:211], v[8:11]
	v_mfma_f32_16x16x32_bf16 v[4:7], v[168:171], v[208:211], v[4:7]
	v_mfma_f32_16x16x32_bf16 v[56:59], v[164:167], v[180:183], v[56:59]
	v_mfma_f32_16x16x32_bf16 v[52:55], v[172:175], v[180:183], v[52:55]
	v_mfma_f32_16x16x32_bf16 v[40:43], v[164:167], v[192:195], v[40:43]
	v_mfma_f32_16x16x32_bf16 v[36:39], v[172:175], v[192:195], v[36:39]
	v_mfma_f32_16x16x32_bf16 v[24:27], v[164:167], v[204:207], v[24:27]
	v_mfma_f32_16x16x32_bf16 v[20:23], v[172:175], v[204:207], v[20:23]
	v_mfma_f32_16x16x32_bf16 v[8:11], v[164:167], v[212:215], v[8:11]
	v_mfma_f32_16x16x32_bf16 v[4:7], v[172:175], v[212:215], v[4:7]
	s_barrier
	s_setprio 0
	v_add_u32_e32 v144, s0, v3
	v_add_u32_e32 v172, s54, v3
	ds_read_b128 v[132:135], v144
	ds_read_b128 v[136:139], v144 offset:1024
	ds_read_b128 v[140:143], v144 offset:2048
	ds_read_b128 v[144:147], v144 offset:3072
	ds_read_b128 v[160:163], v172
	ds_read_b128 v[164:167], v172 offset:1024
	ds_read_b128 v[168:171], v172 offset:2048
	ds_read_b128 v[172:175], v172 offset:3072
	s_mov_b32 m0, s55
	v_lshl_add_u64 v[222:223], vcc, 0, v[154:155]
	ds_read_b128 v[176:179], v186 offset:32768
	ds_read_b128 v[180:183], v186 offset:33792
	ds_read_b128 v[188:191], v186 offset:34816
	ds_read_b128 v[192:195], v186 offset:35840
	ds_read_b128 v[200:203], v186 offset:36864
	ds_read_b128 v[204:207], v186 offset:37888
	ds_read_b128 v[208:211], v186 offset:38912
	ds_read_b128 v[212:215], v186 offset:39936
	global_load_lds_dwordx4 v[222:223], off
	v_lshl_add_u64 v[222:223], vcc, 0, v[150:151]
	s_mov_b32 m0, s50
	s_nop 0
	global_load_lds_dwordx4 v[222:223], off
	s_nop 0
	s_waitcnt vmcnt(8)
	s_waitcnt lgkmcnt(0)
	s_setprio 1
	s_barrier
	v_mfma_f32_16x16x32_bf16 v[128:131], v[132:135], v[176:179], v[128:131]
	v_mfma_f32_16x16x32_bf16 v[124:127], v[140:143], v[176:179], v[124:127]
	v_mfma_f32_16x16x32_bf16 v[112:115], v[132:135], v[188:191], v[112:115]
	v_mfma_f32_16x16x32_bf16 v[108:111], v[140:143], v[188:191], v[108:111]
	v_mfma_f32_16x16x32_bf16 v[96:99], v[132:135], v[200:203], v[96:99]
	v_mfma_f32_16x16x32_bf16 v[92:95], v[140:143], v[200:203], v[92:95]
	v_mfma_f32_16x16x32_bf16 v[80:83], v[132:135], v[208:211], v[80:83]
	v_mfma_f32_16x16x32_bf16 v[76:79], v[140:143], v[208:211], v[76:79]
	v_mfma_f32_16x16x32_bf16 v[128:131], v[136:139], v[180:183], v[128:131]
	v_mfma_f32_16x16x32_bf16 v[124:127], v[144:147], v[180:183], v[124:127]
	v_mfma_f32_16x16x32_bf16 v[112:115], v[136:139], v[192:195], v[112:115]
	v_mfma_f32_16x16x32_bf16 v[108:111], v[144:147], v[192:195], v[108:111]
	v_mfma_f32_16x16x32_bf16 v[96:99], v[136:139], v[204:207], v[96:99]
	v_mfma_f32_16x16x32_bf16 v[92:95], v[144:147], v[204:207], v[92:95]
	v_mfma_f32_16x16x32_bf16 v[80:83], v[136:139], v[212:215], v[80:83]
	v_mfma_f32_16x16x32_bf16 v[76:79], v[144:147], v[212:215], v[76:79]
	s_setprio 0
	s_setprio 1
	v_mfma_f32_16x16x32_bf16 v[120:123], v[160:163], v[176:179], v[120:123]
	v_mfma_f32_16x16x32_bf16 v[116:119], v[168:171], v[176:179], v[116:119]
	v_mfma_f32_16x16x32_bf16 v[104:107], v[160:163], v[188:191], v[104:107]
	v_mfma_f32_16x16x32_bf16 v[100:103], v[168:171], v[188:191], v[100:103]
	v_mfma_f32_16x16x32_bf16 v[88:91], v[160:163], v[200:203], v[88:91]
	v_mfma_f32_16x16x32_bf16 v[84:87], v[168:171], v[200:203], v[84:87]
	v_mfma_f32_16x16x32_bf16 v[72:75], v[160:163], v[208:211], v[72:75]
	v_mfma_f32_16x16x32_bf16 v[68:71], v[168:171], v[208:211], v[68:71]
	v_mfma_f32_16x16x32_bf16 v[120:123], v[164:167], v[180:183], v[120:123]
	v_mfma_f32_16x16x32_bf16 v[116:119], v[172:175], v[180:183], v[116:119]
	v_mfma_f32_16x16x32_bf16 v[104:107], v[164:167], v[192:195], v[104:107]
	v_mfma_f32_16x16x32_bf16 v[100:103], v[172:175], v[192:195], v[100:103]
	v_mfma_f32_16x16x32_bf16 v[88:91], v[164:167], v[204:207], v[88:91]
	v_mfma_f32_16x16x32_bf16 v[84:87], v[172:175], v[204:207], v[84:87]
	v_mfma_f32_16x16x32_bf16 v[72:75], v[164:167], v[212:215], v[72:75]
	v_mfma_f32_16x16x32_bf16 v[68:71], v[172:175], v[212:215], v[68:71]
	s_barrier
	s_setprio 0
	s_mov_b32 m0, s73
	v_lshl_add_u64 v[198:199], v[198:199], 0, s[90:91]
	ds_read_b128 v[176:179], v186 offset:49152
	ds_read_b128 v[180:183], v186 offset:50176
	ds_read_b128 v[188:191], v186 offset:51200
	ds_read_b128 v[192:195], v186 offset:52224
	ds_read_b128 v[200:203], v186 offset:53248
	ds_read_b128 v[204:207], v186 offset:54272
	ds_read_b128 v[208:211], v186 offset:55296
	ds_read_b128 v[212:215], v186 offset:56320
	global_load_lds_dwordx4 v[198:199], off
	v_lshl_add_u64 v[198:199], v[216:217], 0, s[90:91]
	s_mov_b32 m0, s6
	s_nop 0
	global_load_lds_dwordx4 v[198:199], off
	v_lshl_add_u64 v[198:199], s[38:39], 0, v[152:153]
	s_mov_b32 m0, s83
	s_nop 0
	global_load_lds_dwordx4 v[198:199], off
	v_lshl_add_u64 v[198:199], s[38:39], 0, v[148:149]
	s_mov_b32 m0, s96
	s_nop 0
	global_load_lds_dwordx4 v[198:199], off
	v_lshl_add_u64 v[198:199], v[218:219], 0, s[90:91]
	s_mov_b32 m0, s1
	s_nop 0
	global_load_lds_dwordx4 v[198:199], off
	v_lshl_add_u64 v[198:199], v[220:221], 0, s[90:91]
	s_mov_b32 m0, s24
	s_nop 0
	global_load_lds_dwordx4 v[198:199], off
	s_nop 0
	s_waitcnt vmcnt(8)
	s_waitcnt lgkmcnt(0)
	s_setprio 1
	s_barrier
	v_mfma_f32_16x16x32_bf16 v[64:67], v[132:135], v[176:179], v[64:67]
	v_mfma_f32_16x16x32_bf16 v[60:63], v[140:143], v[176:179], v[60:63]
	v_mfma_f32_16x16x32_bf16 v[48:51], v[132:135], v[188:191], v[48:51]
	v_mfma_f32_16x16x32_bf16 v[44:47], v[140:143], v[188:191], v[44:47]
	v_mfma_f32_16x16x32_bf16 v[32:35], v[132:135], v[200:203], v[32:35]
	v_mfma_f32_16x16x32_bf16 v[28:31], v[140:143], v[200:203], v[28:31]
	v_mfma_f32_16x16x32_bf16 v[16:19], v[132:135], v[208:211], v[16:19]
	v_mfma_f32_16x16x32_bf16 v[12:15], v[140:143], v[208:211], v[12:15]
	v_mfma_f32_16x16x32_bf16 v[64:67], v[136:139], v[180:183], v[64:67]
	v_mfma_f32_16x16x32_bf16 v[60:63], v[144:147], v[180:183], v[60:63]
	v_mfma_f32_16x16x32_bf16 v[48:51], v[136:139], v[192:195], v[48:51]
	v_mfma_f32_16x16x32_bf16 v[44:47], v[144:147], v[192:195], v[44:47]
	v_mfma_f32_16x16x32_bf16 v[32:35], v[136:139], v[204:207], v[32:35]
	v_mfma_f32_16x16x32_bf16 v[28:31], v[144:147], v[204:207], v[28:31]
	v_mfma_f32_16x16x32_bf16 v[16:19], v[136:139], v[212:215], v[16:19]
	v_mfma_f32_16x16x32_bf16 v[12:15], v[144:147], v[212:215], v[12:15]
	s_setprio 0
	s_setprio 1
	v_mfma_f32_16x16x32_bf16 v[56:59], v[160:163], v[176:179], v[56:59]
	v_mfma_f32_16x16x32_bf16 v[52:55], v[168:171], v[176:179], v[52:55]
	v_mfma_f32_16x16x32_bf16 v[40:43], v[160:163], v[188:191], v[40:43]
	v_mfma_f32_16x16x32_bf16 v[36:39], v[168:171], v[188:191], v[36:39]
	v_mfma_f32_16x16x32_bf16 v[24:27], v[160:163], v[200:203], v[24:27]
	v_mfma_f32_16x16x32_bf16 v[20:23], v[168:171], v[200:203], v[20:23]
	v_mfma_f32_16x16x32_bf16 v[8:11], v[160:163], v[208:211], v[8:11]
	v_mfma_f32_16x16x32_bf16 v[4:7], v[168:171], v[208:211], v[4:7]
	v_mfma_f32_16x16x32_bf16 v[56:59], v[164:167], v[180:183], v[56:59]
	v_mfma_f32_16x16x32_bf16 v[52:55], v[172:175], v[180:183], v[52:55]
	v_mfma_f32_16x16x32_bf16 v[40:43], v[164:167], v[192:195], v[40:43]
	v_mfma_f32_16x16x32_bf16 v[36:39], v[172:175], v[192:195], v[36:39]
	v_mfma_f32_16x16x32_bf16 v[24:27], v[164:167], v[204:207], v[24:27]
	v_mfma_f32_16x16x32_bf16 v[20:23], v[172:175], v[204:207], v[20:23]
	v_mfma_f32_16x16x32_bf16 v[8:11], v[164:167], v[212:215], v[8:11]
	v_mfma_f32_16x16x32_bf16 v[4:7], v[172:175], v[212:215], v[4:7]
	s_barrier
	s_setprio 0
	s_movk_i32 s30, 0x100
	s_andn2_b64 vcc, exec, s[36:37]
	s_mov_b64 s[38:39], -1
	s_mov_b64 s[36:37], 0
	s_cbranch_vccz .LBB0_1441
	s_and_b64 vcc, exec, s[28:29]
	s_cbranch_vccz .LBB0_1444
	s_barrier
